# wave reductions in S1 and fused epilogues and the diff-attention tail use DPP and permlane swaps instead of serialized ds_bpermute
# baseline (speedup 1.0000x reference)
;     __device__ __forceinline__ void operator()(const f32x4 (&acc)[2][2][4][2], const Unit& u, int wr, int wc, int fr_, int fq_) const {
;     ...
;         if (kind == 2) { const float* gn = (pn == 12 ? kn : qn) + 64 * (wc & 1) + i0;
;             ga[0] = *(const f32x4*)gn; ga[1] = *(const f32x4*)(gn + 4); gb[0] = *(const f32x4*)(gn + 32); gb[1] = *(const f32x4*)(gn + 36);
; #pragma unroll
;             for (int ai = 0; ai < 2; ++ai)
; #pragma unroll
;                 for (int m = 0; m < 4; ++m) { float q = 0.f;
; #pragma unroll
;                     for (int bj = 0; bj < 2; ++bj)
; #pragma unroll
;                         for (int n = 0; n < 2; ++n) { const f32x4 x = acc[ai][bj][m][n]; q += (x[0] * x[0] + x[1] * x[1]) + (x[2] * x[2] + x[3] * x[3]); }
;                     q += __shfl_xor(q, 16); q += __shfl_xor(q, 32);
;                     if (fq == 0) X[(ai * HALF + wr * 64 + m * 16 + fr) * 4 + wc] = q; }
;             asm volatile("s_waitcnt lgkmcnt(0)" ::: "memory"); __builtin_amdgcn_s_barrier(); asm volatile("" ::: "memory");
;         } else { ga[0] = ga[1] = gb[0] = gb[1] = (f32x4){1.f, 1.f, 1.f, 1.f}; }
.LBB0_169:
	s_or_b64 exec, exec, s[6:7]
	s_add_i32 s6, s50, -10
	v_mov_b32_e32 v133, 1.0
	s_cmp_lt_u32 s6, 3
	v_lshlrev_b32_e32 v156, 3, v178
	s_cselect_b64 s[8:9], -1, 0
	s_cmp_gt_u32 s6, 2
	v_mov_b32_e32 v132, v133
	v_mov_b32_e32 v131, v133
	v_mov_b32_e32 v130, v133
	v_mov_b32_e32 v141, v133
	v_mov_b32_e32 v140, v133
	v_mov_b32_e32 v139, v133
	v_mov_b32_e32 v138, v133
	v_mov_b32_e32 v137, v133
	v_mov_b32_e32 v136, v133
	v_mov_b32_e32 v135, v133
	v_mov_b32_e32 v134, v133
	v_mov_b32_e32 v145, v133
	v_mov_b32_e32 v144, v133
	v_mov_b32_e32 v143, v133
	v_mov_b32_e32 v142, v133
	s_cbranch_scc1 .LBB0_187
	v_readlane_b32 s52, v251, 9
	v_readlane_b32 s56, v251, 13
	v_readlane_b32 s57, v251, 14
	v_readlane_b32 s58, v251, 15
	v_readlane_b32 s59, v251, 16
	v_readlane_b32 s56, v251, 33
	s_cmp_eq_u32 s50, 12
	v_readlane_b32 s53, v251, 10
	v_readlane_b32 s70, v251, 47
	v_readlane_b32 s71, v251, 48
	s_cselect_b32 s19, s53, s71
	s_cselect_b32 s21, s52, s70
	s_lshl_b64 s[6:7], s[10:11], 2
	s_add_u32 s6, s21, s6
	s_addc_u32 s7, s19, s7
	s_add_u32 s6, s6, s49
	s_addc_u32 s7, s7, 0
	v_ashrrev_i32_e32 v157, 31, v156
	v_lshl_add_u64 v[142:143], v[156:157], 2, s[6:7]
	global_load_dwordx4 v[130:133], v[142:143], off offset:16
	global_load_dwordx4 v[138:141], v[142:143], off
	global_load_dwordx4 v[134:137], v[142:143], off offset:144
	s_nop 0
	global_load_dwordx4 v[142:145], v[142:143], off offset:128
	v_mul_f32_e32 v160, v127, v127
	v_mul_f32_e32 v164, v129, v129
	v_fmac_f32_e32 v160, v126, v126
	v_fmac_f32_e32 v164, v128, v128
	v_add_f32_e32 v160, v160, v164
	v_mul_f32_e32 v164, v123, v123
	v_mul_f32_e32 v165, v125, v125
	v_fmac_f32_e32 v164, v122, v122
	v_fmac_f32_e32 v165, v124, v124
	v_add_f32_e32 v164, v164, v165
	v_add_f32_e32 v160, v160, v164
	v_mul_f32_e32 v164, v115, v115
	v_mul_f32_e32 v165, v117, v117
	v_fmac_f32_e32 v164, v114, v114
	v_fmac_f32_e32 v165, v116, v116
	v_and_b32_e32 v158, 64, v192
	v_add_f32_e32 v164, v164, v165
	v_xor_b32_e32 v157, 16, v192
	v_add_u32_e32 v158, 64, v158
	v_add_f32_e32 v160, v160, v164
	v_mul_f32_e32 v164, v107, v107
	v_mul_f32_e32 v165, v109, v109
	v_cmp_lt_i32_e32 vcc, v157, v158
	v_fmac_f32_e32 v164, v106, v106
	v_fmac_f32_e32 v165, v108, v108
	v_cndmask_b32_e32 v157, v192, v157, vcc
	v_add_f32_e32 v164, v164, v165
	v_lshlrev_b32_e32 v157, 2, v157
	v_add_f32_e32 v164, v160, v164
	v_mov_b32_e32 v165, v164
	s_nop 1
	v_permlane16_swap_b32_e32 v164, v165
	v_xor_b32_e32 v160, 32, v192
	v_cmp_lt_i32_e32 vcc, v160, v158
	v_readlane_b32 s54, v251, 11
	v_readlane_b32 s55, v251, 12
	v_cndmask_b32_e32 v158, v192, v160, vcc
	v_lshlrev_b32_e32 v160, 2, v158
	s_waitcnt lgkmcnt(0)
	v_add_f32_e32 v187, v164, v165
	v_mov_b32_e32 v200, v187
	s_nop 1
	v_permlane32_swap_b32_e32 v187, v200
	v_cmp_eq_u32_e32 vcc, 0, v178
	v_lshl_add_u32 v158, v177, 4, s48
	v_readlane_b32 s57, v251, 34
	v_readlane_b32 s58, v251, 35
	v_readlane_b32 s59, v251, 36
	v_readlane_b32 s60, v251, 37
	v_readlane_b32 s61, v251, 38
	v_readlane_b32 s62, v251, 39
	v_readlane_b32 s63, v251, 40
	v_readlane_b32 s64, v251, 41
	v_readlane_b32 s65, v251, 42
	v_readlane_b32 s66, v251, 43
	v_readlane_b32 s67, v251, 44
	v_readlane_b32 s68, v251, 45
	v_readlane_b32 s69, v251, 46
	s_and_saveexec_b64 s[6:7], vcc
	s_cbranch_execz .LBB0_172
	s_waitcnt lgkmcnt(0)
	v_add_f32_e32 v164, v187, v200
	ds_write_b32 v158, v164
.LBB0_172:
	s_or_b64 exec, exec, s[6:7]
	v_mul_f32_e32 v164, v119, v119
	v_mul_f32_e32 v165, v121, v121
	v_fmac_f32_e32 v164, v118, v118
	v_fmac_f32_e32 v165, v120, v120
	v_add_f32_e32 v164, v164, v165
	v_mul_f32_e32 v165, v111, v111
	v_mul_f32_e32 v166, v113, v113
	v_fmac_f32_e32 v165, v110, v110
	v_fmac_f32_e32 v166, v112, v112
	v_add_f32_e32 v165, v165, v166
	v_add_f32_e32 v164, v164, v165
	v_mul_f32_e32 v165, v99, v99
	v_mul_f32_e32 v166, v101, v101
	v_fmac_f32_e32 v165, v98, v98
	v_fmac_f32_e32 v166, v100, v100
	v_add_f32_e32 v165, v165, v166
	v_add_f32_e32 v164, v164, v165
	v_mul_f32_e32 v165, v91, v91
	v_mul_f32_e32 v166, v93, v93
	v_fmac_f32_e32 v165, v90, v90
	v_fmac_f32_e32 v166, v92, v92
	v_add_f32_e32 v165, v165, v166
	v_add_f32_e32 v164, v164, v165
	v_mov_b32_e32 v165, v164
	s_nop 1
	v_permlane16_swap_b32_e32 v164, v165
	s_waitcnt lgkmcnt(0)
	v_add_f32_e32 v187, v164, v165
	v_mov_b32_e32 v200, v187
	s_nop 1
	v_permlane32_swap_b32_e32 v187, v200
	s_and_saveexec_b64 s[6:7], vcc
	s_cbranch_execz .LBB0_174
	s_waitcnt lgkmcnt(0)
	v_add_f32_e32 v164, v187, v200
	ds_write_b32 v158, v164 offset:256
.LBB0_174:
	s_or_b64 exec, exec, s[6:7]
	v_mul_f32_e32 v164, v103, v103
	v_mul_f32_e32 v165, v105, v105
	v_fmac_f32_e32 v164, v102, v102
	v_fmac_f32_e32 v165, v104, v104
	v_add_f32_e32 v164, v164, v165
	v_mul_f32_e32 v165, v95, v95
	v_mul_f32_e32 v166, v97, v97
	v_fmac_f32_e32 v165, v94, v94
	v_fmac_f32_e32 v166, v96, v96
	v_add_f32_e32 v165, v165, v166
	v_add_f32_e32 v164, v164, v165
	v_mul_f32_e32 v165, v83, v83
	v_mul_f32_e32 v166, v85, v85
	v_fmac_f32_e32 v165, v82, v82
	v_fmac_f32_e32 v166, v84, v84
	v_add_f32_e32 v165, v165, v166
	v_add_f32_e32 v164, v164, v165
	v_mul_f32_e32 v165, v75, v75
	v_mul_f32_e32 v166, v77, v77
	v_fmac_f32_e32 v165, v74, v74
	v_fmac_f32_e32 v166, v76, v76
	v_add_f32_e32 v165, v165, v166
	v_add_f32_e32 v164, v164, v165
	v_mov_b32_e32 v165, v164
	s_nop 1
	v_permlane16_swap_b32_e32 v164, v165
	s_waitcnt lgkmcnt(0)
	v_add_f32_e32 v187, v164, v165
	v_mov_b32_e32 v200, v187
	s_nop 1
	v_permlane32_swap_b32_e32 v187, v200
	s_and_saveexec_b64 s[6:7], vcc
	s_cbranch_execz .LBB0_176
	s_waitcnt lgkmcnt(0)
	v_add_f32_e32 v164, v187, v200
	ds_write_b32 v158, v164 offset:512
;     __device__ __forceinline__ void operator()(const f32x4 (&acc)[2][2][4][2], const Unit& u, int wr, int wc, int fr_, int fq_) const {
;     ...
;                 for (int m = 0; m < 4; ++m) { float q = 0.f;
; #pragma unroll
;                     for (int bj = 0; bj < 2; ++bj)
; #pragma unroll
;                         for (int n = 0; n < 2; ++n) { const f32x4 x = acc[ai][bj][m][n]; q += (x[0] * x[0] + x[1] * x[1]) + (x[2] * x[2] + x[3] * x[3]); }
;                     q += __shfl_xor(q, 16); q += __shfl_xor(q, 32);
;                     if (fq == 0) X[(ai * HALF + wr * 64 + m * 16 + fr) * 4 + wc] = q; }
.LBB0_176:
	s_or_b64 exec, exec, s[6:7]
	v_mul_f32_e32 v164, v87, v87
	v_mul_f32_e32 v165, v89, v89
	v_fmac_f32_e32 v164, v86, v86
	v_fmac_f32_e32 v165, v88, v88
	v_add_f32_e32 v164, v164, v165
	v_mul_f32_e32 v165, v79, v79
	v_mul_f32_e32 v166, v81, v81
	v_fmac_f32_e32 v165, v78, v78
	v_fmac_f32_e32 v166, v80, v80
	v_add_f32_e32 v165, v165, v166
	v_add_f32_e32 v164, v164, v165
	v_mul_f32_e32 v165, v71, v71
	v_mul_f32_e32 v166, v73, v73
	v_fmac_f32_e32 v165, v70, v70
	v_fmac_f32_e32 v166, v72, v72
	v_add_f32_e32 v165, v165, v166
	v_add_f32_e32 v164, v164, v165
	v_mul_f32_e32 v165, v67, v67
	v_mul_f32_e32 v166, v69, v69
	v_fmac_f32_e32 v165, v66, v66
	v_fmac_f32_e32 v166, v68, v68
	v_add_f32_e32 v165, v165, v166
	v_add_f32_e32 v164, v164, v165
	v_mov_b32_e32 v165, v164
	s_nop 1
	v_permlane16_swap_b32_e32 v164, v165
	s_waitcnt lgkmcnt(0)
	v_add_f32_e32 v187, v164, v165
	v_mov_b32_e32 v200, v187
	s_nop 1
	v_permlane32_swap_b32_e32 v187, v200
	s_and_saveexec_b64 s[6:7], vcc
	s_cbranch_execz .LBB0_178
	s_waitcnt lgkmcnt(0)
	v_add_f32_e32 v164, v187, v200
	ds_write_b32 v158, v164 offset:768
.LBB0_178:
	s_or_b64 exec, exec, s[6:7]
	v_mul_f32_e32 v164, v63, v63
	v_mul_f32_e32 v165, v65, v65
	v_fmac_f32_e32 v164, v62, v62
	v_fmac_f32_e32 v165, v64, v64
	v_add_f32_e32 v164, v164, v165
	v_mul_f32_e32 v165, v59, v59
	v_mul_f32_e32 v166, v61, v61
	v_fmac_f32_e32 v165, v58, v58
	v_fmac_f32_e32 v166, v60, v60
	v_add_f32_e32 v165, v165, v166
	v_add_f32_e32 v164, v164, v165
	v_mul_f32_e32 v165, v51, v51
	v_mul_f32_e32 v166, v53, v53
	v_fmac_f32_e32 v165, v50, v50
	v_fmac_f32_e32 v166, v52, v52
	v_add_f32_e32 v165, v165, v166
	v_add_f32_e32 v164, v164, v165
	v_mul_f32_e32 v165, v43, v43
	v_mul_f32_e32 v166, v45, v45
	v_fmac_f32_e32 v165, v42, v42
	v_fmac_f32_e32 v166, v44, v44
	v_add_f32_e32 v165, v165, v166
	v_add_f32_e32 v164, v164, v165
	v_mov_b32_e32 v165, v164
	s_nop 1
	v_permlane16_swap_b32_e32 v164, v165
	s_waitcnt lgkmcnt(0)
	v_add_f32_e32 v187, v164, v165
	v_mov_b32_e32 v200, v187
	s_nop 1
	v_permlane32_swap_b32_e32 v187, v200
	s_and_saveexec_b64 s[6:7], vcc
	s_cbranch_execz .LBB0_180
	s_waitcnt lgkmcnt(0)
	v_add_f32_e32 v164, v187, v200
	ds_write_b32 v158, v164 offset:2048
.LBB0_180:
	s_or_b64 exec, exec, s[6:7]
	v_mul_f32_e32 v164, v55, v55
	v_mul_f32_e32 v165, v57, v57
	v_fmac_f32_e32 v164, v54, v54
	v_fmac_f32_e32 v165, v56, v56
	v_add_f32_e32 v164, v164, v165
	v_mul_f32_e32 v165, v47, v47
	v_mul_f32_e32 v166, v49, v49
	v_fmac_f32_e32 v165, v46, v46
	v_fmac_f32_e32 v166, v48, v48
	v_add_f32_e32 v165, v165, v166
	v_add_f32_e32 v164, v164, v165
	v_mul_f32_e32 v165, v35, v35
	v_mul_f32_e32 v166, v37, v37
	v_fmac_f32_e32 v165, v34, v34
	v_fmac_f32_e32 v166, v36, v36
	v_add_f32_e32 v165, v165, v166
	v_add_f32_e32 v164, v164, v165
	v_mul_f32_e32 v165, v27, v27
	v_mul_f32_e32 v166, v29, v29
	v_fmac_f32_e32 v165, v26, v26
	v_fmac_f32_e32 v166, v28, v28
	v_add_f32_e32 v165, v165, v166
	v_add_f32_e32 v164, v164, v165
	v_mov_b32_e32 v165, v164
	s_nop 1
	v_permlane16_swap_b32_e32 v164, v165
	s_waitcnt lgkmcnt(0)
	v_add_f32_e32 v187, v164, v165
	v_mov_b32_e32 v200, v187
	s_nop 1
	v_permlane32_swap_b32_e32 v187, v200
	s_and_saveexec_b64 s[6:7], vcc
	s_cbranch_execz .LBB0_182
	s_waitcnt lgkmcnt(0)
	v_add_f32_e32 v164, v187, v200
	ds_write_b32 v158, v164 offset:2304
.LBB0_182:
	s_or_b64 exec, exec, s[6:7]
	v_mul_f32_e32 v164, v39, v39
	v_mul_f32_e32 v165, v41, v41
	v_fmac_f32_e32 v164, v38, v38
	v_fmac_f32_e32 v165, v40, v40
	v_add_f32_e32 v164, v164, v165
	v_mul_f32_e32 v165, v31, v31
	v_mul_f32_e32 v166, v33, v33
	v_fmac_f32_e32 v165, v30, v30
	v_fmac_f32_e32 v166, v32, v32
	v_add_f32_e32 v165, v165, v166
	v_add_f32_e32 v164, v164, v165
	v_mul_f32_e32 v165, v19, v19
	v_mul_f32_e32 v166, v21, v21
	v_fmac_f32_e32 v165, v18, v18
	v_fmac_f32_e32 v166, v20, v20
	v_add_f32_e32 v165, v165, v166
	v_add_f32_e32 v164, v164, v165
	v_mul_f32_e32 v165, v11, v11
	v_mul_f32_e32 v166, v13, v13
	v_fmac_f32_e32 v165, v10, v10
	v_fmac_f32_e32 v166, v12, v12
	v_add_f32_e32 v165, v165, v166
	v_add_f32_e32 v164, v164, v165
	v_mov_b32_e32 v165, v164
	s_nop 1
	v_permlane16_swap_b32_e32 v164, v165
	s_waitcnt lgkmcnt(0)
	v_add_f32_e32 v187, v164, v165
	v_mov_b32_e32 v200, v187
	s_nop 1
	v_permlane32_swap_b32_e32 v187, v200
	s_and_saveexec_b64 s[6:7], vcc
	s_cbranch_execz .LBB0_184
	s_waitcnt lgkmcnt(0)
	v_add_f32_e32 v164, v187, v200
	ds_write_b32 v158, v164 offset:2560
.LBB0_184:
	s_or_b64 exec, exec, s[6:7]
	v_mul_f32_e32 v164, v23, v23
	v_mul_f32_e32 v165, v25, v25
	v_fmac_f32_e32 v164, v22, v22
	v_fmac_f32_e32 v165, v24, v24
	v_add_f32_e32 v164, v164, v165
	v_mul_f32_e32 v165, v15, v15
	v_mul_f32_e32 v166, v17, v17
	v_fmac_f32_e32 v165, v14, v14
	v_fmac_f32_e32 v166, v16, v16
	v_add_f32_e32 v165, v165, v166
	v_add_f32_e32 v164, v164, v165
	v_mul_f32_e32 v165, v7, v7
	v_mul_f32_e32 v166, v9, v9
	v_fmac_f32_e32 v165, v6, v6
	v_fmac_f32_e32 v166, v8, v8
	v_add_f32_e32 v165, v165, v166
	v_add_f32_e32 v164, v164, v165
	v_mul_f32_e32 v165, v3, v3
	v_mul_f32_e32 v166, v5, v5
	v_fmac_f32_e32 v165, v2, v2
	v_fmac_f32_e32 v166, v4, v4
	v_add_f32_e32 v165, v165, v166
	v_add_f32_e32 v164, v164, v165
	v_mov_b32_e32 v157, v164
	s_nop 1
	v_permlane16_swap_b32_e32 v164, v157
	s_waitcnt lgkmcnt(0)
	v_add_f32_e32 v157, v164, v157
	v_mov_b32_e32 v160, v157
	s_nop 1
	v_permlane32_swap_b32_e32 v157, v160
	s_and_saveexec_b64 s[6:7], vcc
	s_cbranch_execz .LBB0_186
	s_waitcnt lgkmcnt(0)
	v_add_f32_e32 v157, v157, v160
	ds_write_b32 v158, v157 offset:2816

; __device__ __forceinline__ int opaque_tid() { int t = threadIdx.x; asm volatile("" : "+v"(t)); return t; }
; __device__ __forceinline__ int crow(int r, int hi) { return (r & 3) + 8 * (r >> 2) + 4 * hi; }
; template <int DK, bool NA, bool QL, int SD> ...
;     ...
;   if (hi == 0) li_l[r32] = l_reg; asm volatile("s_waitcnt vmcnt(0) lgkmcnt(0)" ::: "memory");
; #pragma unroll
;   for (int r = 0; r < 16; ++r) { const float rl = __builtin_amdgcn_rcpf(li_l[crow(r, hi)]);
; #pragma unroll
;     for (int d = 0; d < 4; ++d) o[d][r] *= rl; }
; __global__ void __launch_bounds__(NTHR) mega_fwd(Params p) {
;     ...
;                     { const int t3 = opaque_tid(), l3 = t3 & 63, r32 = l3 & 31; const v4u* STv = (const v4u*)((char*)lds + 69632) + t3;
;                       const float* sg = p.diff_subln + l * 128;
;                       float gsub[4], ss[16];
; #pragma unroll
;                       for (int d = 0; d < 4; ++d) gsub[d] = sg[32 * d + r32] * (1.0f - lam_init);
; #pragma unroll
;                       for (int r = 0; r < 16; ++r) ss[r] = 0.f;
; #pragma unroll
;                       for (int k = 0; k < 8; ++k) { const int d = k >> 1, r0 = 8 * (k & 1); const v4u w = STv[k * 512];
; #pragma unroll
;                           for (int i = 0; i < 4; ++i) { const unsigned wi = i == 0 ? w.x : (i == 1 ? w.y : (i == 2 ? w.z : w.w));
;                               const float va = bf2f((unsigned short)(wi & 0xffffu)) - lam * o[d][r0 + 2 * i], vb = bf2f((unsigned short)(wi >> 16)) - lam * o[d][r0 + 2 * i + 1];
;                               o[d][r0 + 2 * i] = va; o[d][r0 + 2 * i + 1] = vb; ss[r0 + 2 * i] += va * va; ss[r0 + 2 * i + 1] += vb * vb; } }
.LBB0_368:
	s_or_b64 exec, exec, s[2:3]
	v_mov_b32_e32 v194, 0x3c23d70a
	v_mov_b32_e32 v195, 0x2800
	v_mov_b64_e32 v[196:197], 0x580
	s_waitcnt vmcnt(0) lgkmcnt(0)
	v_add_u32_e32 v0, v207, v0
	ds_read_b128 v[72:75], v0
	ds_read_b128 v[76:79], v0 offset:32
	v_readlane_b32 s0, v255, 40
	v_readlane_b32 s1, v255, 41
	s_mov_b32 s2, 0xf800000
	s_waitcnt lgkmcnt(1)
	v_rcp_f32_e32 v67, v72
	v_rcp_f32_e32 v68, v73
	v_mul_f32_e32 v70, v67, v34
	v_mul_f32_e32 v34, v67, v18
	v_rcp_f32_e32 v18, v74
	v_mul_f32_e32 v69, v67, v50
	v_mul_f32_e32 v71, v68, v35
	v_mul_f32_e32 v66, v68, v19
	v_mul_f32_e32 v50, v18, v4
	v_rcp_f32_e32 v4, v75
	v_mul_f32_e32 v72, v18, v52
	v_mul_f32_e32 v73, v18, v36
	v_mul_f32_e32 v36, v18, v20
	v_mul_f32_e32 v82, v4, v5
	v_mul_f32_e32 v74, v4, v53
	v_mul_f32_e32 v53, v4, v37
	v_mul_f32_e32 v52, v4, v21
	s_waitcnt lgkmcnt(0)
	v_rcp_f32_e32 v4, v76
	v_mul_f32_e32 v2, v67, v2
	v_mul_f32_e32 v3, v68, v3
	v_mul_f32_e32 v51, v68, v51
	v_mul_f32_e32 v37, v4, v6
	v_mul_f32_e32 v80, v4, v54
	v_mul_f32_e32 v76, v4, v38
	v_mul_f32_e32 v75, v4, v22
	v_rcp_f32_e32 v4, v77
	s_nop 0
	v_mul_f32_e32 v54, v4, v7
	v_mul_f32_e32 v38, v4, v55
	v_mul_f32_e32 v81, v4, v39
	v_mul_f32_e32 v77, v4, v23
	v_rcp_f32_e32 v4, v78
	ds_read_b128 v[20:23], v0 offset:64
	v_mul_f32_e32 v55, v4, v8
	v_mul_f32_e32 v88, v4, v56
	v_mul_f32_e32 v84, v4, v40
	v_mul_f32_e32 v40, v4, v24
	v_rcp_f32_e32 v4, v79
	s_nop 0
	v_mul_f32_e32 v86, v4, v9
	v_mul_f32_e32 v57, v4, v57
	v_mul_f32_e32 v85, v4, v41
	v_mul_f32_e32 v41, v4, v25
	s_waitcnt lgkmcnt(0)
	v_rcp_f32_e32 v4, v20
	s_nop 0
	v_mul_f32_e32 v7, v4, v10
	v_mul_f32_e32 v8, v4, v58
	v_mul_f32_e32 v10, v4, v42
	v_mul_f32_e32 v18, v4, v26
	v_rcp_f32_e32 v4, v21
	s_nop 0
	v_mul_f32_e32 v9, v4, v11
	v_mul_f32_e32 v21, v4, v59
	v_mul_f32_e32 v35, v4, v43
	v_mul_f32_e32 v20, v4, v27
	v_rcp_f32_e32 v4, v22
	s_nop 0
	v_mul_f32_e32 v12, v4, v12
	v_mul_f32_e32 v11, v4, v60
	v_mul_f32_e32 v25, v4, v44
	v_mul_f32_e32 v22, v4, v28
	v_rcp_f32_e32 v4, v23
	s_nop 0
	v_mul_f32_e32 v28, v4, v45
	ds_read_b128 v[42:45], v0 offset:96
	v_mul_f32_e32 v19, v4, v13
	v_mul_f32_e32 v27, v4, v61
	v_mul_f32_e32 v23, v4, v29
	s_waitcnt lgkmcnt(0)
	v_rcp_f32_e32 v0, v42
	s_nop 0
	v_mul_f32_e32 v42, v0, v14
	v_mul_f32_e32 v13, v0, v62
	v_mul_f32_e32 v46, v0, v46
	v_mul_f32_e32 v14, v0, v30
	v_rcp_f32_e32 v0, v43
	s_nop 0
	v_mul_f32_e32 v30, v0, v15
	v_mul_f32_e32 v61, v0, v63
	v_mul_f32_e32 v78, v0, v47
	v_mul_f32_e32 v24, v0, v31
	v_rcp_f32_e32 v0, v44
	v_mov_b32_e32 v15, v188
	v_mul_f32_e32 v16, v0, v16
	v_mul_f32_e32 v43, v0, v64
	v_mul_f32_e32 v56, v0, v48
	v_mul_f32_e32 v31, v0, v32
	v_rcp_f32_e32 v0, v45
	s_nop 0
	v_mul_f32_e32 v45, v0, v17
	v_mul_f32_e32 v17, v0, v65
	v_mul_f32_e32 v79, v0, v49
	v_mul_f32_e32 v32, v0, v33
	v_and_b32_e32 v0, 31, v15
	v_lshl_add_u32 v15, v15, 4, 0
	v_add_u32_e32 v92, 0x11000, v15
	ds_read_b128 v[62:65], v92
	ds_read_b128 v[94:97], v92 offset:8192
	v_lshlrev_b32_e32 v6, 2, v0
	global_load_dword v0, v6, s[0:1]
	global_load_dword v4, v6, s[0:1] offset:128
	global_load_dword v5, v6, s[0:1] offset:256
	s_waitcnt lgkmcnt(1)
	v_lshlrev_b32_e32 v15, 16, v62
	v_fma_f32 v87, -v202, v2, v15
	v_and_b32_e32 v2, 0xffff0000, v62
	v_fma_f32 v33, -v202, v3, v2
	v_lshlrev_b32_e32 v2, 16, v63
	v_fma_f32 v39, -v202, v50, v2
	v_and_b32_e32 v2, 0xffff0000, v63
	v_fma_f32 v49, -v202, v82, v2
	v_lshlrev_b32_e32 v2, 16, v64
	v_fma_f32 v58, -v202, v37, v2
	v_and_b32_e32 v2, 0xffff0000, v64
	v_fma_f32 v67, -v202, v54, v2
	v_lshlrev_b32_e32 v2, 16, v65
	v_fma_f32 v64, -v202, v55, v2
	v_and_b32_e32 v2, 0xffff0000, v65
	v_fma_f32 v54, -v202, v86, v2
	s_waitcnt lgkmcnt(0)
	v_lshlrev_b32_e32 v2, 16, v94
	v_fma_f32 v47, -v202, v7, v2
	v_and_b32_e32 v2, 0xffff0000, v94
	v_fma_f32 v37, -v202, v9, v2
	v_lshlrev_b32_e32 v2, 16, v95
	v_fma_f32 v29, -v202, v12, v2
	v_and_b32_e32 v2, 0xffff0000, v95
	v_fma_f32 v19, -v202, v19, v2
	v_lshlrev_b32_e32 v2, 16, v96
	v_fma_f32 v15, -v202, v42, v2
	v_and_b32_e32 v2, 0xffff0000, v96
	v_fma_f32 v9, -v202, v30, v2
	v_lshlrev_b32_e32 v2, 16, v97
	v_fma_f32 v7, -v202, v16, v2
	v_and_b32_e32 v2, 0xffff0000, v97
	ds_read_b128 v[94:97], v92 offset:16384
	global_load_dword v6, v6, s[0:1] offset:384
	v_mul_f32_e32 v83, v33, v33
	v_mul_f32_e32 v50, v49, v49
	v_mul_f32_e32 v68, v67, v67
	s_waitcnt lgkmcnt(0)
	v_lshlrev_b32_e32 v16, 16, v94
	v_fma_f32 v89, -v202, v69, v16
	v_and_b32_e32 v16, 0xffff0000, v94
	v_fma_f32 v86, -v202, v51, v16
	v_lshlrev_b32_e32 v16, 16, v95
	v_fma_f32 v42, -v202, v72, v16
	v_and_b32_e32 v16, 0xffff0000, v95
	v_fma_f32 v51, -v202, v74, v16
	v_lshlrev_b32_e32 v16, 16, v96
	v_fma_f32 v59, -v202, v80, v16
	v_and_b32_e32 v16, 0xffff0000, v96
	v_fma_f32 v69, -v202, v38, v16
	v_lshlrev_b32_e32 v16, 16, v97
	v_fma_f32 v72, -v202, v88, v16
	v_and_b32_e32 v16, 0xffff0000, v97
	ds_read_b128 v[94:97], v92 offset:24576
	v_fma_f32 v63, -v202, v57, v16
	v_mul_f32_e32 v91, v89, v89
	v_fmac_f32_e32 v91, v87, v87
	v_fmac_f32_e32 v83, v86, v86
	s_waitcnt lgkmcnt(0)
	v_lshlrev_b32_e32 v16, 16, v94
	v_fma_f32 v57, -v202, v8, v16
	v_and_b32_e32 v8, 0xffff0000, v94
	v_fma_f32 v48, -v202, v21, v8
	v_lshlrev_b32_e32 v8, 16, v95
	v_fma_f32 v38, -v202, v11, v8
	v_and_b32_e32 v8, 0xffff0000, v95
	v_fma_f32 v30, -v202, v27, v8
	v_lshlrev_b32_e32 v8, 16, v96
	v_fma_f32 v21, -v202, v13, v8
	v_and_b32_e32 v8, 0xffff0000, v96
	v_fma_f32 v16, -v202, v61, v8
	v_lshlrev_b32_e32 v8, 16, v97
	v_fma_f32 v11, -v202, v43, v8
	v_and_b32_e32 v8, 0xffff0000, v97
	ds_read_b128 v[94:97], v92 offset:32768
	v_fma_f32 v8, -v202, v17, v8
	v_mul_f32_e32 v82, v42, v42
	v_fmac_f32_e32 v82, v39, v39
	v_fmac_f32_e32 v50, v51, v51
	s_waitcnt lgkmcnt(0)
; __global__ void __launch_bounds__(NTHR) mega_fwd(Params p) {
;     ...
;                       for (int k = 0; k < 8; ++k) { const int d = k >> 1, r0 = 8 * (k & 1); const v4u w = STv[k * 512];
; #pragma unroll
;                           for (int i = 0; i < 4; ++i) { const unsigned wi = i == 0 ? w.x : (i == 1 ? w.y : (i == 2 ? w.z : w.w));
;                               const float va = bf2f((unsigned short)(wi & 0xffffu)) - lam * o[d][r0 + 2 * i], vb = bf2f((unsigned short)(wi >> 16)) - lam * o[d][r0 + 2 * i + 1];
;                               o[d][r0 + 2 * i] = va; o[d][r0 + 2 * i + 1] = vb; ss[r0 + 2 * i] += va * va; ss[r0 + 2 * i + 1] += vb * vb; } }
; #pragma unroll
;                       for (int r = 0; r < 16; ++r) { float q = ss[r]; q += __shfl_xor(q, 1); q += __shfl_xor(q, 2); q += __shfl_xor(q, 4); q += __shfl_xor(q, 8); q += __shfl_xor(q, 16);
;                           const float rstd = 1.0f / sqrtf(q * (1.0f / 128.0f) + EPS);
; #pragma unroll
;                           for (int d = 0; d < 4; ++d) o[d][r] *= rstd * gsub[d]; } }
	v_lshlrev_b32_e32 v17, 16, v94
	v_fma_f32 v93, -v202, v70, v17
	v_and_b32_e32 v17, 0xffff0000, v94
	v_fma_f32 v90, -v202, v71, v17
	v_lshlrev_b32_e32 v17, 16, v95
	v_fma_f32 v88, -v202, v73, v17
	v_and_b32_e32 v17, 0xffff0000, v95
	v_fma_f32 v80, -v202, v53, v17
	v_lshlrev_b32_e32 v17, 16, v96
	v_fma_f32 v61, -v202, v76, v17
	v_and_b32_e32 v17, 0xffff0000, v96
	v_fma_f32 v70, -v202, v81, v17
	v_lshlrev_b32_e32 v17, 16, v97
	v_fma_f32 v76, -v202, v84, v17
	v_and_b32_e32 v17, 0xffff0000, v97
	ds_read_b128 v[94:97], v92 offset:40960
	v_fma_f32 v73, -v202, v85, v17
	v_fmac_f32_e32 v91, v93, v93
	v_fmac_f32_e32 v83, v90, v90
	s_waitcnt vmcnt(3)
	v_mul_f32_e32 v0, v201, v0
	s_waitcnt lgkmcnt(0)
	v_lshlrev_b32_e32 v17, 16, v94
	v_fma_f32 v71, -v202, v10, v17
	v_and_b32_e32 v10, 0xffff0000, v94
	v_fma_f32 v62, -v202, v35, v10
	v_lshlrev_b32_e32 v10, 16, v95
	v_fma_f32 v53, -v202, v25, v10
	v_and_b32_e32 v10, 0xffff0000, v95
	v_fma_f32 v43, -v202, v28, v10
	v_lshlrev_b32_e32 v10, 16, v96
	v_fma_f32 v35, -v202, v46, v10
	v_and_b32_e32 v10, 0xffff0000, v96
	v_fma_f32 v25, -v202, v78, v10
	v_lshlrev_b32_e32 v10, 16, v97
	v_fma_f32 v17, -v202, v56, v10
	v_and_b32_e32 v10, 0xffff0000, v97
	ds_read_b128 v[94:97], v92 offset:49152
	v_fma_f32 v10, -v202, v79, v10
	s_waitcnt vmcnt(2)
	v_mul_f32_e32 v4, v201, v4
	s_waitcnt vmcnt(1)
	v_mul_f32_e32 v5, v201, v5
	s_waitcnt vmcnt(0)
	v_mul_f32_e32 v6, v201, v6
	s_waitcnt lgkmcnt(0)
	v_lshlrev_b32_e32 v28, 16, v94
	v_fma_f32 v85, -v202, v34, v28
	v_and_b32_e32 v28, 0xffff0000, v94
	v_fma_f32 v34, -v202, v66, v28
	v_lshlrev_b32_e32 v28, 16, v95
	v_fma_f32 v84, -v202, v36, v28
	v_and_b32_e32 v28, 0xffff0000, v95
	v_fma_f32 v52, -v202, v52, v28
	v_lshlrev_b32_e32 v28, 16, v96
	v_fma_f32 v81, -v202, v75, v28
	v_and_b32_e32 v28, 0xffff0000, v96
	v_fma_f32 v79, -v202, v77, v28
	v_lshlrev_b32_e32 v28, 16, v97
	v_fma_f32 v78, -v202, v40, v28
	v_and_b32_e32 v28, 0xffff0000, v97
	ds_read_b128 v[94:97], v92 offset:57344
	v_fma_f32 v77, -v202, v41, v28
	v_fmac_f32_e32 v91, v85, v85
	v_fmac_f32_e32 v83, v34, v34
	v_fmac_f32_e32 v82, v88, v88
	s_waitcnt lgkmcnt(0)
	v_lshlrev_b32_e32 v28, 16, v94
	v_fma_f32 v75, -v202, v18, v28
	v_and_b32_e32 v18, 0xffff0000, v94
	v_fma_f32 v66, -v202, v20, v18
	s_nop 1
	v_mov_b32_dpp v20, v91 quad_perm:[1,0,3,2] row_mask:0xf bank_mask:0xf
	v_lshlrev_b32_e32 v18, 16, v95
	v_fma_f32 v56, -v202, v22, v18
	v_and_b32_e32 v18, 0xffff0000, v95
	v_fma_f32 v46, -v202, v23, v18
	s_waitcnt lgkmcnt(0)
	v_add_f32_e32 v20, v91, v20
	s_nop 1
	v_mov_b32_dpp v22, v20 quad_perm:[2,3,0,1] row_mask:0xf bank_mask:0xf
	v_lshlrev_b32_e32 v18, 16, v96
	v_fma_f32 v36, -v202, v14, v18
	v_and_b32_e32 v14, 0xffff0000, v96
	v_fma_f32 v28, -v202, v24, v14
	s_waitcnt lgkmcnt(0)
	v_add_f32_e32 v20, v20, v22
	s_nop 1
	v_mov_b32_dpp v22, v20 row_half_mirror row_mask:0xf bank_mask:0xf
	v_lshlrev_b32_e32 v14, 16, v97
	v_fma_f32 v18, -v202, v31, v14
	v_and_b32_e32 v14, 0xffff0000, v97
	v_fma_f32 v14, -v202, v32, v14
	s_waitcnt lgkmcnt(0)
	v_add_f32_e32 v20, v20, v22
	s_nop 1
	v_mov_b32_dpp v22, v20 row_mirror row_mask:0xf bank_mask:0xf
	v_fmac_f32_e32 v82, v84, v84
	v_fmac_f32_e32 v50, v80, v80
	v_fmac_f32_e32 v50, v52, v52
	v_mul_f32_e32 v60, v59, v59
	s_waitcnt lgkmcnt(0)
	v_add_f32_e32 v20, v20, v22
	v_mov_b32_e32 v22, v20
	s_nop 1
	v_permlane16_swap_b32_e32 v20, v22
	v_fmac_f32_e32 v60, v58, v58
	v_fmac_f32_e32 v60, v61, v61
	v_fmac_f32_e32 v60, v81, v81
	v_fmac_f32_e32 v68, v69, v69
	s_waitcnt lgkmcnt(0)
	v_add_f32_e32 v20, v20, v22
	v_fmamk_f32 v20, v20, 0x3c000000, v189
	v_cmp_gt_f32_e32 vcc, s2, v20
	v_mul_f32_e32 v22, 0x4f800000, v20
	v_fmac_f32_e32 v68, v70, v70
	v_cndmask_b32_e32 v20, v20, v22, vcc
	v_sqrt_f32_e32 v22, v20
	v_fmac_f32_e32 v68, v79, v79
	v_mul_f32_e32 v74, v72, v72
	v_fmac_f32_e32 v74, v64, v64
	v_add_u32_e32 v23, -1, v22
	v_fma_f32 v24, -v23, v22, v20
	v_cmp_ge_f32_e64 s[0:1], 0, v24
	v_add_u32_e32 v24, 1, v22
	v_fmac_f32_e32 v74, v76, v76
	v_cndmask_b32_e64 v23, v22, v23, s[0:1]
	v_fma_f32 v22, -v24, v22, v20
	v_cmp_lt_f32_e64 s[0:1], 0, v22
	v_fmac_f32_e32 v74, v78, v78
	v_mul_f32_e32 v55, v54, v54
	v_cndmask_b32_e64 v22, v23, v24, s[0:1]
	v_mul_f32_e32 v23, 0x37800000, v22
	v_cndmask_b32_e32 v22, v22, v23, vcc
	v_cmp_class_f32_e32 vcc, v20, v190
	v_fmac_f32_e32 v55, v63, v63
	v_fmac_f32_e32 v55, v73, v73
	v_cndmask_b32_e32 v20, v22, v20, vcc
	v_div_scale_f32 v22, s[0:1], v20, v20, 1.0
	v_rcp_f32_e32 v23, v22
	v_fmac_f32_e32 v55, v77, v77
	v_mul_f32_e32 v65, v57, v57
	v_fmac_f32_e32 v65, v47, v47
	v_fma_f32 v24, -v22, v23, 1.0
	v_fmac_f32_e32 v23, v24, v23
	v_div_scale_f32 v24, vcc, 1.0, v20, 1.0
	v_mul_f32_e32 v31, v24, v23
	v_fma_f32 v32, -v22, v31, v24
	v_fmac_f32_e32 v31, v32, v23
	v_fma_f32 v22, -v22, v31, v24
	v_div_fmas_f32 v22, v22, v23, v31
	s_nop 1
	v_mov_b32_dpp v31, v83 quad_perm:[1,0,3,2] row_mask:0xf bank_mask:0xf
	v_div_fixup_f32 v24, v22, v20, 1.0
	v_mul_f32_e32 v20, v24, v0
	v_mul_f32_e32 v22, v24, v4
	v_mul_f32_e32 v23, v24, v5
	s_waitcnt lgkmcnt(0)
	v_add_f32_e32 v31, v83, v31
	s_nop 1
	v_mov_b32_dpp v32, v31 quad_perm:[2,3,0,1] row_mask:0xf bank_mask:0xf
	v_mul_f32_e32 v24, v24, v6
	v_mul_f32_e32 v24, v24, v85
	v_fmac_f32_e32 v65, v71, v71
	v_fmac_f32_e32 v65, v75, v75
	s_waitcnt lgkmcnt(0)
	v_add_f32_e32 v31, v31, v32
	s_nop 1
	v_mov_b32_dpp v32, v31 row_half_mirror row_mask:0xf bank_mask:0xf
	v_mul_f32_e32 v44, v37, v37
	v_fmac_f32_e32 v44, v48, v48
	v_fmac_f32_e32 v44, v62, v62
	v_fmac_f32_e32 v44, v66, v66
	s_waitcnt lgkmcnt(0)
	v_add_f32_e32 v31, v31, v32
	s_nop 1
	v_mov_b32_dpp v32, v31 row_mirror row_mask:0xf bank_mask:0xf
	v_fma_f32 v2, -v202, v45, v2
	v_mul_f32_e32 v45, v38, v38
	v_fmac_f32_e32 v45, v29, v29
	v_fmac_f32_e32 v45, v53, v53
	s_waitcnt lgkmcnt(0)
; __global__ void __launch_bounds__(NTHR) mega_fwd(Params p) {
;     ...
;                       for (int r = 0; r < 16; ++r) { float q = ss[r]; q += __shfl_xor(q, 1); q += __shfl_xor(q, 2); q += __shfl_xor(q, 4); q += __shfl_xor(q, 8); q += __shfl_xor(q, 16);
;                           const float rstd = 1.0f / sqrtf(q * (1.0f / 128.0f) + EPS);
; #pragma unroll
;                           for (int d = 0; d < 4; ++d) o[d][r] *= rstd * gsub[d]; } }
	v_add_f32_e32 v31, v31, v32
	v_mov_b32_e32 v32, v31
	s_nop 1
	v_permlane16_swap_b32_e32 v31, v32
	v_fmac_f32_e32 v45, v56, v56
	v_mul_f32_e32 v26, v19, v19
	v_fmac_f32_e32 v26, v30, v30
	v_fmac_f32_e32 v26, v43, v43
	s_waitcnt lgkmcnt(0)
	v_add_f32_e32 v31, v31, v32
	v_fmamk_f32 v31, v31, 0x3c000000, v189
	v_cmp_gt_f32_e32 vcc, s2, v31
	v_mul_f32_e32 v32, 0x4f800000, v31
	v_fmac_f32_e32 v26, v46, v46
	v_cndmask_b32_e32 v31, v31, v32, vcc
	v_sqrt_f32_e32 v32, v31
	v_mul_f32_e32 v27, v21, v21
	v_fmac_f32_e32 v27, v15, v15
	v_fmac_f32_e32 v27, v35, v35
	v_add_u32_e32 v40, -1, v32
	v_fma_f32 v41, -v40, v32, v31
	v_cmp_ge_f32_e64 s[0:1], 0, v41
	v_add_u32_e32 v41, 1, v32
	v_fmac_f32_e32 v27, v36, v36
	v_cndmask_b32_e64 v40, v32, v40, s[0:1]
	v_fma_f32 v32, -v41, v32, v31
	v_cmp_lt_f32_e64 s[0:1], 0, v32
	v_mul_f32_e32 v12, v9, v9
	v_fmac_f32_e32 v12, v16, v16
	v_cndmask_b32_e64 v32, v40, v41, s[0:1]
	v_mul_f32_e32 v40, 0x37800000, v32
	v_cndmask_b32_e32 v32, v32, v40, vcc
	v_cmp_class_f32_e32 vcc, v31, v190
	v_fmac_f32_e32 v12, v25, v25
	v_fmac_f32_e32 v12, v28, v28
	v_cndmask_b32_e32 v31, v32, v31, vcc
	v_div_scale_f32 v32, s[0:1], v31, v31, 1.0
	v_rcp_f32_e32 v40, v32
	v_mul_f32_e32 v13, v11, v11
	v_fmac_f32_e32 v13, v7, v7
	v_fmac_f32_e32 v13, v17, v17
	v_fma_f32 v41, -v32, v40, 1.0
	v_fmac_f32_e32 v40, v41, v40
	v_div_scale_f32 v41, vcc, 1.0, v31, 1.0
	v_mul_f32_e32 v83, v41, v40
	v_fma_f32 v85, -v32, v83, v41
	v_fmac_f32_e32 v83, v85, v40
	v_fma_f32 v32, -v32, v83, v41
	v_div_fmas_f32 v32, v32, v40, v83
	v_div_fixup_f32 v40, v32, v31, 1.0
	v_mul_f32_e32 v31, v40, v0
	v_mul_f32_e32 v31, v31, v33
	v_mul_f32_e32 v32, v40, v4
	v_mul_f32_e32 v33, v40, v5
	v_mul_f32_e32 v40, v40, v6
	v_mul_f32_e32 v34, v40, v34
	s_nop 1
	v_mov_b32_dpp v40, v82 quad_perm:[1,0,3,2] row_mask:0xf bank_mask:0xf
	v_mul_f32_e32 v32, v32, v86
	v_fmac_f32_e32 v13, v18, v18
	v_mul_f32_e32 v3, v2, v2
	v_fmac_f32_e32 v3, v8, v8
	s_waitcnt lgkmcnt(0)
	v_add_f32_e32 v40, v82, v40
	s_nop 1
	v_mov_b32_dpp v41, v40 quad_perm:[2,3,0,1] row_mask:0xf bank_mask:0xf
	v_fmac_f32_e32 v3, v10, v10
	v_fmac_f32_e32 v3, v14, v14
	v_mul_f32_e32 v20, v20, v87
	v_mul_f32_e32 v22, v22, v89
	s_waitcnt lgkmcnt(0)
	v_add_f32_e32 v40, v40, v41
	s_nop 1
	v_mov_b32_dpp v41, v40 row_half_mirror row_mask:0xf bank_mask:0xf
	v_mul_f32_e32 v23, v23, v93
	v_mul_f32_e32 v33, v33, v90
	s_waitcnt lgkmcnt(0)
	v_add_f32_e32 v40, v40, v41
	s_nop 1
	v_mov_b32_dpp v41, v40 row_mirror row_mask:0xf bank_mask:0xf
	s_waitcnt lgkmcnt(0)
	v_add_f32_e32 v40, v40, v41
	v_mov_b32_e32 v41, v40
	s_nop 1
	v_permlane16_swap_b32_e32 v40, v41
	s_waitcnt lgkmcnt(0)
	v_add_f32_e32 v40, v40, v41
	v_fmamk_f32 v40, v40, 0x3c000000, v189
	v_cmp_gt_f32_e32 vcc, s2, v40
	v_mul_f32_e32 v41, 0x4f800000, v40
	s_nop 0
	v_cndmask_b32_e32 v40, v40, v41, vcc
	v_sqrt_f32_e32 v41, v40
	s_nop 0
	v_add_u32_e32 v82, -1, v41
	v_fma_f32 v83, -v82, v41, v40
	v_cmp_ge_f32_e64 s[0:1], 0, v83
	v_add_u32_e32 v83, 1, v41
	s_nop 0
	v_cndmask_b32_e64 v82, v41, v82, s[0:1]
	v_fma_f32 v41, -v83, v41, v40
	v_cmp_lt_f32_e64 s[0:1], 0, v41
	s_nop 1
	v_cndmask_b32_e64 v41, v82, v83, s[0:1]
	v_mul_f32_e32 v82, 0x37800000, v41
	v_cndmask_b32_e32 v41, v41, v82, vcc
	v_cmp_class_f32_e32 vcc, v40, v190
	s_nop 1
	v_cndmask_b32_e32 v40, v41, v40, vcc
	v_div_scale_f32 v41, s[0:1], v40, v40, 1.0
	v_rcp_f32_e32 v82, v41
	s_nop 0
	v_fma_f32 v83, -v41, v82, 1.0
	v_fmac_f32_e32 v82, v83, v82
	v_div_scale_f32 v83, vcc, 1.0, v40, 1.0
	v_mul_f32_e32 v85, v83, v82
	v_fma_f32 v86, -v41, v85, v83
	v_fmac_f32_e32 v85, v86, v82
	v_fma_f32 v41, -v41, v85, v83
	v_div_fmas_f32 v41, v41, v82, v85
	v_div_fixup_f32 v82, v41, v40, 1.0
	v_mul_f32_e32 v40, v82, v0
	v_mul_f32_e32 v39, v40, v39
	v_mul_f32_e32 v40, v82, v4
	v_mul_f32_e32 v40, v40, v42
	v_mul_f32_e32 v41, v82, v5
	v_mul_f32_e32 v42, v82, v6
	s_nop 1
	v_mov_b32_dpp v82, v50 quad_perm:[1,0,3,2] row_mask:0xf bank_mask:0xf
	v_mul_f32_e32 v42, v42, v84
	v_mul_f32_e32 v41, v41, v88
	s_waitcnt lgkmcnt(0)
	v_add_f32_e32 v50, v50, v82
	s_nop 1
	v_mov_b32_dpp v82, v50 quad_perm:[2,3,0,1] row_mask:0xf bank_mask:0xf
	s_waitcnt lgkmcnt(0)
	v_add_f32_e32 v50, v50, v82
	s_nop 1
	v_mov_b32_dpp v82, v50 row_half_mirror row_mask:0xf bank_mask:0xf
	s_waitcnt lgkmcnt(0)
	v_add_f32_e32 v50, v50, v82
	s_nop 1
	v_mov_b32_dpp v82, v50 row_mirror row_mask:0xf bank_mask:0xf
	s_waitcnt lgkmcnt(0)
	v_add_f32_e32 v50, v50, v82
	v_mov_b32_e32 v82, v50
	s_nop 1
	v_permlane16_swap_b32_e32 v50, v82
	s_waitcnt lgkmcnt(0)
	v_add_f32_e32 v50, v50, v82
	v_fmamk_f32 v50, v50, 0x3c000000, v189
	v_cmp_gt_f32_e32 vcc, s2, v50
	v_mul_f32_e32 v82, 0x4f800000, v50
	s_nop 0
	v_cndmask_b32_e32 v50, v50, v82, vcc
	v_sqrt_f32_e32 v82, v50
	s_nop 0
	v_add_u32_e32 v83, -1, v82
	v_fma_f32 v84, -v83, v82, v50
	v_cmp_ge_f32_e64 s[0:1], 0, v84
	v_add_u32_e32 v84, 1, v82
	s_nop 0
	v_cndmask_b32_e64 v83, v82, v83, s[0:1]
	v_fma_f32 v82, -v84, v82, v50
	v_cmp_lt_f32_e64 s[0:1], 0, v82
	s_nop 1
	v_cndmask_b32_e64 v82, v83, v84, s[0:1]
	v_mul_f32_e32 v83, 0x37800000, v82
	v_cndmask_b32_e32 v82, v82, v83, vcc
	v_cmp_class_f32_e32 vcc, v50, v190
	s_nop 1
	v_cndmask_b32_e32 v50, v82, v50, vcc
	v_div_scale_f32 v82, s[0:1], v50, v50, 1.0
	v_rcp_f32_e32 v83, v82
	s_nop 0
	v_fma_f32 v84, -v82, v83, 1.0
	v_fmac_f32_e32 v83, v84, v83
	v_div_scale_f32 v84, vcc, 1.0, v50, 1.0
	v_mul_f32_e32 v85, v84, v83
	v_fma_f32 v86, -v82, v85, v84
	v_fmac_f32_e32 v85, v86, v83
	v_fma_f32 v82, -v82, v85, v84
	v_div_fmas_f32 v82, v82, v83, v85
	v_div_fixup_f32 v82, v82, v50, 1.0
	v_mul_f32_e32 v50, v82, v0
	v_mul_f32_e32 v49, v50, v49
	v_mul_f32_e32 v50, v82, v4
	v_mul_f32_e32 v50, v50, v51
	v_mul_f32_e32 v51, v82, v5
	v_mul_f32_e32 v51, v51, v80
	v_mul_f32_e32 v80, v82, v6
	v_mul_f32_e32 v52, v80, v52
	s_nop 1
	v_mov_b32_dpp v80, v60 quad_perm:[1,0,3,2] row_mask:0xf bank_mask:0xf
	s_waitcnt lgkmcnt(0)
; __global__ void __launch_bounds__(NTHR) mega_fwd(Params p) {
;     ...
;                       for (int r = 0; r < 16; ++r) { float q = ss[r]; q += __shfl_xor(q, 1); q += __shfl_xor(q, 2); q += __shfl_xor(q, 4); q += __shfl_xor(q, 8); q += __shfl_xor(q, 16);
;                           const float rstd = 1.0f / sqrtf(q * (1.0f / 128.0f) + EPS);
; #pragma unroll
;                           for (int d = 0; d < 4; ++d) o[d][r] *= rstd * gsub[d]; } }
	v_add_f32_e32 v60, v60, v80
	s_nop 1
	v_mov_b32_dpp v80, v60 quad_perm:[2,3,0,1] row_mask:0xf bank_mask:0xf
	s_waitcnt lgkmcnt(0)
	v_add_f32_e32 v60, v60, v80
	s_nop 1
	v_mov_b32_dpp v80, v60 row_half_mirror row_mask:0xf bank_mask:0xf
	s_waitcnt lgkmcnt(0)
	v_add_f32_e32 v60, v60, v80
	s_nop 1
	v_mov_b32_dpp v80, v60 row_mirror row_mask:0xf bank_mask:0xf
	s_waitcnt lgkmcnt(0)
	v_add_f32_e32 v60, v60, v80
	v_mov_b32_e32 v80, v60
	s_nop 1
	v_permlane16_swap_b32_e32 v60, v80
	s_waitcnt lgkmcnt(0)
	v_add_f32_e32 v60, v60, v80
	v_fmamk_f32 v60, v60, 0x3c000000, v189
	v_cmp_gt_f32_e32 vcc, s2, v60
	v_mul_f32_e32 v80, 0x4f800000, v60
	s_nop 0
	v_cndmask_b32_e32 v60, v60, v80, vcc
	v_sqrt_f32_e32 v80, v60
	s_nop 0
	v_add_u32_e32 v82, -1, v80
	v_fma_f32 v83, -v82, v80, v60
	v_cmp_ge_f32_e64 s[0:1], 0, v83
	v_add_u32_e32 v83, 1, v80
	s_nop 0
	v_cndmask_b32_e64 v82, v80, v82, s[0:1]
	v_fma_f32 v80, -v83, v80, v60
	v_cmp_lt_f32_e64 s[0:1], 0, v80
	s_nop 1
	v_cndmask_b32_e64 v80, v82, v83, s[0:1]
	v_mul_f32_e32 v82, 0x37800000, v80
	v_cndmask_b32_e32 v80, v80, v82, vcc
	v_cmp_class_f32_e32 vcc, v60, v190
	s_nop 1
	v_cndmask_b32_e32 v60, v80, v60, vcc
	v_div_scale_f32 v80, s[0:1], v60, v60, 1.0
	v_rcp_f32_e32 v82, v80
	s_nop 0
	v_fma_f32 v83, -v80, v82, 1.0
	v_fmac_f32_e32 v82, v83, v82
	v_div_scale_f32 v83, vcc, 1.0, v60, 1.0
	v_mul_f32_e32 v84, v83, v82
	v_fma_f32 v85, -v80, v84, v83
	v_fmac_f32_e32 v84, v85, v82
	v_fma_f32 v80, -v80, v84, v83
	v_div_fmas_f32 v80, v80, v82, v84
	v_div_fixup_f32 v80, v80, v60, 1.0
	v_mul_f32_e32 v60, v80, v0
	v_mul_f32_e32 v58, v60, v58
	v_mul_f32_e32 v60, v80, v4
	v_mul_f32_e32 v59, v60, v59
	v_mul_f32_e32 v60, v80, v5
	v_mul_f32_e32 v60, v60, v61
	v_mul_f32_e32 v61, v80, v6
	s_nop 1
	v_mov_b32_dpp v80, v68 quad_perm:[1,0,3,2] row_mask:0xf bank_mask:0xf
	v_mul_f32_e32 v61, v61, v81
	s_waitcnt lgkmcnt(0)
	v_add_f32_e32 v68, v68, v80
	s_nop 1
	v_mov_b32_dpp v80, v68 quad_perm:[2,3,0,1] row_mask:0xf bank_mask:0xf
	s_waitcnt lgkmcnt(0)
	v_add_f32_e32 v68, v68, v80
	s_nop 1
	v_mov_b32_dpp v80, v68 row_half_mirror row_mask:0xf bank_mask:0xf
	s_waitcnt lgkmcnt(0)
	v_add_f32_e32 v68, v68, v80
	s_nop 1
	v_mov_b32_dpp v80, v68 row_mirror row_mask:0xf bank_mask:0xf
	s_waitcnt lgkmcnt(0)
	v_add_f32_e32 v68, v68, v80
	v_mov_b32_e32 v80, v68
	s_nop 1
	v_permlane16_swap_b32_e32 v68, v80
	s_waitcnt lgkmcnt(0)
	v_add_f32_e32 v68, v68, v80
	v_fmamk_f32 v68, v68, 0x3c000000, v189
	v_cmp_gt_f32_e32 vcc, s2, v68
	v_mul_f32_e32 v80, 0x4f800000, v68
	s_nop 0
	v_cndmask_b32_e32 v68, v68, v80, vcc
	v_sqrt_f32_e32 v80, v68
	s_nop 0
	v_add_u32_e32 v81, -1, v80
	v_fma_f32 v82, -v81, v80, v68
	v_cmp_ge_f32_e64 s[0:1], 0, v82
	v_add_u32_e32 v82, 1, v80
	s_nop 0
	v_cndmask_b32_e64 v81, v80, v81, s[0:1]
	v_fma_f32 v80, -v82, v80, v68
	v_cmp_lt_f32_e64 s[0:1], 0, v80
	s_nop 1
	v_cndmask_b32_e64 v80, v81, v82, s[0:1]
	v_mul_f32_e32 v81, 0x37800000, v80
	v_cndmask_b32_e32 v80, v80, v81, vcc
	v_cmp_class_f32_e32 vcc, v68, v190
	s_nop 1
	v_cndmask_b32_e32 v68, v80, v68, vcc
	v_div_scale_f32 v80, s[0:1], v68, v68, 1.0
	v_rcp_f32_e32 v81, v80
	s_nop 0
	v_fma_f32 v82, -v80, v81, 1.0
	v_fmac_f32_e32 v81, v82, v81
	v_div_scale_f32 v82, vcc, 1.0, v68, 1.0
	v_mul_f32_e32 v83, v82, v81
	v_fma_f32 v84, -v80, v83, v82
	v_fmac_f32_e32 v83, v84, v81
	v_fma_f32 v80, -v80, v83, v82
	v_div_fmas_f32 v80, v80, v81, v83
	v_div_fixup_f32 v80, v80, v68, 1.0
	v_mul_f32_e32 v68, v80, v0
	v_mul_f32_e32 v67, v68, v67
	v_mul_f32_e32 v68, v80, v4
	v_mul_f32_e32 v68, v68, v69
	v_mul_f32_e32 v69, v80, v5
	v_mul_f32_e32 v69, v69, v70
	v_mul_f32_e32 v70, v80, v6
	v_mul_f32_e32 v70, v70, v79
	s_nop 1
	v_mov_b32_dpp v79, v74 quad_perm:[1,0,3,2] row_mask:0xf bank_mask:0xf
	s_waitcnt lgkmcnt(0)
	v_add_f32_e32 v74, v74, v79
	s_nop 1
	v_mov_b32_dpp v79, v74 quad_perm:[2,3,0,1] row_mask:0xf bank_mask:0xf
	s_waitcnt lgkmcnt(0)
	v_add_f32_e32 v74, v74, v79
	s_nop 1
	v_mov_b32_dpp v79, v74 row_half_mirror row_mask:0xf bank_mask:0xf
	s_waitcnt lgkmcnt(0)
	v_add_f32_e32 v74, v74, v79
	s_nop 1
	v_mov_b32_dpp v79, v74 row_mirror row_mask:0xf bank_mask:0xf
	s_waitcnt lgkmcnt(0)
	v_add_f32_e32 v74, v74, v79
	v_mov_b32_e32 v79, v74
	s_nop 1
	v_permlane16_swap_b32_e32 v74, v79
	s_waitcnt lgkmcnt(0)
	v_add_f32_e32 v74, v74, v79
	v_fmamk_f32 v74, v74, 0x3c000000, v189
	v_cmp_gt_f32_e32 vcc, s2, v74
	v_mul_f32_e32 v79, 0x4f800000, v74
	s_nop 0
	v_cndmask_b32_e32 v74, v74, v79, vcc
	v_sqrt_f32_e32 v79, v74
	s_nop 0
	v_add_u32_e32 v80, -1, v79
	v_fma_f32 v81, -v80, v79, v74
	v_cmp_ge_f32_e64 s[0:1], 0, v81
	v_add_u32_e32 v81, 1, v79
	s_nop 0
	v_cndmask_b32_e64 v80, v79, v80, s[0:1]
	v_fma_f32 v79, -v81, v79, v74
	v_cmp_lt_f32_e64 s[0:1], 0, v79
	s_nop 1
	v_cndmask_b32_e64 v79, v80, v81, s[0:1]
	v_mul_f32_e32 v80, 0x37800000, v79
	v_cndmask_b32_e32 v79, v79, v80, vcc
	v_cmp_class_f32_e32 vcc, v74, v190
	s_nop 1
	v_cndmask_b32_e32 v74, v79, v74, vcc
	v_div_scale_f32 v79, s[0:1], v74, v74, 1.0
	v_rcp_f32_e32 v80, v79
	s_nop 0
	v_fma_f32 v81, -v79, v80, 1.0
	v_fmac_f32_e32 v80, v81, v80
	v_div_scale_f32 v81, vcc, 1.0, v74, 1.0
	v_mul_f32_e32 v82, v81, v80
	v_fma_f32 v83, -v79, v82, v81
	v_fmac_f32_e32 v82, v83, v80
	v_fma_f32 v79, -v79, v82, v81
	v_div_fmas_f32 v79, v79, v80, v82
	v_div_fixup_f32 v79, v79, v74, 1.0
	v_mul_f32_e32 v74, v79, v0
	v_mul_f32_e32 v64, v74, v64
	v_mul_f32_e32 v74, v79, v4
	v_mul_f32_e32 v72, v74, v72
	v_mul_f32_e32 v74, v79, v5
	v_mul_f32_e32 v74, v74, v76
	v_mul_f32_e32 v76, v79, v6
	v_mul_f32_e32 v76, v76, v78
	s_nop 1
	v_mov_b32_dpp v78, v55 quad_perm:[1,0,3,2] row_mask:0xf bank_mask:0xf
	s_waitcnt lgkmcnt(0)
	v_add_f32_e32 v55, v55, v78
	s_nop 1
	v_mov_b32_dpp v78, v55 quad_perm:[2,3,0,1] row_mask:0xf bank_mask:0xf
	s_waitcnt lgkmcnt(0)
; __global__ void __launch_bounds__(NTHR) mega_fwd(Params p) {
;     ...
;                       for (int r = 0; r < 16; ++r) { float q = ss[r]; q += __shfl_xor(q, 1); q += __shfl_xor(q, 2); q += __shfl_xor(q, 4); q += __shfl_xor(q, 8); q += __shfl_xor(q, 16);
;                           const float rstd = 1.0f / sqrtf(q * (1.0f / 128.0f) + EPS);
; #pragma unroll
;                           for (int d = 0; d < 4; ++d) o[d][r] *= rstd * gsub[d]; } }
	v_add_f32_e32 v55, v55, v78
	s_nop 1
	v_mov_b32_dpp v78, v55 row_half_mirror row_mask:0xf bank_mask:0xf
	s_waitcnt lgkmcnt(0)
	v_add_f32_e32 v55, v55, v78
	s_nop 1
	v_mov_b32_dpp v78, v55 row_mirror row_mask:0xf bank_mask:0xf
	s_waitcnt lgkmcnt(0)
	v_add_f32_e32 v55, v55, v78
	v_mov_b32_e32 v78, v55
	s_nop 1
	v_permlane16_swap_b32_e32 v55, v78
	s_waitcnt lgkmcnt(0)
	v_add_f32_e32 v55, v55, v78
	v_fmamk_f32 v55, v55, 0x3c000000, v189
	v_cmp_gt_f32_e32 vcc, s2, v55
	v_mul_f32_e32 v78, 0x4f800000, v55
	s_nop 0
	v_cndmask_b32_e32 v55, v55, v78, vcc
	v_sqrt_f32_e32 v78, v55
	s_nop 0
	v_add_u32_e32 v79, -1, v78
	v_fma_f32 v80, -v79, v78, v55
	v_cmp_ge_f32_e64 s[0:1], 0, v80
	v_add_u32_e32 v80, 1, v78
	s_nop 0
	v_cndmask_b32_e64 v79, v78, v79, s[0:1]
	v_fma_f32 v78, -v80, v78, v55
	v_cmp_lt_f32_e64 s[0:1], 0, v78
	s_nop 1
	v_cndmask_b32_e64 v78, v79, v80, s[0:1]
	v_mul_f32_e32 v79, 0x37800000, v78
	v_cndmask_b32_e32 v78, v78, v79, vcc
	v_cmp_class_f32_e32 vcc, v55, v190
	s_nop 1
	v_cndmask_b32_e32 v55, v78, v55, vcc
	v_div_scale_f32 v78, s[0:1], v55, v55, 1.0
	v_rcp_f32_e32 v79, v78
	s_nop 0
	v_fma_f32 v80, -v78, v79, 1.0
	v_fmac_f32_e32 v79, v80, v79
	v_div_scale_f32 v80, vcc, 1.0, v55, 1.0
	v_mul_f32_e32 v81, v80, v79
	v_fma_f32 v82, -v78, v81, v80
	v_fmac_f32_e32 v81, v82, v79
	v_fma_f32 v78, -v78, v81, v80
	v_div_fmas_f32 v78, v78, v79, v81
	v_div_fixup_f32 v78, v78, v55, 1.0
	v_mul_f32_e32 v55, v78, v0
	v_mul_f32_e32 v54, v55, v54
	v_mul_f32_e32 v55, v78, v4
	v_mul_f32_e32 v55, v55, v63
	v_mul_f32_e32 v63, v78, v5
	v_mul_f32_e32 v63, v63, v73
	v_mul_f32_e32 v73, v78, v6
	v_mul_f32_e32 v73, v73, v77
	s_nop 1
	v_mov_b32_dpp v77, v65 quad_perm:[1,0,3,2] row_mask:0xf bank_mask:0xf
	s_waitcnt lgkmcnt(0)
	v_add_f32_e32 v65, v65, v77
	s_nop 1
	v_mov_b32_dpp v77, v65 quad_perm:[2,3,0,1] row_mask:0xf bank_mask:0xf
	s_waitcnt lgkmcnt(0)
	v_add_f32_e32 v65, v65, v77
	s_nop 1
	v_mov_b32_dpp v77, v65 row_half_mirror row_mask:0xf bank_mask:0xf
	s_waitcnt lgkmcnt(0)
	v_add_f32_e32 v65, v65, v77
	s_nop 1
	v_mov_b32_dpp v77, v65 row_mirror row_mask:0xf bank_mask:0xf
	s_waitcnt lgkmcnt(0)
	v_add_f32_e32 v65, v65, v77
	v_mov_b32_e32 v77, v65
	s_nop 1
	v_permlane16_swap_b32_e32 v65, v77
	s_waitcnt lgkmcnt(0)
	v_add_f32_e32 v65, v65, v77
	v_fmamk_f32 v65, v65, 0x3c000000, v189
	v_cmp_gt_f32_e32 vcc, s2, v65
	v_mul_f32_e32 v77, 0x4f800000, v65
	s_nop 0
	v_cndmask_b32_e32 v65, v65, v77, vcc
	v_sqrt_f32_e32 v77, v65
	s_nop 0
	v_add_u32_e32 v78, -1, v77
	v_fma_f32 v79, -v78, v77, v65
	v_cmp_ge_f32_e64 s[0:1], 0, v79
	v_add_u32_e32 v79, 1, v77
	s_nop 0
	v_cndmask_b32_e64 v78, v77, v78, s[0:1]
	v_fma_f32 v77, -v79, v77, v65
	v_cmp_lt_f32_e64 s[0:1], 0, v77
	s_nop 1
	v_cndmask_b32_e64 v77, v78, v79, s[0:1]
	v_mul_f32_e32 v78, 0x37800000, v77
	v_cndmask_b32_e32 v77, v77, v78, vcc
	v_cmp_class_f32_e32 vcc, v65, v190
	s_nop 1
	v_cndmask_b32_e32 v65, v77, v65, vcc
	v_div_scale_f32 v77, s[0:1], v65, v65, 1.0
	v_rcp_f32_e32 v78, v77
	s_nop 0
	v_fma_f32 v79, -v77, v78, 1.0
	v_fmac_f32_e32 v78, v79, v78
	v_div_scale_f32 v79, vcc, 1.0, v65, 1.0
	v_mul_f32_e32 v80, v79, v78
	v_fma_f32 v81, -v77, v80, v79
	v_fmac_f32_e32 v80, v81, v78
	v_fma_f32 v77, -v77, v80, v79
	v_div_fmas_f32 v77, v77, v78, v80
	v_div_fixup_f32 v77, v77, v65, 1.0
	v_mul_f32_e32 v65, v77, v0
	v_mul_f32_e32 v47, v65, v47
	v_mul_f32_e32 v65, v77, v4
	v_mul_f32_e32 v57, v65, v57
	v_mul_f32_e32 v65, v77, v5
	v_mul_f32_e32 v65, v65, v71
	v_mul_f32_e32 v71, v77, v6
	v_mul_f32_e32 v71, v71, v75
	s_nop 1
	v_mov_b32_dpp v75, v44 quad_perm:[1,0,3,2] row_mask:0xf bank_mask:0xf
	s_waitcnt lgkmcnt(0)
	v_add_f32_e32 v44, v44, v75
	s_nop 1
	v_mov_b32_dpp v75, v44 quad_perm:[2,3,0,1] row_mask:0xf bank_mask:0xf
	s_waitcnt lgkmcnt(0)
	v_add_f32_e32 v44, v44, v75
	s_nop 1
	v_mov_b32_dpp v75, v44 row_half_mirror row_mask:0xf bank_mask:0xf
	s_waitcnt lgkmcnt(0)
	v_add_f32_e32 v44, v44, v75
	s_nop 1
	v_mov_b32_dpp v75, v44 row_mirror row_mask:0xf bank_mask:0xf
	s_waitcnt lgkmcnt(0)
	v_add_f32_e32 v44, v44, v75
	v_mov_b32_e32 v75, v44
	s_nop 1
	v_permlane16_swap_b32_e32 v44, v75
	s_waitcnt lgkmcnt(0)
	v_add_f32_e32 v44, v44, v75
	v_fmamk_f32 v44, v44, 0x3c000000, v189
	v_cmp_gt_f32_e32 vcc, s2, v44
	v_mul_f32_e32 v75, 0x4f800000, v44
	s_nop 0
	v_cndmask_b32_e32 v44, v44, v75, vcc
	v_sqrt_f32_e32 v75, v44
	s_nop 0
	v_add_u32_e32 v77, -1, v75
	v_fma_f32 v78, -v77, v75, v44
	v_cmp_ge_f32_e64 s[0:1], 0, v78
	v_add_u32_e32 v78, 1, v75
	s_nop 0
	v_cndmask_b32_e64 v77, v75, v77, s[0:1]
	v_fma_f32 v75, -v78, v75, v44
	v_cmp_lt_f32_e64 s[0:1], 0, v75
	s_nop 1
	v_cndmask_b32_e64 v75, v77, v78, s[0:1]
	v_mul_f32_e32 v77, 0x37800000, v75
	v_cndmask_b32_e32 v75, v75, v77, vcc
	v_cmp_class_f32_e32 vcc, v44, v190
	s_nop 1
	v_cndmask_b32_e32 v44, v75, v44, vcc
	v_div_scale_f32 v75, s[0:1], v44, v44, 1.0
	v_rcp_f32_e32 v77, v75
	s_nop 0
	v_fma_f32 v78, -v75, v77, 1.0
	v_fmac_f32_e32 v77, v78, v77
	v_div_scale_f32 v78, vcc, 1.0, v44, 1.0
	v_mul_f32_e32 v79, v78, v77
	v_fma_f32 v80, -v75, v79, v78
	v_fmac_f32_e32 v79, v80, v77
	v_fma_f32 v75, -v75, v79, v78
	v_div_fmas_f32 v75, v75, v77, v79
	v_div_fixup_f32 v75, v75, v44, 1.0
	v_mul_f32_e32 v44, v75, v0
	v_mul_f32_e32 v37, v44, v37
	v_mul_f32_e32 v44, v75, v4
	v_mul_f32_e32 v44, v44, v48
	v_mul_f32_e32 v48, v75, v5
	v_mul_f32_e32 v48, v48, v62
	v_mul_f32_e32 v62, v75, v6
	v_mul_f32_e32 v62, v62, v66
	s_nop 1
	v_mov_b32_dpp v66, v45 quad_perm:[1,0,3,2] row_mask:0xf bank_mask:0xf
	s_waitcnt lgkmcnt(0)
	v_add_f32_e32 v45, v45, v66
	s_nop 1
	v_mov_b32_dpp v66, v45 quad_perm:[2,3,0,1] row_mask:0xf bank_mask:0xf
	s_waitcnt lgkmcnt(0)
	v_add_f32_e32 v45, v45, v66
	s_nop 1
	v_mov_b32_dpp v66, v45 row_half_mirror row_mask:0xf bank_mask:0xf
	s_waitcnt lgkmcnt(0)
; __global__ void __launch_bounds__(NTHR) mega_fwd(Params p) {
;     ...
;                       for (int r = 0; r < 16; ++r) { float q = ss[r]; q += __shfl_xor(q, 1); q += __shfl_xor(q, 2); q += __shfl_xor(q, 4); q += __shfl_xor(q, 8); q += __shfl_xor(q, 16);
;                           const float rstd = 1.0f / sqrtf(q * (1.0f / 128.0f) + EPS);
; #pragma unroll
;                           for (int d = 0; d < 4; ++d) o[d][r] *= rstd * gsub[d]; } }
	v_add_f32_e32 v45, v45, v66
	s_nop 1
	v_mov_b32_dpp v66, v45 row_mirror row_mask:0xf bank_mask:0xf
	s_waitcnt lgkmcnt(0)
	v_add_f32_e32 v45, v45, v66
	v_mov_b32_e32 v66, v45
	s_nop 1
	v_permlane16_swap_b32_e32 v45, v66
	s_waitcnt lgkmcnt(0)
	v_add_f32_e32 v45, v45, v66
	v_fmamk_f32 v45, v45, 0x3c000000, v189
	v_cmp_gt_f32_e32 vcc, s2, v45
	v_mul_f32_e32 v66, 0x4f800000, v45
	s_nop 0
	v_cndmask_b32_e32 v45, v45, v66, vcc
	v_sqrt_f32_e32 v66, v45
	s_nop 0
	v_add_u32_e32 v75, -1, v66
	v_fma_f32 v77, -v75, v66, v45
	v_cmp_ge_f32_e64 s[0:1], 0, v77
	v_add_u32_e32 v77, 1, v66
	s_nop 0
	v_cndmask_b32_e64 v75, v66, v75, s[0:1]
	v_fma_f32 v66, -v77, v66, v45
	v_cmp_lt_f32_e64 s[0:1], 0, v66
	s_nop 1
	v_cndmask_b32_e64 v66, v75, v77, s[0:1]
	v_mul_f32_e32 v75, 0x37800000, v66
	v_cndmask_b32_e32 v66, v66, v75, vcc
	v_cmp_class_f32_e32 vcc, v45, v190
	s_nop 1
	v_cndmask_b32_e32 v45, v66, v45, vcc
	v_div_scale_f32 v66, s[0:1], v45, v45, 1.0
	v_rcp_f32_e32 v75, v66
	s_nop 0
	v_fma_f32 v77, -v66, v75, 1.0
	v_fmac_f32_e32 v75, v77, v75
	v_div_scale_f32 v77, vcc, 1.0, v45, 1.0
	v_mul_f32_e32 v78, v77, v75
	v_fma_f32 v79, -v66, v78, v77
	v_fmac_f32_e32 v78, v79, v75
	v_fma_f32 v66, -v66, v78, v77
	v_div_fmas_f32 v66, v66, v75, v78
	v_div_fixup_f32 v66, v66, v45, 1.0
	v_mul_f32_e32 v45, v66, v0
	v_mul_f32_e32 v29, v45, v29
	v_mul_f32_e32 v45, v66, v4
	v_mul_f32_e32 v38, v45, v38
	v_mul_f32_e32 v45, v66, v5
	v_mul_f32_e32 v45, v45, v53
	v_mul_f32_e32 v53, v66, v6
	v_mul_f32_e32 v53, v53, v56
	s_nop 1
	v_mov_b32_dpp v56, v26 quad_perm:[1,0,3,2] row_mask:0xf bank_mask:0xf
	s_waitcnt lgkmcnt(0)
	v_add_f32_e32 v26, v26, v56
	s_nop 1
	v_mov_b32_dpp v56, v26 quad_perm:[2,3,0,1] row_mask:0xf bank_mask:0xf
	s_waitcnt lgkmcnt(0)
	v_add_f32_e32 v26, v26, v56
	s_nop 1
	v_mov_b32_dpp v56, v26 row_half_mirror row_mask:0xf bank_mask:0xf
	s_waitcnt lgkmcnt(0)
	v_add_f32_e32 v26, v26, v56
	s_nop 1
	v_mov_b32_dpp v56, v26 row_mirror row_mask:0xf bank_mask:0xf
	s_waitcnt lgkmcnt(0)
	v_add_f32_e32 v26, v26, v56
	v_mov_b32_e32 v56, v26
	s_nop 1
	v_permlane16_swap_b32_e32 v26, v56
	s_waitcnt lgkmcnt(0)
	v_add_f32_e32 v26, v26, v56
	v_fmamk_f32 v26, v26, 0x3c000000, v189
	v_cmp_gt_f32_e32 vcc, s2, v26
	v_mul_f32_e32 v56, 0x4f800000, v26
	s_nop 0
	v_cndmask_b32_e32 v26, v26, v56, vcc
	v_sqrt_f32_e32 v56, v26
	s_nop 0
	v_add_u32_e32 v66, -1, v56
	v_fma_f32 v75, -v66, v56, v26
	v_cmp_ge_f32_e64 s[0:1], 0, v75
	v_add_u32_e32 v75, 1, v56
	s_nop 0
	v_cndmask_b32_e64 v66, v56, v66, s[0:1]
	v_fma_f32 v56, -v75, v56, v26
	v_cmp_lt_f32_e64 s[0:1], 0, v56
	s_nop 1
	v_cndmask_b32_e64 v56, v66, v75, s[0:1]
	v_mul_f32_e32 v66, 0x37800000, v56
	v_cndmask_b32_e32 v56, v56, v66, vcc
	v_cmp_class_f32_e32 vcc, v26, v190
	s_nop 1
	v_cndmask_b32_e32 v26, v56, v26, vcc
	v_div_scale_f32 v56, s[0:1], v26, v26, 1.0
	v_rcp_f32_e32 v66, v56
	s_nop 0
	v_fma_f32 v75, -v56, v66, 1.0
	v_fmac_f32_e32 v66, v75, v66
	v_div_scale_f32 v75, vcc, 1.0, v26, 1.0
	v_mul_f32_e32 v77, v75, v66
	v_fma_f32 v78, -v56, v77, v75
	v_fmac_f32_e32 v77, v78, v66
	v_fma_f32 v56, -v56, v77, v75
	v_div_fmas_f32 v56, v56, v66, v77
	v_div_fixup_f32 v56, v56, v26, 1.0
	v_mul_f32_e32 v26, v56, v0
	v_mul_f32_e32 v19, v26, v19
	v_mul_f32_e32 v26, v56, v4
	v_mul_f32_e32 v26, v26, v30
	v_mul_f32_e32 v30, v56, v5
	v_mul_f32_e32 v30, v30, v43
	v_mul_f32_e32 v43, v56, v6
	v_mul_f32_e32 v43, v43, v46
	s_nop 1
	v_mov_b32_dpp v46, v27 quad_perm:[1,0,3,2] row_mask:0xf bank_mask:0xf
	s_waitcnt lgkmcnt(0)
	v_add_f32_e32 v27, v27, v46
	s_nop 1
	v_mov_b32_dpp v46, v27 quad_perm:[2,3,0,1] row_mask:0xf bank_mask:0xf
	s_waitcnt lgkmcnt(0)
	v_add_f32_e32 v27, v27, v46
	s_nop 1
	v_mov_b32_dpp v46, v27 row_half_mirror row_mask:0xf bank_mask:0xf
	s_waitcnt lgkmcnt(0)
	v_add_f32_e32 v27, v27, v46
	s_nop 1
	v_mov_b32_dpp v46, v27 row_mirror row_mask:0xf bank_mask:0xf
	s_waitcnt lgkmcnt(0)
	v_add_f32_e32 v27, v27, v46
	v_mov_b32_e32 v46, v27
	s_nop 1
	v_permlane16_swap_b32_e32 v27, v46
	s_waitcnt lgkmcnt(0)
	v_add_f32_e32 v27, v27, v46
	v_fmamk_f32 v27, v27, 0x3c000000, v189
	v_cmp_gt_f32_e32 vcc, s2, v27
	v_mul_f32_e32 v46, 0x4f800000, v27
	s_nop 0
	v_cndmask_b32_e32 v27, v27, v46, vcc
	v_sqrt_f32_e32 v46, v27
	s_nop 0
	v_add_u32_e32 v56, -1, v46
	v_fma_f32 v66, -v56, v46, v27
	v_cmp_ge_f32_e64 s[0:1], 0, v66
	v_add_u32_e32 v66, 1, v46
	s_nop 0
	v_cndmask_b32_e64 v56, v46, v56, s[0:1]
	v_fma_f32 v46, -v66, v46, v27
	v_cmp_lt_f32_e64 s[0:1], 0, v46
	s_nop 1
	v_cndmask_b32_e64 v46, v56, v66, s[0:1]
	v_mul_f32_e32 v56, 0x37800000, v46
	v_cndmask_b32_e32 v46, v46, v56, vcc
	v_cmp_class_f32_e32 vcc, v27, v190
	s_nop 1
	v_cndmask_b32_e32 v27, v46, v27, vcc
	v_div_scale_f32 v46, s[0:1], v27, v27, 1.0
	v_rcp_f32_e32 v56, v46
	s_nop 0
	v_fma_f32 v66, -v46, v56, 1.0
	v_fmac_f32_e32 v56, v66, v56
	v_div_scale_f32 v66, vcc, 1.0, v27, 1.0
	v_mul_f32_e32 v75, v66, v56
	v_fma_f32 v77, -v46, v75, v66
	v_fmac_f32_e32 v75, v77, v56
	v_fma_f32 v46, -v46, v75, v66
	v_div_fmas_f32 v46, v46, v56, v75
	v_div_fixup_f32 v46, v46, v27, 1.0
	v_mul_f32_e32 v27, v46, v0
	v_mul_f32_e32 v15, v27, v15
	v_mul_f32_e32 v27, v46, v4
	v_mul_f32_e32 v21, v27, v21
	v_mul_f32_e32 v27, v46, v5
	v_mul_f32_e32 v27, v27, v35
	v_mul_f32_e32 v35, v46, v6
	v_mul_f32_e32 v35, v35, v36
	s_nop 1
	v_mov_b32_dpp v36, v12 quad_perm:[1,0,3,2] row_mask:0xf bank_mask:0xf
	s_waitcnt lgkmcnt(0)
	v_add_f32_e32 v12, v12, v36
	s_nop 1
	v_mov_b32_dpp v36, v12 quad_perm:[2,3,0,1] row_mask:0xf bank_mask:0xf
	s_waitcnt lgkmcnt(0)
	v_add_f32_e32 v12, v12, v36
	s_nop 1
	v_mov_b32_dpp v36, v12 row_half_mirror row_mask:0xf bank_mask:0xf
	s_waitcnt lgkmcnt(0)
	v_add_f32_e32 v12, v12, v36
	s_nop 1
	v_mov_b32_dpp v36, v12 row_mirror row_mask:0xf bank_mask:0xf
	s_waitcnt lgkmcnt(0)
; __device__ __forceinline__ int opaque_tid() { int t = threadIdx.x; asm volatile("" : "+v"(t)); return t; }
; __device__ __forceinline__ void store_o_bf16(const att::f32x16 (&o)[4], bf16* base  , unsigned char* lds) {
;     const int tid = opaque_tid(), lane = tid & 63, wave = __builtin_amdgcn_readfirstlane(tid >> 6), r32 = lane & 31, hi = lane >> 5;
;     __syncthreads();
;     float* T = (float*)(lds + wave * 16896);
; __global__ void __launch_bounds__(NTHR) mega_fwd(Params p) {
;     ...
;                       for (int r = 0; r < 16; ++r) { float q = ss[r]; q += __shfl_xor(q, 1); q += __shfl_xor(q, 2); q += __shfl_xor(q, 4); q += __shfl_xor(q, 8); q += __shfl_xor(q, 16);
;                           const float rstd = 1.0f / sqrtf(q * (1.0f / 128.0f) + EPS);
; #pragma unroll
;                           for (int d = 0; d < 4; ++d) o[d][r] *= rstd * gsub[d]; } }
	v_add_f32_e32 v12, v12, v36
	v_mov_b32_e32 v36, v12
	s_nop 1
	v_permlane16_swap_b32_e32 v12, v36
	s_waitcnt lgkmcnt(0)
	v_add_f32_e32 v12, v12, v36
	v_fmamk_f32 v12, v12, 0x3c000000, v189
	v_cmp_gt_f32_e32 vcc, s2, v12
	v_mul_f32_e32 v36, 0x4f800000, v12
	s_nop 0
	v_cndmask_b32_e32 v12, v12, v36, vcc
	v_sqrt_f32_e32 v36, v12
	s_nop 0
	v_add_u32_e32 v46, -1, v36
	v_fma_f32 v56, -v46, v36, v12
	v_cmp_ge_f32_e64 s[0:1], 0, v56
	v_add_u32_e32 v56, 1, v36
	s_nop 0
	v_cndmask_b32_e64 v46, v36, v46, s[0:1]
	v_fma_f32 v36, -v56, v36, v12
	v_cmp_lt_f32_e64 s[0:1], 0, v36
	s_nop 1
	v_cndmask_b32_e64 v36, v46, v56, s[0:1]
	v_mul_f32_e32 v46, 0x37800000, v36
	v_cndmask_b32_e32 v36, v36, v46, vcc
	v_cmp_class_f32_e32 vcc, v12, v190
	s_nop 1
	v_cndmask_b32_e32 v12, v36, v12, vcc
	v_div_scale_f32 v36, s[0:1], v12, v12, 1.0
	v_rcp_f32_e32 v46, v36
	s_nop 0
	v_fma_f32 v56, -v36, v46, 1.0
	v_fmac_f32_e32 v46, v56, v46
	v_div_scale_f32 v56, vcc, 1.0, v12, 1.0
	v_mul_f32_e32 v66, v56, v46
	v_fma_f32 v75, -v36, v66, v56
	v_fmac_f32_e32 v66, v75, v46
	v_fma_f32 v36, -v36, v66, v56
	v_div_fmas_f32 v36, v36, v46, v66
	v_div_fixup_f32 v36, v36, v12, 1.0
	v_mul_f32_e32 v12, v36, v0
	v_mul_f32_e32 v9, v12, v9
	v_mul_f32_e32 v12, v36, v4
	v_mul_f32_e32 v12, v12, v16
	v_mul_f32_e32 v16, v36, v5
	v_mul_f32_e32 v16, v16, v25
	v_mul_f32_e32 v25, v36, v6
	v_mul_f32_e32 v25, v25, v28
	s_nop 1
	v_mov_b32_dpp v28, v13 quad_perm:[1,0,3,2] row_mask:0xf bank_mask:0xf
	s_waitcnt lgkmcnt(0)
	v_add_f32_e32 v13, v13, v28
	s_nop 1
	v_mov_b32_dpp v28, v13 quad_perm:[2,3,0,1] row_mask:0xf bank_mask:0xf
	s_waitcnt lgkmcnt(0)
	v_add_f32_e32 v13, v13, v28
	s_nop 1
	v_mov_b32_dpp v28, v13 row_half_mirror row_mask:0xf bank_mask:0xf
	s_waitcnt lgkmcnt(0)
	v_add_f32_e32 v13, v13, v28
	s_nop 1
	v_mov_b32_dpp v28, v13 row_mirror row_mask:0xf bank_mask:0xf
	s_waitcnt lgkmcnt(0)
	v_add_f32_e32 v13, v13, v28
	v_mov_b32_e32 v28, v13
	s_nop 1
	v_permlane16_swap_b32_e32 v13, v28
	s_waitcnt lgkmcnt(0)
	v_add_f32_e32 v13, v13, v28
	v_fmamk_f32 v13, v13, 0x3c000000, v189
	v_cmp_gt_f32_e32 vcc, s2, v13
	v_mul_f32_e32 v28, 0x4f800000, v13
	s_nop 0
	v_cndmask_b32_e32 v13, v13, v28, vcc
	v_sqrt_f32_e32 v28, v13
	s_nop 0
	v_add_u32_e32 v36, -1, v28
	v_fma_f32 v46, -v36, v28, v13
	v_cmp_ge_f32_e64 s[0:1], 0, v46
	v_add_u32_e32 v46, 1, v28
	s_nop 0
	v_cndmask_b32_e64 v36, v28, v36, s[0:1]
	v_fma_f32 v28, -v46, v28, v13
	v_cmp_lt_f32_e64 s[0:1], 0, v28
	s_nop 1
	v_cndmask_b32_e64 v28, v36, v46, s[0:1]
	v_mul_f32_e32 v36, 0x37800000, v28
	v_cndmask_b32_e32 v28, v28, v36, vcc
	v_cmp_class_f32_e32 vcc, v13, v190
	s_nop 1
	v_cndmask_b32_e32 v13, v28, v13, vcc
	v_div_scale_f32 v28, s[0:1], v13, v13, 1.0
	v_rcp_f32_e32 v36, v28
	s_nop 0
	v_fma_f32 v46, -v28, v36, 1.0
	v_fmac_f32_e32 v36, v46, v36
	v_div_scale_f32 v46, vcc, 1.0, v13, 1.0
	v_mul_f32_e32 v56, v46, v36
	v_fma_f32 v66, -v28, v56, v46
	v_fmac_f32_e32 v56, v66, v36
	v_fma_f32 v28, -v28, v56, v46
	v_div_fmas_f32 v28, v28, v36, v56
	v_div_fixup_f32 v13, v28, v13, 1.0
	v_mul_f32_e32 v28, v13, v0
	v_mul_f32_e32 v7, v28, v7
	v_mul_f32_e32 v28, v13, v4
	v_mul_f32_e32 v11, v28, v11
	v_mul_f32_e32 v28, v13, v5
	v_mul_f32_e32 v13, v13, v6
	v_mul_f32_e32 v13, v13, v18
	s_nop 1
	v_mov_b32_dpp v18, v3 quad_perm:[1,0,3,2] row_mask:0xf bank_mask:0xf
	v_mul_f32_e32 v17, v28, v17
	s_waitcnt lgkmcnt(0)
	v_add_f32_e32 v3, v3, v18
	s_nop 1
	v_mov_b32_dpp v18, v3 quad_perm:[2,3,0,1] row_mask:0xf bank_mask:0xf
	s_waitcnt lgkmcnt(0)
	v_add_f32_e32 v3, v3, v18
	s_nop 1
	v_mov_b32_dpp v18, v3 row_half_mirror row_mask:0xf bank_mask:0xf
	s_waitcnt lgkmcnt(0)
	v_add_f32_e32 v3, v3, v18
	s_nop 1
	v_mov_b32_dpp v18, v3 row_mirror row_mask:0xf bank_mask:0xf
	s_waitcnt lgkmcnt(0)
	v_add_f32_e32 v3, v3, v18
	v_mov_b32_e32 v18, v3
	s_nop 1
	v_permlane16_swap_b32_e32 v3, v18
	s_waitcnt lgkmcnt(0)
	v_add_f32_e32 v3, v3, v18
	v_fmamk_f32 v3, v3, 0x3c000000, v189
	v_cmp_gt_f32_e32 vcc, s2, v3
	v_mul_f32_e32 v18, 0x4f800000, v3
	v_readlane_b32 s2, v253, 7
	v_cndmask_b32_e32 v3, v3, v18, vcc
	v_sqrt_f32_e32 v18, v3
	v_readlane_b32 s3, v253, 8
	v_add_u32_e32 v28, -1, v18
	v_fma_f32 v36, -v28, v18, v3
	v_cmp_ge_f32_e64 s[0:1], 0, v36
	v_add_u32_e32 v36, 1, v18
	s_nop 0
	v_cndmask_b32_e64 v28, v18, v28, s[0:1]
	v_fma_f32 v18, -v36, v18, v3
	v_cmp_lt_f32_e64 s[0:1], 0, v18
	s_nop 1
	v_cndmask_b32_e64 v18, v28, v36, s[0:1]
	v_mul_f32_e32 v28, 0x37800000, v18
	v_cndmask_b32_e32 v18, v18, v28, vcc
	v_cmp_class_f32_e32 vcc, v3, v190
	s_nop 1
	v_cndmask_b32_e32 v3, v18, v3, vcc
	v_div_scale_f32 v18, s[0:1], v3, v3, 1.0
	v_rcp_f32_e32 v28, v18
	s_nop 0
	v_fma_f32 v36, -v18, v28, 1.0
	v_fmac_f32_e32 v28, v36, v28
	v_div_scale_f32 v36, vcc, 1.0, v3, 1.0
	v_mul_f32_e32 v46, v36, v28
	v_fma_f32 v56, -v18, v46, v36
	v_fmac_f32_e32 v46, v56, v28
	v_fma_f32 v18, -v18, v46, v36
	v_div_fmas_f32 v18, v18, v28, v46
	v_div_fixup_f32 v3, v18, v3, 1.0
	v_mul_f32_e32 v0, v3, v0
	v_mul_f32_e32 v0, v0, v2
	v_mul_f32_e32 v2, v3, v4
	v_mul_f32_e32 v4, v3, v5
	v_mov_b32_e32 v5, v188
	v_mul_f32_e32 v2, v2, v8
	v_readfirstlane_b32 s0, v5
	s_ashr_i32 s0, s0, 6
	v_lshrrev_b32_e32 v8, 3, v5
	v_mul_f32_e32 v3, v3, v6
	v_and_b32_e32 v6, 31, v5
	s_mul_i32 s1, s0, 0x4200
	v_and_b32_e32 v8, 4, v8
	s_add_i32 s1, s1, 0
	v_lshlrev_b32_e32 v6, 2, v6
	v_mul_u32_u24_e32 v8, 0x210, v8
	v_add3_u32 v6, s1, v6, v8
	v_add_u32_e32 v8, 0x400, v6
	s_barrier
; __device__ __forceinline__ int crow(int r, int hi) { return (r & 3) + 8 * (r >> 2) + 4 * hi; }
; __device__ __forceinline__ unsigned cvtpk(float lo, float hi) { unsigned r; asm volatile("v_cvt_pk_bf16_f32 %0, %1, %2" : "=v"(r) : "v"(lo), "v"(hi)); return r; }
; __device__ __forceinline__ void store_o_bf16(const att::f32x16 (&o)[4], bf16* base  , unsigned char* lds) {
;     ...
;     for (int r = 0; r < 16; ++r) { float* tp = T + att::crow(r, hi) * 132 + r32;
; #pragma unroll
;         for (int d = 0; d < 4; ++d) tp[32 * d] = o[d][r]; }
; #pragma unroll
;     for (int k = 0; k < 8; ++k) { const int chunk = k * 64 + lane, row = chunk >> 4, c8 = chunk & 15;
;         const f32x4 a = *(const f32x4*)(T + row * 132 + c8 * 8), b = *(const f32x4*)(T + row * 132 + c8 * 8 + 4);
;         v4u w; w.x = att::cvtpk(a.x, a.y); w.y = att::cvtpk(a.z, a.w); w.z = att::cvtpk(b.x, b.y); w.w = att::cvtpk(b.z, b.w);
;         *(v4u*)(base + (size_t)(wave * 32 + row) * DM + c8 * 8) = w; }
	ds_write2_b32 v6, v20, v22 offset1:32
	ds_write2_b32 v6, v23, v24 offset0:64 offset1:96
	ds_write2_b32 v6, v31, v32 offset0:132 offset1:164
	ds_write2_b32 v6, v33, v34 offset0:196 offset1:228
	ds_write2_b32 v8, v39, v40 offset0:8 offset1:40
	ds_write2_b32 v8, v41, v42 offset0:72 offset1:104
	ds_write2_b32 v8, v49, v50 offset0:140 offset1:172
	ds_write2_b32 v8, v51, v52 offset0:204 offset1:236
	v_add_u32_e32 v8, 0x1000, v6
	ds_write2_b32 v8, v58, v59 offset0:32 offset1:64
	ds_write2_b32 v8, v60, v61 offset0:96 offset1:128
	ds_write2_b32 v8, v67, v68 offset0:164 offset1:196
	v_add_u32_e32 v8, 0x1200, v6
	ds_write2_b32 v8, v69, v70 offset0:100 offset1:132
	v_add_u32_e32 v8, 0x1400, v6
	ds_write2_b32 v8, v64, v72 offset0:40 offset1:72
	ds_write2_b32 v8, v74, v76 offset0:104 offset1:136
	ds_write2_b32 v8, v54, v55 offset0:172 offset1:204
	v_add_u32_e32 v8, 0x1600, v6
	ds_write2_b32 v8, v63, v73 offset0:108 offset1:140
	v_add_u32_e32 v8, 0x2000, v6
	ds_write2_b32 v8, v47, v57 offset0:64 offset1:96
	ds_write2_b32 v8, v65, v71 offset0:128 offset1:160
	ds_write2_b32 v8, v37, v44 offset0:196 offset1:228
	v_add_u32_e32 v8, 0x2400, v6
	ds_write2_b32 v8, v48, v62 offset0:4 offset1:36
	ds_write2_b32 v8, v29, v38 offset0:72 offset1:104
	ds_write2_b32 v8, v45, v53 offset0:136 offset1:168
	ds_write2_b32 v8, v19, v26 offset0:204 offset1:236
	v_add_u32_e32 v8, 0x2800, v6
	ds_write2_b32 v8, v30, v43 offset0:12 offset1:44
	v_add_u32_e32 v8, 0x3000, v6
	ds_write2_b32 v8, v15, v21 offset0:96 offset1:128
	ds_write2_b32 v8, v27, v35 offset0:160 offset1:192
	v_add_u32_e32 v8, 0x3200, v6
	ds_write2_b32 v8, v9, v12 offset0:100 offset1:132
	v_add_u32_e32 v8, 0x3400, v6
	ds_write2_b32 v8, v16, v25 offset0:36 offset1:68
	ds_write2_b32 v8, v7, v11 offset0:104 offset1:136
	ds_write2_b32 v8, v17, v13 offset0:168 offset1:200
	v_add_u32_e32 v7, 0x3600, v6
	v_mul_f32_e32 v4, v4, v10
	v_mul_f32_e32 v3, v3, v14
	ds_write2_b32 v7, v0, v2 offset0:108 offset1:140
	v_add_u32_e32 v0, 0x3800, v6
	ds_write2_b32 v0, v4, v3 offset0:44 offset1:76
	v_lshlrev_b32_e32 v0, 3, v5
	v_and_b32_e32 v0, 0x78, v0
	v_lshlrev_b32_e32 v2, 2, v0
	v_lshlrev_b32_e32 v0, 1, v0
	v_lshl_add_u64 v[6:7], s[2:3], 0, v[0:1]
	v_bfe_u32 v0, v5, 4, 2
	v_mul_u32_u24_e32 v3, 0x210, v0
	v_add3_u32 v14, s1, v2, v3
	ds_read_b128 v[2:5], v14
	ds_read_b128 v[8:11], v14 offset:16
	s_waitcnt lgkmcnt(1)
	v_cvt_pk_bf16_f32 v2, v2, v3
	v_cvt_pk_bf16_f32 v3, v4, v5
	s_waitcnt lgkmcnt(0)
	v_cvt_pk_bf16_f32 v4, v8, v9
	v_lshl_or_b32 v8, s0, 5, v0
	v_ashrrev_i32_e32 v9, 31, v8
	v_cvt_pk_bf16_f32 v5, v10, v11
	v_lshlrev_b64 v[10:11], 12, v[8:9]
	v_lshl_add_u64 v[10:11], v[6:7], 0, v[10:11]
	global_store_dwordx4 v[10:11], v[2:5], off
	ds_read_b128 v[2:5], v14 offset:2112
	ds_read_b128 v[10:13], v14 offset:2128
	s_waitcnt lgkmcnt(1)
	v_cvt_pk_bf16_f32 v2, v2, v3
	v_cvt_pk_bf16_f32 v3, v4, v5
	s_waitcnt lgkmcnt(0)
	v_cvt_pk_bf16_f32 v4, v10, v11
	v_or_b32_e32 v10, 4, v8
	v_ashrrev_i32_e32 v11, 31, v10
	v_lshlrev_b64 v[10:11], 12, v[10:11]
	v_lshl_add_u64 v[10:11], v[6:7], 0, v[10:11]
	v_cvt_pk_bf16_f32 v5, v12, v13
	global_store_dwordx4 v[10:11], v[2:5], off
	ds_read_b128 v[2:5], v14 offset:4224
	ds_read_b128 v[10:13], v14 offset:4240
	s_waitcnt lgkmcnt(1)
	v_cvt_pk_bf16_f32 v2, v2, v3
	v_cvt_pk_bf16_f32 v3, v4, v5
	s_waitcnt lgkmcnt(0)
	v_cvt_pk_bf16_f32 v4, v10, v11
	v_or_b32_e32 v10, 8, v8
	v_ashrrev_i32_e32 v11, 31, v10
	v_lshlrev_b64 v[10:11], 12, v[10:11]
	v_lshl_add_u64 v[10:11], v[6:7], 0, v[10:11]
	v_cvt_pk_bf16_f32 v5, v12, v13
	global_store_dwordx4 v[10:11], v[2:5], off
	ds_read_b128 v[2:5], v14 offset:6336
	ds_read_b128 v[10:13], v14 offset:6352
	s_waitcnt lgkmcnt(1)
	v_cvt_pk_bf16_f32 v2, v2, v3
	v_cvt_pk_bf16_f32 v3, v4, v5
	s_waitcnt lgkmcnt(0)
	v_cvt_pk_bf16_f32 v4, v10, v11
	v_or_b32_e32 v10, 12, v8
	v_ashrrev_i32_e32 v11, 31, v10
	v_lshlrev_b64 v[10:11], 12, v[10:11]
	v_lshl_add_u64 v[10:11], v[6:7], 0, v[10:11]
	v_cvt_pk_bf16_f32 v5, v12, v13
	global_store_dwordx4 v[10:11], v[2:5], off
	ds_read_b128 v[2:5], v14 offset:8448
	ds_read_b128 v[10:13], v14 offset:8464
	s_waitcnt lgkmcnt(1)
	v_cvt_pk_bf16_f32 v2, v2, v3
	v_cvt_pk_bf16_f32 v3, v4, v5
	s_waitcnt lgkmcnt(0)
	v_cvt_pk_bf16_f32 v4, v10, v11
	v_or_b32_e32 v10, 16, v8
	v_ashrrev_i32_e32 v11, 31, v10
	v_lshlrev_b64 v[10:11], 12, v[10:11]
	v_lshl_add_u64 v[10:11], v[6:7], 0, v[10:11]
	v_cvt_pk_bf16_f32 v5, v12, v13
	global_store_dwordx4 v[10:11], v[2:5], off
	ds_read_b128 v[2:5], v14 offset:10560
	ds_read_b128 v[10:13], v14 offset:10576
	s_waitcnt lgkmcnt(1)
	v_cvt_pk_bf16_f32 v2, v2, v3
	v_cvt_pk_bf16_f32 v3, v4, v5
	s_waitcnt lgkmcnt(0)
	v_cvt_pk_bf16_f32 v4, v10, v11
	v_or_b32_e32 v10, 20, v8
	v_ashrrev_i32_e32 v11, 31, v10
	v_lshlrev_b64 v[10:11], 12, v[10:11]
	v_lshl_add_u64 v[10:11], v[6:7], 0, v[10:11]
	v_cvt_pk_bf16_f32 v5, v12, v13
	global_store_dwordx4 v[10:11], v[2:5], off
	ds_read_b128 v[2:5], v14 offset:12672
	ds_read_b128 v[10:13], v14 offset:12688
	s_waitcnt lgkmcnt(1)
	v_cvt_pk_bf16_f32 v2, v2, v3
	v_cvt_pk_bf16_f32 v3, v4, v5
	s_waitcnt lgkmcnt(0)
	v_cvt_pk_bf16_f32 v4, v10, v11
	v_or_b32_e32 v10, 24, v8
	v_ashrrev_i32_e32 v11, 31, v10
	v_lshlrev_b64 v[10:11], 12, v[10:11]
	v_lshl_add_u64 v[10:11], v[6:7], 0, v[10:11]
	v_cvt_pk_bf16_f32 v5, v12, v13
	global_store_dwordx4 v[10:11], v[2:5], off
	ds_read_b128 v[2:5], v14 offset:14784
	ds_read_b128 v[10:13], v14 offset:14800
	v_or_b32_e32 v8, 28, v8
	s_waitcnt lgkmcnt(1)
	v_cvt_pk_bf16_f32 v2, v2, v3
	v_cvt_pk_bf16_f32 v3, v4, v5
	s_waitcnt lgkmcnt(0)
	v_cvt_pk_bf16_f32 v4, v10, v11
	v_cvt_pk_bf16_f32 v5, v12, v13

; #define PG8_LAS __attribute__((address_space(3)))
;     __device__ __forceinline__ void fused(f32x4 (&acc)[2][2][4][2], const Unit& u, int wr, int wc, int fr, int fq, PG8_LAS unsigned char* lds, int wid, int lane) const {
;     ...
;         const int col0 = u.pn * BM + wc * 32 + 8 * fq;
;         f32x4 gv[2][2];
; #pragma unroll
;         for (int bj = 0; bj < 2; ++bj)
; #pragma unroll
;             for (int n = 0; n < 2; ++n) gv[bj][n] = *(const f32x4*)(g1 + col0 + bj * HALF + n * 4);
;         PG8_LAS u32x4* XL = (PG8_LAS u32x4*)lds + (wid * 64 + lane);
; #pragma unroll
;         for (int ai = 0; ai < 2; ++ai)
; #pragma unroll
;             for (int m = 0; m < 4; ++m) { const size_t off = (size_t)(u.pm * BM + ai * HALF + wr * 64 + m * 16 + fr) * ldc + col0;
; #pragma unroll
;                 for (int bj = 0; bj < 2; ++bj) XL[((ai * 4 + m) * 2 + bj) * 512] = *(const u32x4*)(base_b + off + bj * HALF); }
.LBB0_831:
	v_readlane_b32 s0, v251, 17
	v_readlane_b32 s1, v251, 18
	v_readlane_b32 s2, v251, 19
	v_readlane_b32 s4, v251, 21
	v_readlane_b32 s0, v255, 21
	v_readlane_b32 s3, v251, 20
	v_readlane_b32 s5, v251, 22
	v_readlane_b32 s1, v255, 22
	s_add_u32 s2, s4, s0
	v_readlane_b32 s10, v251, 27
	s_addc_u32 s3, s5, s1
	s_lshl_b32 s0, s26, 5
	s_lshl_b32 s1, s25, 8
	v_lshrrev_b32_e32 v0, 1, v154
	s_or_b32 s0, s1, s0
	s_lshl_b32 s10, s24, 8
	v_and_or_b32 v176, v0, 24, s0
	s_add_i32 s0, s10, s20
	v_or_b32_e32 v164, s0, v178
	v_or_b32_e32 v158, 16, v164
	v_readlane_b32 s0, v251, 63
	v_ashrrev_i32_e32 v159, 31, v158
	v_ashrrev_i32_e32 v177, 31, v176
	v_readlane_b32 s1, v252, 0
	v_lshlrev_b64 v[158:159], 12, v[158:159]
	v_lshlrev_b64 v[166:167], 1, v[176:177]
	v_lshl_add_u64 v[158:159], s[0:1], 0, v[158:159]
	v_lshl_add_u64 v[134:135], v[176:177], 2, s[2:3]
	v_lshl_add_u64 v[172:173], v[158:159], 0, v[166:167]
	s_barrier
	global_load_dwordx4 v[138:141], v[134:135], off offset:16
	global_load_dwordx4 v[142:145], v[134:135], off
	global_load_dwordx4 v[130:133], v[134:135], off offset:528
	s_nop 0
	global_load_dwordx4 v[134:137], v[134:135], off offset:512
	v_and_b32_e32 v156, 63, v154
	global_load_dwordx4 v[158:161], v[172:173], off
	v_lshl_add_u32 v207, v156, 4, s30
	v_add_u32_e32 v206, 0x10000, v207
	v_add_u32_e32 v205, 0x12000, v207
	v_add_u32_e32 v204, 0x14000, v207
	v_add_u32_e32 v203, 0x16000, v207
	v_add_u32_e32 v202, 0x18000, v207
	v_add_u32_e32 v201, 0x1a000, v207
	v_ashrrev_i32_e32 v165, 31, v164
	v_lshlrev_b64 v[146:147], 12, v[164:165]
	v_lshl_add_u64 v[146:147], s[0:1], 0, v[146:147]
	v_lshl_add_u64 v[146:147], v[146:147], 0, v[166:167]
	global_load_dwordx4 v[150:153], v[146:147], off
	v_add_u32_e32 v0, 0x1c000, v207
	v_add_u32_e32 v200, 0x1e000, v207
	v_cmp_gt_u32_e32 vcc, 16, v156
	v_readlane_b32 s6, v251, 23
	v_readlane_b32 s7, v251, 24
	v_readlane_b32 s8, v251, 25
	v_readlane_b32 s9, v251, 26
	v_readlane_b32 s11, v251, 28
	v_readlane_b32 s12, v251, 29
	v_readlane_b32 s13, v251, 30
	v_readlane_b32 s14, v251, 31
	v_readlane_b32 s15, v251, 32
	s_waitcnt vmcnt(0)
	v_pk_mul_f32 v[218:219], v[116:117], v[132:133]
	v_pk_mul_f32 v[220:221], v[114:115], v[130:131]
	ds_write_b128 v207, v[158:161] offset:16384
	global_load_dwordx4 v[224:227], v[172:173], off offset:256
	v_or_b32_e32 v158, 32, v164
	v_ashrrev_i32_e32 v159, 31, v158
	v_lshlrev_b64 v[158:159], 12, v[158:159]
	v_lshl_add_u64 v[158:159], s[0:1], 0, v[158:159]
	v_lshl_add_u64 v[172:173], v[158:159], 0, v[166:167]
	global_load_dwordx4 v[228:231], v[172:173], off
	global_load_dwordx4 v[232:235], v[172:173], off offset:256
	v_or_b32_e32 v158, 48, v164
	v_ashrrev_i32_e32 v159, 31, v158
	v_lshlrev_b64 v[158:159], 12, v[158:159]
	v_lshl_add_u64 v[158:159], s[0:1], 0, v[158:159]
	v_lshl_add_u64 v[172:173], v[158:159], 0, v[166:167]
	global_load_dwordx4 v[236:239], v[172:173], off
	global_load_dwordx4 v[240:243], v[172:173], off offset:256
	v_add_u32_e32 v158, 0x80, v164
	v_ashrrev_i32_e32 v159, 31, v158
	v_lshlrev_b64 v[158:159], 12, v[158:159]
	v_lshl_add_u64 v[158:159], s[0:1], 0, v[158:159]
	v_lshl_add_u64 v[172:173], v[158:159], 0, v[166:167]
	global_load_dwordx4 v[244:247], v[172:173], off
	global_load_dwordx4 v[158:161], v[172:173], off offset:256
	s_waitcnt vmcnt(6)
	ds_write_b128 v207, v[224:227] offset:24576
	s_waitcnt vmcnt(5)
	ds_write_b128 v207, v[228:231] offset:32768
	s_waitcnt vmcnt(4)
	ds_write_b128 v207, v[232:235] offset:40960
	s_waitcnt vmcnt(3)
	ds_write_b128 v207, v[236:239] offset:49152
	s_waitcnt vmcnt(2)
	ds_write_b128 v207, v[240:243] offset:57344
	s_waitcnt vmcnt(1)
	ds_write_b128 v206, v[244:247]
	s_waitcnt vmcnt(0)
	ds_write_b128 v205, v[158:161]
	v_add_u32_e32 v158, 0x90, v164
	v_ashrrev_i32_e32 v159, 31, v158
	v_lshlrev_b64 v[158:159], 12, v[158:159]
	v_lshl_add_u64 v[158:159], s[0:1], 0, v[158:159]
	v_lshl_add_u64 v[172:173], v[158:159], 0, v[166:167]
	global_load_dwordx4 v[224:227], v[172:173], off
	global_load_dwordx4 v[228:231], v[172:173], off offset:256
	v_add_u32_e32 v158, 0xa0, v164
	v_ashrrev_i32_e32 v159, 31, v158
	v_lshlrev_b64 v[158:159], 12, v[158:159]
	v_lshl_add_u64 v[158:159], s[0:1], 0, v[158:159]
	v_lshl_add_u64 v[172:173], v[158:159], 0, v[166:167]
	global_load_dwordx4 v[232:235], v[172:173], off
	global_load_dwordx4 v[236:239], v[172:173], off offset:256
	v_add_u32_e32 v158, 0xb0, v164
	v_ashrrev_i32_e32 v159, 31, v158
	v_lshlrev_b64 v[158:159], 12, v[158:159]
	v_lshl_add_u64 v[158:159], s[0:1], 0, v[158:159]
	v_lshl_add_u64 v[164:165], v[158:159], 0, v[166:167]
	global_load_dwordx4 v[158:161], v[164:165], off
	v_pk_mul_f32 v[166:167], v[126:127], v[126:127]
	global_load_dwordx4 v[146:149], v[146:147], off offset:256
	ds_write_b128 v207, v[150:153]
	s_lshl_b32 s0, s26, 4
	s_add_i32 s4, s0, 0
	s_add_i32 s4, s4, 0x20000
	s_waitcnt vmcnt(1)
	ds_write_b128 v204, v[224:227]
	ds_write_b128 v203, v[228:231]
	ds_write_b128 v202, v[232:235]
	ds_write_b128 v201, v[236:239]
	ds_write_b128 v0, v[158:161]
	global_load_dwordx4 v[158:161], v[164:165], off offset:256
	v_pk_mul_f32 v[164:165], v[128:129], v[128:129]
	s_waitcnt vmcnt(1)
;     __device__ __forceinline__ void fused(f32x4 (&acc)[2][2][4][2], const Unit& u, int wr, int wc, int fr, int fq, PG8_LAS unsigned char* lds, int wid, int lane) const {
;     ...
;         for (int ai = 0; ai < 2; ++ai)
; #pragma unroll
;             for (int m = 0; m < 4; ++m) {
;                 float saa = 0.f, sxx = 0.f, sxag = 0.f, sgg = 0.f;
; #pragma unroll
;                 for (int bj = 0; bj < 2; ++bj) { const u32x4 w4 = XL[((ai * 4 + m) * 2 + bj) * 512];
; #pragma unroll
;                     for (int n = 0; n < 2; ++n) { const f32x4 a = acc[ai][bj][m][n]; const f32x4 ag = a * gv[bj][n]; const unsigned wx = n == 0 ? w4.x : w4.z, wy = n == 0 ? w4.y : w4.w;
;                         const f32x4 x = (f32x4){bflo(wx), bfhi(wx), bflo(wy), bfhi(wy)};
;                         saa += (a[0] * a[0] + a[1] * a[1]) + (a[2] * a[2] + a[3] * a[3]); sxx += (x[0] * x[0] + x[1] * x[1]) + (x[2] * x[2] + x[3] * x[3]);
;                         sxag += (x[0] * ag[0] + x[1] * ag[1]) + (x[2] * ag[2] + x[3] * ag[3]); sgg += (ag[0] * ag[0] + ag[1] * ag[1]) + (ag[2] * ag[2] + ag[3] * ag[3]); } }
;                 asm volatile("" : "+v"(saa), "+v"(sxx), "+v"(sxag), "+v"(sgg));
;                 saa += __shfl_xor(saa, 16); sxx += __shfl_xor(sxx, 16); sxag += __shfl_xor(sxag, 16); sgg += __shfl_xor(sgg, 16);
;                 saa += __shfl_xor(saa, 32); sxx += __shfl_xor(sxx, 32); sxag += __shfl_xor(sxag, 32); sgg += __shfl_xor(sgg, 32);
;                 if (fq == 0) P[(ai * HALF + wr * 64 + m * 16 + fr) * 4 + wc] = (f32x4){saa, sxx, sxag, sgg};
	v_lshlrev_b32_e32 v212, 16, v146
	v_pk_mov_b32 v[172:173], v[166:167], v[164:165] op_sel:[1,0]
	v_mov_b32_e32 v167, v165
	v_pk_add_f32 v[164:165], v[172:173], v[166:167]
	v_lshlrev_b32_e32 v166, 16, v150
	v_and_b32_e32 v173, 0xffff0000, v150
	v_and_b32_e32 v172, 16, v150
	v_mov_b32_e32 v167, v173
	v_mul_f32_e32 v150, v166, v166
	v_pk_fma_f32 v[174:175], v[166:167], v[166:167], v[150:151] op_sel_hi:[1,1,0]
	v_lshlrev_b32_e32 v150, 16, v151
	v_and_b32_e32 v151, 0xffff0000, v151
	v_mul_f32_e32 v162, v150, v150
	v_mov_b32_e32 v167, v151
	v_pk_fma_f32 v[180:181], v[150:151], v[150:151], v[162:163] op_sel_hi:[1,1,0]
	v_pk_mov_b32 v[172:173], v[172:173], v[150:151] op_sel:[1,0]
	ds_write_b128 v207, v[146:149] offset:8192
	v_and_b32_e32 v213, 0xffff0000, v146
	v_mul_f32_e32 v146, v212, v212
	v_pk_fma_f32 v[214:215], v[212:213], v[212:213], v[146:147] op_sel_hi:[1,1,0]
	v_lshlrev_b32_e32 v146, 16, v147
	v_and_b32_e32 v147, 0xffff0000, v147
	v_pk_add_f32 v[164:165], v[164:165], v[164:165] op_sel_hi:[0,1]
	v_lshlrev_b32_e32 v222, 16, v148
	v_lshlrev_b32_e32 v157, 16, v149
	v_and_b32_e32 v162, 0xffff0000, v149
	v_mul_f32_e32 v164, v117, v117
	v_mov_b32_e32 v223, v175
	v_mul_f32_e32 v214, v157, v157
	s_waitcnt vmcnt(0)
	ds_write_b128 v200, v[158:161]
	v_pk_mul_f32 v[158:159], v[128:129], v[144:145]
	v_pk_mul_f32 v[160:161], v[126:127], v[142:143]
	v_mov_b32_e32 v185, v159
	v_mov_b32_e32 v184, v160
	v_pk_mov_b32 v[182:183], v[160:161], v[158:159] op_sel:[1,0]
	v_pk_mul_f32 v[150:151], v[184:185], v[166:167]
	v_pk_mul_f32 v[158:159], v[158:159], v[158:159]
	v_pk_mul_f32 v[160:161], v[160:161], v[160:161]
	v_pk_fma_f32 v[150:151], v[182:183], v[172:173], v[150:151]
	v_pk_mov_b32 v[166:167], v[160:161], v[158:159] op_sel:[1,0]
	v_mov_b32_e32 v161, v159
	v_pk_mul_f32 v[172:173], v[124:125], v[124:125]
	v_pk_mul_f32 v[182:183], v[122:123], v[122:123]
	v_pk_add_f32 v[158:159], v[166:167], v[160:161]
	v_pk_mul_f32 v[160:161], v[124:125], v[140:141]
	v_pk_mul_f32 v[166:167], v[122:123], v[138:139]
	v_pk_mov_b32 v[184:185], v[182:183], v[172:173] op_sel:[1,0]
	v_mov_b32_e32 v183, v173
	v_add_f32_e32 v150, v150, v151
	v_pk_add_f32 v[172:173], v[184:185], v[182:183]
	v_lshlrev_b32_e32 v183, 16, v153
	v_lshlrev_b32_e32 v182, 16, v152
	v_and_b32_e32 v153, 0xffff0000, v153
	v_and_b32_e32 v152, 0xffff0000, v152
	v_mov_b32_e32 v210, v167
	v_mov_b32_e32 v211, v161
	v_add_f32_e32 v151, 0, v150
	v_pk_mul_f32 v[184:185], v[152:153], v[152:153]
	v_mov_b32_e32 v208, v166
	v_mov_b32_e32 v209, v160
	v_pk_mul_f32 v[152:153], v[210:211], v[152:153]
	v_pk_mul_f32 v[160:161], v[160:161], v[160:161]
	v_pk_mul_f32 v[166:167], v[166:167], v[166:167]
	v_mul_f32_e32 v150, v118, v118
	v_pk_fma_f32 v[184:185], v[182:183], v[182:183], v[184:185]
	v_pk_fma_f32 v[152:153], v[208:209], v[182:183], v[152:153]
	v_pk_mov_b32 v[182:183], v[166:167], v[160:161] op_sel:[1,0]
	v_mov_b32_e32 v167, v161
	v_pk_fma_f32 v[208:209], v[118:119], v[118:119], v[150:151] op_sel_hi:[1,1,0]
	v_mul_f32_e32 v150, v120, v120
	v_pk_add_f32 v[160:161], v[182:183], v[166:167]
	v_pk_mul_f32 v[182:183], v[118:119], v[134:135]
	v_pk_fma_f32 v[210:211], v[120:121], v[120:121], v[150:151] op_sel_hi:[1,1,0]
	v_mul_f32_e32 v150, v146, v146
	v_pk_mul_f32 v[166:167], v[120:121], v[136:137]
	v_pk_fma_f32 v[216:217], v[146:147], v[146:147], v[150:151] op_sel_hi:[1,1,0]
	v_mul_f32_e32 v150, v182, v212
	v_pk_fma_f32 v[212:213], v[182:183], v[212:213], v[150:151] op_sel_hi:[1,1,0]
	v_mul_f32_e32 v150, v166, v146
	v_pk_add_f32 v[172:173], v[172:173], v[172:173] op_sel_hi:[0,1]
	v_pk_fma_f32 v[146:147], v[166:167], v[146:147], v[150:151] op_sel_hi:[1,1,0]
	v_pk_add_f32 v[184:185], v[184:185], v[184:185] op_sel_hi:[0,1]
	v_pk_add_f32 v[152:153], v[152:153], v[152:153] op_sel_hi:[0,1]
	v_and_b32_e32 v146, 0xffff0000, v148
	v_mul_f32_e32 v208, v114, v114
	v_mul_f32_e32 v210, v115, v115
	v_mul_f32_e32 v172, v116, v116
	v_pk_add_f32 v[148:149], v[208:209], v[210:211]
	v_pk_add_f32 v[164:165], v[172:173], v[164:165]
	v_mul_f32_e32 v184, v146, v146
	v_mul_f32_e32 v152, v220, v222
	v_mul_f32_e32 v150, v221, v146
	v_mul_f32_e32 v212, v218, v157
	v_mul_f32_e32 v146, v219, v162
	v_pk_add_f32 v[148:149], v[148:149], v[164:165]
	v_mov_b32_e32 v164, v222
	v_mov_b32_e32 v165, v181
	v_pk_add_f32 v[150:151], v[152:153], v[150:151]
	v_pk_add_f32 v[146:147], v[212:213], v[146:147]
	v_pk_mul_f32 v[164:165], v[222:223], v[164:165]
	v_pk_add_f32 v[172:173], v[174:175], v[180:181]
	v_pk_add_f32 v[146:147], v[150:151], v[146:147]
	v_mul_f32_e32 v216, v162, v162
	v_mov_b32_e32 v165, v173
	v_add_f32_e32 v150, v146, v147
	v_mul_f32_e32 v151, v220, v220
	v_mul_f32_e32 v157, v221, v221
	v_pk_add_f32 v[146:147], v[158:159], v[158:159] op_sel:[0,1] op_sel_hi:[1,0]
	v_pk_add_f32 v[152:153], v[160:161], v[160:161] op_sel:[0,1] op_sel_hi:[1,0]
	v_pk_add_f32 v[164:165], v[164:165], v[184:185]
	v_pk_add_f32 v[172:173], v[214:215], v[216:217]
	v_mov_b32_e32 v147, v151
	v_mov_b32_e32 v153, v157
	v_pk_add_f32 v[164:165], v[164:165], v[172:173]
	v_pk_add_f32 v[146:147], v[146:147], v[152:153]
	v_mul_f32_e32 v152, v183, v183
	v_mul_f32_e32 v158, v167, v167
	v_add_f32_e32 v148, v148, v149
	v_add_f32_e32 v149, v164, v165
	v_mul_f32_e32 v162, v218, v218
	v_mul_f32_e32 v164, v219, v219
	v_pk_fma_f32 v[152:153], v[182:183], v[182:183], v[152:153] op_sel_hi:[1,1,0]
	v_pk_fma_f32 v[158:159], v[166:167], v[166:167], v[158:159] op_sel_hi:[1,1,0]
	v_mov_b32_e32 v153, v162
	v_mov_b32_e32 v159, v164
	v_pk_add_f32 v[152:153], v[152:153], v[158:159]
	s_nop 0
	v_pk_add_f32 v[146:147], v[146:147], v[152:153]
	s_nop 0
	v_add_f32_e32 v151, v146, v147
	v_mov_b32_e32 v146, v148
	s_nop 1
	v_permlane16_swap_b32_e32 v148, v146
	v_mov_b32_e32 v147, v149
	s_nop 1
	v_permlane16_swap_b32_e32 v149, v147
	s_waitcnt lgkmcnt(0)
	v_pk_add_f32 v[146:147], v[148:149], v[146:147]
	v_mov_b32_e32 v148, v150
	s_nop 1
	v_permlane16_swap_b32_e32 v150, v148
	v_mov_b32_e32 v149, v151
	s_nop 1
	v_permlane16_swap_b32_e32 v151, v149
	s_waitcnt lgkmcnt(0)
	v_pk_add_f32 v[150:151], v[150:151], v[148:149]
	v_mov_b32_e32 v148, v146
	s_nop 1
	v_permlane32_swap_b32_e32 v146, v148
	v_mov_b32_e32 v149, v147
	s_nop 1
	v_permlane32_swap_b32_e32 v147, v149
	v_mov_b32_e32 v152, v150
	s_nop 1
	v_permlane32_swap_b32_e32 v150, v152
	v_mov_b32_e32 v153, v151
	s_nop 1
	v_permlane32_swap_b32_e32 v151, v153
	s_and_saveexec_b64 s[0:1], vcc
	s_cbranch_execz .LBB0_833
	s_lshl_b32 s5, s23, 12
	s_add_i32 s5, s4, s5
	s_waitcnt lgkmcnt(0)
	v_pk_add_f32 v[150:151], v[150:151], v[152:153]
	v_pk_add_f32 v[148:149], v[146:147], v[148:149]
	v_add_u32_e32 v146, s5, v155
	ds_write_b128 v146, v[148:151]
;     __device__ __forceinline__ void fused(f32x4 (&acc)[2][2][4][2], const Unit& u, int wr, int wc, int fr, int fq, PG8_LAS unsigned char* lds, int wid, int lane) const {
;     ...
;         for (int ai = 0; ai < 2; ++ai)
; #pragma unroll
;             for (int m = 0; m < 4; ++m) {
;                 float saa = 0.f, sxx = 0.f, sxag = 0.f, sgg = 0.f;
; #pragma unroll
;                 for (int bj = 0; bj < 2; ++bj) { const u32x4 w4 = XL[((ai * 4 + m) * 2 + bj) * 512];
; #pragma unroll
;                     for (int n = 0; n < 2; ++n) { const f32x4 a = acc[ai][bj][m][n]; const f32x4 ag = a * gv[bj][n]; const unsigned wx = n == 0 ? w4.x : w4.z, wy = n == 0 ? w4.y : w4.w;
;                         const f32x4 x = (f32x4){bflo(wx), bfhi(wx), bflo(wy), bfhi(wy)};
;                         saa += (a[0] * a[0] + a[1] * a[1]) + (a[2] * a[2] + a[3] * a[3]); sxx += (x[0] * x[0] + x[1] * x[1]) + (x[2] * x[2] + x[3] * x[3]);
;                         sxag += (x[0] * ag[0] + x[1] * ag[1]) + (x[2] * ag[2] + x[3] * ag[3]); sgg += (ag[0] * ag[0] + ag[1] * ag[1]) + (ag[2] * ag[2] + ag[3] * ag[3]); } }
;                 asm volatile("" : "+v"(saa), "+v"(sxx), "+v"(sxag), "+v"(sgg));
;                 saa += __shfl_xor(saa, 16); sxx += __shfl_xor(sxx, 16); sxag += __shfl_xor(sxag, 16); sgg += __shfl_xor(sgg, 16);
;                 saa += __shfl_xor(saa, 32); sxx += __shfl_xor(sxx, 32); sxag += __shfl_xor(sxag, 32); sgg += __shfl_xor(sgg, 32);
;                 if (fq == 0) P[(ai * HALF + wr * 64 + m * 16 + fr) * 4 + wc] = (f32x4){saa, sxx, sxag, sgg};
.LBB0_833:
	s_or_b64 exec, exec, s[0:1]
	s_waitcnt lgkmcnt(0)
	ds_read_b128 v[146:149], v207 offset:16384
	v_pk_mul_f32 v[150:151], v[112:113], v[112:113]
	s_waitcnt lgkmcnt(0)
	v_pk_mul_f32 v[152:153], v[110:111], v[110:111]
	v_pk_mul_f32 v[158:159], v[112:113], v[144:145]
	v_pk_mov_b32 v[164:165], v[152:153], v[150:151] op_sel:[1,0]
	v_mov_b32_e32 v153, v151
	v_pk_add_f32 v[150:151], v[164:165], v[152:153]
	v_pk_mul_f32 v[160:161], v[110:111], v[142:143]
	v_pk_add_f32 v[164:165], v[150:151], v[150:151] op_sel_hi:[0,1]
	ds_read_b128 v[150:153], v207 offset:24576
	s_waitcnt lgkmcnt(0)
	v_lshlrev_b32_e32 v166, 16, v146
	v_and_b32_e32 v173, 0xffff0000, v146
	v_and_b32_e32 v172, 16, v146
	v_mov_b32_e32 v167, v173
	v_mul_f32_e32 v146, v166, v166
	v_pk_fma_f32 v[174:175], v[166:167], v[166:167], v[146:147] op_sel_hi:[1,1,0]
	v_lshlrev_b32_e32 v146, 16, v147
	v_and_b32_e32 v147, 0xffff0000, v147
	v_mul_f32_e32 v162, v146, v146
	v_mov_b32_e32 v184, v160
	v_mov_b32_e32 v185, v159
	v_mov_b32_e32 v167, v147
	v_pk_fma_f32 v[180:181], v[146:147], v[146:147], v[162:163] op_sel_hi:[1,1,0]
	v_pk_mov_b32 v[182:183], v[160:161], v[158:159] op_sel:[1,0]
	v_pk_mov_b32 v[172:173], v[172:173], v[146:147] op_sel:[1,0]
	v_pk_mul_f32 v[146:147], v[184:185], v[166:167]
	v_pk_mul_f32 v[158:159], v[158:159], v[158:159]
	v_pk_mul_f32 v[160:161], v[160:161], v[160:161]
	v_pk_fma_f32 v[146:147], v[182:183], v[172:173], v[146:147]
	v_pk_mov_b32 v[166:167], v[160:161], v[158:159] op_sel:[1,0]
	v_mov_b32_e32 v161, v159
	v_pk_mul_f32 v[172:173], v[108:109], v[108:109]
	v_pk_mul_f32 v[182:183], v[106:107], v[106:107]
	v_pk_add_f32 v[158:159], v[166:167], v[160:161]
	v_pk_mul_f32 v[160:161], v[108:109], v[140:141]
	v_pk_mul_f32 v[166:167], v[106:107], v[138:139]
	v_pk_mov_b32 v[184:185], v[182:183], v[172:173] op_sel:[1,0]
	v_mov_b32_e32 v183, v173
	v_add_f32_e32 v146, v146, v147
	v_pk_add_f32 v[172:173], v[184:185], v[182:183]
	v_lshlrev_b32_e32 v183, 16, v149
	v_lshlrev_b32_e32 v182, 16, v148
	v_and_b32_e32 v149, 0xffff0000, v149
	v_and_b32_e32 v148, 0xffff0000, v148
	v_mov_b32_e32 v210, v167
	v_mov_b32_e32 v211, v161
	v_add_f32_e32 v147, 0, v146
	v_pk_mul_f32 v[184:185], v[148:149], v[148:149]
	v_mov_b32_e32 v208, v166
	v_mov_b32_e32 v209, v160
	v_pk_mul_f32 v[148:149], v[210:211], v[148:149]
	v_mul_f32_e32 v146, v102, v102
	v_pk_fma_f32 v[148:149], v[208:209], v[182:183], v[148:149]
	v_pk_mul_f32 v[160:161], v[160:161], v[160:161]
	v_pk_mul_f32 v[166:167], v[166:167], v[166:167]
	v_pk_fma_f32 v[208:209], v[102:103], v[102:103], v[146:147] op_sel_hi:[1,1,0]
	v_mul_f32_e32 v146, v104, v104
	s_waitcnt lgkmcnt(0)
	v_lshlrev_b32_e32 v212, 16, v150
	v_pk_fma_f32 v[184:185], v[182:183], v[182:183], v[184:185]
	v_pk_mov_b32 v[182:183], v[166:167], v[160:161] op_sel:[1,0]
	v_mov_b32_e32 v167, v161
	v_pk_fma_f32 v[210:211], v[104:105], v[104:105], v[146:147] op_sel_hi:[1,1,0]
	v_and_b32_e32 v213, 0xffff0000, v150
	v_mul_f32_e32 v146, v212, v212
	v_lshlrev_b32_e32 v150, 16, v151
	v_pk_add_f32 v[160:161], v[182:183], v[166:167]
	v_pk_mul_f32 v[182:183], v[102:103], v[134:135]
	v_pk_fma_f32 v[214:215], v[212:213], v[212:213], v[146:147] op_sel_hi:[1,1,0]
	v_and_b32_e32 v151, 0xffff0000, v151
	v_mul_f32_e32 v146, v150, v150
	v_pk_mul_f32 v[166:167], v[104:105], v[136:137]
	v_pk_fma_f32 v[216:217], v[150:151], v[150:151], v[146:147] op_sel_hi:[1,1,0]
	v_mul_f32_e32 v146, v182, v212
	v_pk_add_f32 v[172:173], v[172:173], v[172:173] op_sel_hi:[0,1]
	v_pk_add_f32 v[148:149], v[148:149], v[148:149] op_sel_hi:[0,1]
	v_pk_fma_f32 v[212:213], v[182:183], v[212:213], v[146:147] op_sel_hi:[1,1,0]
	v_mul_f32_e32 v146, v166, v150
	v_pk_add_f32 v[184:185], v[184:185], v[184:185] op_sel_hi:[0,1]
	v_pk_fma_f32 v[150:151], v[166:167], v[150:151], v[146:147] op_sel_hi:[1,1,0]
	v_pk_mul_f32 v[218:219], v[100:101], v[132:133]
	v_pk_mul_f32 v[220:221], v[98:99], v[130:131]
	v_lshlrev_b32_e32 v222, 16, v152
	v_and_b32_e32 v146, 0xffff0000, v152
	v_lshlrev_b32_e32 v148, 16, v153
	v_and_b32_e32 v157, 0xffff0000, v153
	v_mul_f32_e32 v208, v98, v98
	v_mul_f32_e32 v210, v99, v99
	v_mul_f32_e32 v172, v100, v100
	v_mul_f32_e32 v164, v101, v101
	v_pk_add_f32 v[152:153], v[208:209], v[210:211]
	v_pk_add_f32 v[164:165], v[172:173], v[164:165]
	v_mul_f32_e32 v184, v146, v146
	v_mul_f32_e32 v214, v148, v148
	v_mul_f32_e32 v212, v220, v222
	v_mul_f32_e32 v150, v221, v146
	v_mul_f32_e32 v148, v218, v148
	v_mul_f32_e32 v146, v219, v157
	v_pk_add_f32 v[152:153], v[152:153], v[164:165]
	v_mov_b32_e32 v223, v175
	v_mov_b32_e32 v164, v222
	v_mov_b32_e32 v165, v181
	v_pk_add_f32 v[150:151], v[212:213], v[150:151]
	v_pk_add_f32 v[146:147], v[148:149], v[146:147]
	v_pk_mul_f32 v[164:165], v[222:223], v[164:165]
	v_pk_add_f32 v[172:173], v[174:175], v[180:181]
	v_pk_add_f32 v[146:147], v[150:151], v[146:147]
	v_mul_f32_e32 v216, v157, v157
	v_mov_b32_e32 v165, v173
	v_add_f32_e32 v148, v146, v147
	v_mul_f32_e32 v149, v220, v220
	v_mul_f32_e32 v157, v221, v221
	v_pk_add_f32 v[146:147], v[158:159], v[158:159] op_sel:[0,1] op_sel_hi:[1,0]
	v_pk_add_f32 v[150:151], v[160:161], v[160:161] op_sel:[0,1] op_sel_hi:[1,0]
	v_pk_add_f32 v[164:165], v[164:165], v[184:185]
	v_pk_add_f32 v[172:173], v[214:215], v[216:217]
	v_mov_b32_e32 v147, v149
	v_mov_b32_e32 v151, v157
	v_pk_add_f32 v[164:165], v[164:165], v[172:173]
	v_pk_add_f32 v[146:147], v[146:147], v[150:151]
	v_mul_f32_e32 v150, v183, v183
	v_mul_f32_e32 v158, v167, v167
	v_add_f32_e32 v152, v152, v153
	v_add_f32_e32 v153, v164, v165
	v_mul_f32_e32 v162, v218, v218
	v_mul_f32_e32 v164, v219, v219
	v_pk_fma_f32 v[150:151], v[182:183], v[182:183], v[150:151] op_sel_hi:[1,1,0]
	v_pk_fma_f32 v[158:159], v[166:167], v[166:167], v[158:159] op_sel_hi:[1,1,0]
	v_mov_b32_e32 v151, v162
	v_mov_b32_e32 v159, v164
	v_pk_add_f32 v[150:151], v[150:151], v[158:159]
	s_nop 0
	v_pk_add_f32 v[146:147], v[146:147], v[150:151]
	s_nop 0
	v_add_f32_e32 v149, v146, v147
	v_mov_b32_e32 v146, v152
	s_nop 1
	v_permlane16_swap_b32_e32 v152, v146
	v_mov_b32_e32 v147, v153
	s_nop 1
	v_permlane16_swap_b32_e32 v153, v147
	v_mov_b32_e32 v150, v148
	s_nop 1
	v_permlane16_swap_b32_e32 v148, v150
	v_mov_b32_e32 v151, v149
	s_nop 1
	v_permlane16_swap_b32_e32 v149, v151
	s_waitcnt lgkmcnt(0)
	v_pk_add_f32 v[146:147], v[152:153], v[146:147]
	s_waitcnt lgkmcnt(0)
	v_pk_add_f32 v[150:151], v[148:149], v[150:151]
	v_mov_b32_e32 v148, v146
	s_nop 1
	v_permlane32_swap_b32_e32 v146, v148
	v_mov_b32_e32 v149, v147
	s_nop 1
	v_permlane32_swap_b32_e32 v147, v149
	v_mov_b32_e32 v152, v150
	s_nop 1
	v_permlane32_swap_b32_e32 v150, v152
	v_mov_b32_e32 v153, v151
	s_nop 1
	v_permlane32_swap_b32_e32 v151, v153
	s_and_saveexec_b64 s[0:1], vcc
	s_cbranch_execz .LBB0_835
	s_lshl_b32 s5, s23, 12
	s_add_i32 s5, s4, s5
	s_waitcnt lgkmcnt(0)
	v_pk_add_f32 v[150:151], v[150:151], v[152:153]
	v_pk_add_f32 v[148:149], v[146:147], v[148:149]
	v_add_u32_e32 v146, s5, v155
	ds_write_b128 v146, v[148:151] offset:1024
;     __device__ __forceinline__ void fused(f32x4 (&acc)[2][2][4][2], const Unit& u, int wr, int wc, int fr, int fq, PG8_LAS unsigned char* lds, int wid, int lane) const {
;     ...
;         for (int ai = 0; ai < 2; ++ai)
; #pragma unroll
;             for (int m = 0; m < 4; ++m) {
;                 float saa = 0.f, sxx = 0.f, sxag = 0.f, sgg = 0.f;
; #pragma unroll
;                 for (int bj = 0; bj < 2; ++bj) { const u32x4 w4 = XL[((ai * 4 + m) * 2 + bj) * 512];
; #pragma unroll
;                     for (int n = 0; n < 2; ++n) { const f32x4 a = acc[ai][bj][m][n]; const f32x4 ag = a * gv[bj][n]; const unsigned wx = n == 0 ? w4.x : w4.z, wy = n == 0 ? w4.y : w4.w;
;                         const f32x4 x = (f32x4){bflo(wx), bfhi(wx), bflo(wy), bfhi(wy)};
;                         saa += (a[0] * a[0] + a[1] * a[1]) + (a[2] * a[2] + a[3] * a[3]); sxx += (x[0] * x[0] + x[1] * x[1]) + (x[2] * x[2] + x[3] * x[3]);
;                         sxag += (x[0] * ag[0] + x[1] * ag[1]) + (x[2] * ag[2] + x[3] * ag[3]); sgg += (ag[0] * ag[0] + ag[1] * ag[1]) + (ag[2] * ag[2] + ag[3] * ag[3]); } }
;                 asm volatile("" : "+v"(saa), "+v"(sxx), "+v"(sxag), "+v"(sgg));
;                 saa += __shfl_xor(saa, 16); sxx += __shfl_xor(sxx, 16); sxag += __shfl_xor(sxag, 16); sgg += __shfl_xor(sgg, 16);
;                 saa += __shfl_xor(saa, 32); sxx += __shfl_xor(sxx, 32); sxag += __shfl_xor(sxag, 32); sgg += __shfl_xor(sgg, 32);
;                 if (fq == 0) P[(ai * HALF + wr * 64 + m * 16 + fr) * 4 + wc] = (f32x4){saa, sxx, sxag, sgg};
.LBB0_835:
	s_or_b64 exec, exec, s[0:1]
	s_waitcnt lgkmcnt(0)
	ds_read_b128 v[146:149], v207 offset:32768
	v_pk_mul_f32 v[150:151], v[96:97], v[96:97]
	s_waitcnt lgkmcnt(0)
	v_pk_mul_f32 v[152:153], v[94:95], v[94:95]
	v_pk_mul_f32 v[158:159], v[96:97], v[144:145]
	v_pk_mov_b32 v[164:165], v[152:153], v[150:151] op_sel:[1,0]
	v_mov_b32_e32 v153, v151
	v_pk_add_f32 v[150:151], v[164:165], v[152:153]
	v_pk_mul_f32 v[160:161], v[94:95], v[142:143]
	v_pk_add_f32 v[164:165], v[150:151], v[150:151] op_sel_hi:[0,1]
	ds_read_b128 v[150:153], v207 offset:40960
	s_waitcnt lgkmcnt(0)
	v_lshlrev_b32_e32 v166, 16, v146
	v_and_b32_e32 v173, 0xffff0000, v146
	v_and_b32_e32 v172, 16, v146
	v_mov_b32_e32 v167, v173
	v_mul_f32_e32 v146, v166, v166
	v_pk_fma_f32 v[174:175], v[166:167], v[166:167], v[146:147] op_sel_hi:[1,1,0]
	v_lshlrev_b32_e32 v146, 16, v147
	v_and_b32_e32 v147, 0xffff0000, v147
	v_mul_f32_e32 v162, v146, v146
	v_mov_b32_e32 v184, v160
	v_mov_b32_e32 v185, v159
	v_mov_b32_e32 v167, v147
	v_pk_fma_f32 v[180:181], v[146:147], v[146:147], v[162:163] op_sel_hi:[1,1,0]
	v_pk_mov_b32 v[182:183], v[160:161], v[158:159] op_sel:[1,0]
	v_pk_mov_b32 v[172:173], v[172:173], v[146:147] op_sel:[1,0]
	v_pk_mul_f32 v[146:147], v[184:185], v[166:167]
	v_pk_mul_f32 v[158:159], v[158:159], v[158:159]
	v_pk_mul_f32 v[160:161], v[160:161], v[160:161]
	v_pk_fma_f32 v[146:147], v[182:183], v[172:173], v[146:147]
	v_pk_mov_b32 v[166:167], v[160:161], v[158:159] op_sel:[1,0]
	v_mov_b32_e32 v161, v159
	v_pk_mul_f32 v[172:173], v[92:93], v[92:93]
	v_pk_mul_f32 v[182:183], v[90:91], v[90:91]
	v_pk_add_f32 v[158:159], v[166:167], v[160:161]
	v_pk_mul_f32 v[160:161], v[92:93], v[140:141]
	v_pk_mul_f32 v[166:167], v[90:91], v[138:139]
	v_pk_mov_b32 v[184:185], v[182:183], v[172:173] op_sel:[1,0]
	v_mov_b32_e32 v183, v173
	v_add_f32_e32 v146, v146, v147
	v_pk_add_f32 v[172:173], v[184:185], v[182:183]
	v_lshlrev_b32_e32 v183, 16, v149
	v_lshlrev_b32_e32 v182, 16, v148
	v_and_b32_e32 v149, 0xffff0000, v149
	v_and_b32_e32 v148, 0xffff0000, v148
	v_mov_b32_e32 v210, v167
	v_mov_b32_e32 v211, v161
	v_add_f32_e32 v147, 0, v146
	v_pk_mul_f32 v[184:185], v[148:149], v[148:149]
	v_mov_b32_e32 v208, v166
	v_mov_b32_e32 v209, v160
	v_pk_mul_f32 v[148:149], v[210:211], v[148:149]
	v_mul_f32_e32 v146, v86, v86
	v_pk_fma_f32 v[148:149], v[208:209], v[182:183], v[148:149]
	v_pk_mul_f32 v[160:161], v[160:161], v[160:161]
	v_pk_mul_f32 v[166:167], v[166:167], v[166:167]
	v_pk_fma_f32 v[208:209], v[86:87], v[86:87], v[146:147] op_sel_hi:[1,1,0]
	v_mul_f32_e32 v146, v88, v88
	s_waitcnt lgkmcnt(0)
	v_lshlrev_b32_e32 v212, 16, v150
	v_pk_fma_f32 v[184:185], v[182:183], v[182:183], v[184:185]
	v_pk_mov_b32 v[182:183], v[166:167], v[160:161] op_sel:[1,0]
	v_mov_b32_e32 v167, v161
	v_pk_fma_f32 v[210:211], v[88:89], v[88:89], v[146:147] op_sel_hi:[1,1,0]
	v_and_b32_e32 v213, 0xffff0000, v150
	v_mul_f32_e32 v146, v212, v212
	v_lshlrev_b32_e32 v150, 16, v151
	v_pk_add_f32 v[160:161], v[182:183], v[166:167]
	v_pk_mul_f32 v[182:183], v[86:87], v[134:135]
	v_pk_fma_f32 v[214:215], v[212:213], v[212:213], v[146:147] op_sel_hi:[1,1,0]
	v_and_b32_e32 v151, 0xffff0000, v151
	v_mul_f32_e32 v146, v150, v150
	v_pk_mul_f32 v[166:167], v[88:89], v[136:137]
	v_pk_fma_f32 v[216:217], v[150:151], v[150:151], v[146:147] op_sel_hi:[1,1,0]
	v_mul_f32_e32 v146, v182, v212
	v_pk_add_f32 v[172:173], v[172:173], v[172:173] op_sel_hi:[0,1]
	v_pk_add_f32 v[148:149], v[148:149], v[148:149] op_sel_hi:[0,1]
	v_pk_fma_f32 v[212:213], v[182:183], v[212:213], v[146:147] op_sel_hi:[1,1,0]
	v_mul_f32_e32 v146, v166, v150
	v_pk_add_f32 v[184:185], v[184:185], v[184:185] op_sel_hi:[0,1]
	v_pk_fma_f32 v[150:151], v[166:167], v[150:151], v[146:147] op_sel_hi:[1,1,0]
	v_pk_mul_f32 v[218:219], v[84:85], v[132:133]
	v_pk_mul_f32 v[220:221], v[82:83], v[130:131]
	v_lshlrev_b32_e32 v222, 16, v152
	v_and_b32_e32 v146, 0xffff0000, v152
	v_lshlrev_b32_e32 v148, 16, v153
	v_and_b32_e32 v157, 0xffff0000, v153
	v_mul_f32_e32 v208, v82, v82
	v_mul_f32_e32 v210, v83, v83
	v_mul_f32_e32 v172, v84, v84
	v_mul_f32_e32 v164, v85, v85
	v_pk_add_f32 v[152:153], v[208:209], v[210:211]
	v_pk_add_f32 v[164:165], v[172:173], v[164:165]
	v_mul_f32_e32 v184, v146, v146
	v_mul_f32_e32 v214, v148, v148
	v_mul_f32_e32 v212, v220, v222
	v_mul_f32_e32 v150, v221, v146
	v_mul_f32_e32 v148, v218, v148
	v_mul_f32_e32 v146, v219, v157
	v_pk_add_f32 v[152:153], v[152:153], v[164:165]
	v_mov_b32_e32 v223, v175
	v_mov_b32_e32 v164, v222
	v_mov_b32_e32 v165, v181
	v_pk_add_f32 v[150:151], v[212:213], v[150:151]
	v_pk_add_f32 v[146:147], v[148:149], v[146:147]
	v_pk_mul_f32 v[164:165], v[222:223], v[164:165]
	v_pk_add_f32 v[172:173], v[174:175], v[180:181]
	v_pk_add_f32 v[146:147], v[150:151], v[146:147]
	v_mul_f32_e32 v216, v157, v157
	v_mov_b32_e32 v165, v173
	v_add_f32_e32 v148, v146, v147
	v_mul_f32_e32 v149, v220, v220
	v_mul_f32_e32 v157, v221, v221
	v_pk_add_f32 v[146:147], v[158:159], v[158:159] op_sel:[0,1] op_sel_hi:[1,0]
	v_pk_add_f32 v[150:151], v[160:161], v[160:161] op_sel:[0,1] op_sel_hi:[1,0]
	v_pk_add_f32 v[164:165], v[164:165], v[184:185]
	v_pk_add_f32 v[172:173], v[214:215], v[216:217]
	v_mov_b32_e32 v147, v149
	v_mov_b32_e32 v151, v157
	v_pk_add_f32 v[164:165], v[164:165], v[172:173]
	v_pk_add_f32 v[146:147], v[146:147], v[150:151]
	v_mul_f32_e32 v150, v183, v183
	v_mul_f32_e32 v158, v167, v167
	v_add_f32_e32 v152, v152, v153
	v_add_f32_e32 v153, v164, v165
	v_mul_f32_e32 v162, v218, v218
	v_mul_f32_e32 v164, v219, v219
	v_pk_fma_f32 v[150:151], v[182:183], v[182:183], v[150:151] op_sel_hi:[1,1,0]
	v_pk_fma_f32 v[158:159], v[166:167], v[166:167], v[158:159] op_sel_hi:[1,1,0]
	v_mov_b32_e32 v151, v162
	v_mov_b32_e32 v159, v164
	v_pk_add_f32 v[150:151], v[150:151], v[158:159]
	s_nop 0
	v_pk_add_f32 v[146:147], v[146:147], v[150:151]
	s_nop 0
	v_add_f32_e32 v149, v146, v147
	v_mov_b32_e32 v146, v152
	s_nop 1
	v_permlane16_swap_b32_e32 v152, v146
	v_mov_b32_e32 v147, v153
	s_nop 1
	v_permlane16_swap_b32_e32 v153, v147
	v_mov_b32_e32 v150, v148
	s_nop 1
	v_permlane16_swap_b32_e32 v148, v150
	v_mov_b32_e32 v151, v149
	s_nop 1
	v_permlane16_swap_b32_e32 v149, v151
	s_waitcnt lgkmcnt(0)
	v_pk_add_f32 v[146:147], v[152:153], v[146:147]
	s_waitcnt lgkmcnt(0)
	v_pk_add_f32 v[150:151], v[148:149], v[150:151]
	v_mov_b32_e32 v148, v146
	s_nop 1
	v_permlane32_swap_b32_e32 v146, v148
	v_mov_b32_e32 v149, v147
	s_nop 1
	v_permlane32_swap_b32_e32 v147, v149
	v_mov_b32_e32 v152, v150
	s_nop 1
	v_permlane32_swap_b32_e32 v150, v152
	v_mov_b32_e32 v153, v151
	s_nop 1
	v_permlane32_swap_b32_e32 v151, v153
	s_and_saveexec_b64 s[0:1], vcc
	s_cbranch_execz .LBB0_837
	s_lshl_b32 s5, s23, 12
	s_add_i32 s5, s4, s5
	s_waitcnt lgkmcnt(0)
	v_pk_add_f32 v[150:151], v[150:151], v[152:153]
	v_pk_add_f32 v[148:149], v[146:147], v[148:149]
	v_add_u32_e32 v146, s5, v155
	ds_write_b128 v146, v[148:151] offset:2048
;     __device__ __forceinline__ void fused(f32x4 (&acc)[2][2][4][2], const Unit& u, int wr, int wc, int fr, int fq, PG8_LAS unsigned char* lds, int wid, int lane) const {
;     ...
;         for (int ai = 0; ai < 2; ++ai)
; #pragma unroll
;             for (int m = 0; m < 4; ++m) {
;                 float saa = 0.f, sxx = 0.f, sxag = 0.f, sgg = 0.f;
; #pragma unroll
;                 for (int bj = 0; bj < 2; ++bj) { const u32x4 w4 = XL[((ai * 4 + m) * 2 + bj) * 512];
; #pragma unroll
;                     for (int n = 0; n < 2; ++n) { const f32x4 a = acc[ai][bj][m][n]; const f32x4 ag = a * gv[bj][n]; const unsigned wx = n == 0 ? w4.x : w4.z, wy = n == 0 ? w4.y : w4.w;
;                         const f32x4 x = (f32x4){bflo(wx), bfhi(wx), bflo(wy), bfhi(wy)};
;                         saa += (a[0] * a[0] + a[1] * a[1]) + (a[2] * a[2] + a[3] * a[3]); sxx += (x[0] * x[0] + x[1] * x[1]) + (x[2] * x[2] + x[3] * x[3]);
;                         sxag += (x[0] * ag[0] + x[1] * ag[1]) + (x[2] * ag[2] + x[3] * ag[3]); sgg += (ag[0] * ag[0] + ag[1] * ag[1]) + (ag[2] * ag[2] + ag[3] * ag[3]); } }
;                 asm volatile("" : "+v"(saa), "+v"(sxx), "+v"(sxag), "+v"(sgg));
;                 saa += __shfl_xor(saa, 16); sxx += __shfl_xor(sxx, 16); sxag += __shfl_xor(sxag, 16); sgg += __shfl_xor(sgg, 16);
;                 saa += __shfl_xor(saa, 32); sxx += __shfl_xor(sxx, 32); sxag += __shfl_xor(sxag, 32); sgg += __shfl_xor(sgg, 32);
;                 if (fq == 0) P[(ai * HALF + wr * 64 + m * 16 + fr) * 4 + wc] = (f32x4){saa, sxx, sxag, sgg};
.LBB0_837:
	s_or_b64 exec, exec, s[0:1]
	s_waitcnt lgkmcnt(0)
	ds_read_b128 v[146:149], v207 offset:49152
	v_pk_mul_f32 v[150:151], v[80:81], v[80:81]
	s_waitcnt lgkmcnt(0)
	v_pk_mul_f32 v[152:153], v[78:79], v[78:79]
	v_pk_mul_f32 v[158:159], v[80:81], v[144:145]
	v_pk_mov_b32 v[164:165], v[152:153], v[150:151] op_sel:[1,0]
	v_mov_b32_e32 v153, v151
	v_pk_add_f32 v[150:151], v[164:165], v[152:153]
	v_pk_mul_f32 v[160:161], v[78:79], v[142:143]
	v_pk_add_f32 v[164:165], v[150:151], v[150:151] op_sel_hi:[0,1]
	ds_read_b128 v[150:153], v207 offset:57344
	s_waitcnt lgkmcnt(0)
	v_lshlrev_b32_e32 v166, 16, v146
	v_and_b32_e32 v173, 0xffff0000, v146
	v_and_b32_e32 v172, 16, v146
	v_mov_b32_e32 v167, v173
	v_mul_f32_e32 v146, v166, v166
	v_pk_fma_f32 v[174:175], v[166:167], v[166:167], v[146:147] op_sel_hi:[1,1,0]
	v_lshlrev_b32_e32 v146, 16, v147
	v_and_b32_e32 v147, 0xffff0000, v147
	v_mul_f32_e32 v162, v146, v146
	v_mov_b32_e32 v184, v160
	v_mov_b32_e32 v185, v159
	v_mov_b32_e32 v167, v147
	v_pk_fma_f32 v[180:181], v[146:147], v[146:147], v[162:163] op_sel_hi:[1,1,0]
	v_pk_mov_b32 v[182:183], v[160:161], v[158:159] op_sel:[1,0]
	v_pk_mov_b32 v[172:173], v[172:173], v[146:147] op_sel:[1,0]
	v_pk_mul_f32 v[146:147], v[184:185], v[166:167]
	v_pk_mul_f32 v[158:159], v[158:159], v[158:159]
	v_pk_mul_f32 v[160:161], v[160:161], v[160:161]
	v_pk_fma_f32 v[146:147], v[182:183], v[172:173], v[146:147]
	v_pk_mov_b32 v[166:167], v[160:161], v[158:159] op_sel:[1,0]
	v_mov_b32_e32 v161, v159
	v_pk_mul_f32 v[172:173], v[76:77], v[76:77]
	v_pk_mul_f32 v[182:183], v[74:75], v[74:75]
	v_pk_add_f32 v[158:159], v[166:167], v[160:161]
	v_pk_mul_f32 v[160:161], v[76:77], v[140:141]
	v_pk_mul_f32 v[166:167], v[74:75], v[138:139]
	v_pk_mov_b32 v[184:185], v[182:183], v[172:173] op_sel:[1,0]
	v_mov_b32_e32 v183, v173
	v_add_f32_e32 v146, v146, v147
	v_pk_add_f32 v[172:173], v[184:185], v[182:183]
	v_lshlrev_b32_e32 v183, 16, v149
	v_lshlrev_b32_e32 v182, 16, v148
	v_and_b32_e32 v149, 0xffff0000, v149
	v_and_b32_e32 v148, 0xffff0000, v148
	v_mov_b32_e32 v210, v167
	v_mov_b32_e32 v211, v161
	v_add_f32_e32 v147, 0, v146
	v_pk_mul_f32 v[184:185], v[148:149], v[148:149]
	v_mov_b32_e32 v208, v166
	v_mov_b32_e32 v209, v160
	v_pk_mul_f32 v[148:149], v[210:211], v[148:149]
	v_mul_f32_e32 v146, v70, v70
	v_pk_fma_f32 v[148:149], v[208:209], v[182:183], v[148:149]
	v_pk_mul_f32 v[160:161], v[160:161], v[160:161]
	v_pk_mul_f32 v[166:167], v[166:167], v[166:167]
	v_pk_fma_f32 v[208:209], v[70:71], v[70:71], v[146:147] op_sel_hi:[1,1,0]
	v_mul_f32_e32 v146, v72, v72
	s_waitcnt lgkmcnt(0)
	v_lshlrev_b32_e32 v212, 16, v150
	v_pk_fma_f32 v[184:185], v[182:183], v[182:183], v[184:185]
	v_pk_mov_b32 v[182:183], v[166:167], v[160:161] op_sel:[1,0]
	v_mov_b32_e32 v167, v161
	v_pk_fma_f32 v[210:211], v[72:73], v[72:73], v[146:147] op_sel_hi:[1,1,0]
	v_and_b32_e32 v213, 0xffff0000, v150
	v_mul_f32_e32 v146, v212, v212
	v_lshlrev_b32_e32 v150, 16, v151
	v_pk_add_f32 v[160:161], v[182:183], v[166:167]
	v_pk_mul_f32 v[182:183], v[70:71], v[134:135]
	v_pk_fma_f32 v[214:215], v[212:213], v[212:213], v[146:147] op_sel_hi:[1,1,0]
	v_and_b32_e32 v151, 0xffff0000, v151
	v_mul_f32_e32 v146, v150, v150
	v_pk_mul_f32 v[166:167], v[72:73], v[136:137]
	v_pk_fma_f32 v[216:217], v[150:151], v[150:151], v[146:147] op_sel_hi:[1,1,0]
	v_mul_f32_e32 v146, v182, v212
	v_pk_add_f32 v[172:173], v[172:173], v[172:173] op_sel_hi:[0,1]
	v_pk_add_f32 v[148:149], v[148:149], v[148:149] op_sel_hi:[0,1]
	v_pk_fma_f32 v[212:213], v[182:183], v[212:213], v[146:147] op_sel_hi:[1,1,0]
	v_mul_f32_e32 v146, v166, v150
	v_pk_add_f32 v[184:185], v[184:185], v[184:185] op_sel_hi:[0,1]
	v_pk_fma_f32 v[150:151], v[166:167], v[150:151], v[146:147] op_sel_hi:[1,1,0]
	v_pk_mul_f32 v[218:219], v[68:69], v[132:133]
	v_pk_mul_f32 v[220:221], v[66:67], v[130:131]
	v_lshlrev_b32_e32 v222, 16, v152
	v_and_b32_e32 v146, 0xffff0000, v152
	v_lshlrev_b32_e32 v148, 16, v153
	v_and_b32_e32 v157, 0xffff0000, v153
	v_mul_f32_e32 v208, v66, v66
	v_mul_f32_e32 v210, v67, v67
	v_mul_f32_e32 v172, v68, v68
	v_mul_f32_e32 v164, v69, v69
	v_pk_add_f32 v[152:153], v[208:209], v[210:211]
	v_pk_add_f32 v[164:165], v[172:173], v[164:165]
	v_mul_f32_e32 v184, v146, v146
	v_mul_f32_e32 v214, v148, v148
	v_mul_f32_e32 v212, v220, v222
	v_mul_f32_e32 v150, v221, v146
	v_mul_f32_e32 v148, v218, v148
	v_mul_f32_e32 v146, v219, v157
	v_pk_add_f32 v[152:153], v[152:153], v[164:165]
	v_mov_b32_e32 v223, v175
	v_mov_b32_e32 v164, v222
	v_mov_b32_e32 v165, v181
	v_pk_add_f32 v[150:151], v[212:213], v[150:151]
	v_pk_add_f32 v[146:147], v[148:149], v[146:147]
	v_pk_mul_f32 v[164:165], v[222:223], v[164:165]
	v_pk_add_f32 v[172:173], v[174:175], v[180:181]
	v_pk_add_f32 v[146:147], v[150:151], v[146:147]
	v_mul_f32_e32 v216, v157, v157
	v_mov_b32_e32 v165, v173
	v_add_f32_e32 v148, v146, v147
	v_mul_f32_e32 v149, v220, v220
	v_mul_f32_e32 v157, v221, v221
	v_pk_add_f32 v[146:147], v[158:159], v[158:159] op_sel:[0,1] op_sel_hi:[1,0]
	v_pk_add_f32 v[150:151], v[160:161], v[160:161] op_sel:[0,1] op_sel_hi:[1,0]
	v_pk_add_f32 v[164:165], v[164:165], v[184:185]
	v_pk_add_f32 v[172:173], v[214:215], v[216:217]
	v_mov_b32_e32 v147, v149
	v_mov_b32_e32 v151, v157
	v_pk_add_f32 v[164:165], v[164:165], v[172:173]
	v_pk_add_f32 v[146:147], v[146:147], v[150:151]
	v_mul_f32_e32 v150, v183, v183
	v_mul_f32_e32 v158, v167, v167
	v_add_f32_e32 v152, v152, v153
	v_add_f32_e32 v153, v164, v165
	v_mul_f32_e32 v162, v218, v218
	v_mul_f32_e32 v164, v219, v219
	v_pk_fma_f32 v[150:151], v[182:183], v[182:183], v[150:151] op_sel_hi:[1,1,0]
	v_pk_fma_f32 v[158:159], v[166:167], v[166:167], v[158:159] op_sel_hi:[1,1,0]
	v_mov_b32_e32 v151, v162
	v_mov_b32_e32 v159, v164
	v_pk_add_f32 v[150:151], v[150:151], v[158:159]
	s_nop 0
	v_pk_add_f32 v[146:147], v[146:147], v[150:151]
	s_nop 0
	v_add_f32_e32 v149, v146, v147
	v_mov_b32_e32 v146, v152
	s_nop 1
	v_permlane16_swap_b32_e32 v152, v146
	v_mov_b32_e32 v147, v153
	s_nop 1
	v_permlane16_swap_b32_e32 v153, v147
	v_mov_b32_e32 v150, v148
	s_nop 1
	v_permlane16_swap_b32_e32 v148, v150
	v_mov_b32_e32 v151, v149
	s_nop 1
	v_permlane16_swap_b32_e32 v149, v151
	s_waitcnt lgkmcnt(0)
	v_pk_add_f32 v[146:147], v[152:153], v[146:147]
	s_waitcnt lgkmcnt(0)
	v_pk_add_f32 v[150:151], v[148:149], v[150:151]
	v_mov_b32_e32 v148, v146
	s_nop 1
	v_permlane32_swap_b32_e32 v146, v148
	v_mov_b32_e32 v149, v147
	s_nop 1
	v_permlane32_swap_b32_e32 v147, v149
	v_mov_b32_e32 v152, v150
	s_nop 1
	v_permlane32_swap_b32_e32 v150, v152
	v_mov_b32_e32 v153, v151
	s_nop 1
	v_permlane32_swap_b32_e32 v151, v153
	s_and_saveexec_b64 s[0:1], vcc
	s_cbranch_execz .LBB0_839
	s_lshl_b32 s5, s23, 12
	s_add_i32 s5, s4, s5
	s_waitcnt lgkmcnt(0)
	v_pk_add_f32 v[150:151], v[150:151], v[152:153]
	v_pk_add_f32 v[148:149], v[146:147], v[148:149]
	v_add_u32_e32 v146, s5, v155
	ds_write_b128 v146, v[148:151] offset:3072
;     __device__ __forceinline__ void fused(f32x4 (&acc)[2][2][4][2], const Unit& u, int wr, int wc, int fr, int fq, PG8_LAS unsigned char* lds, int wid, int lane) const {
;     ...
;         for (int ai = 0; ai < 2; ++ai)
; #pragma unroll
;             for (int m = 0; m < 4; ++m) {
;                 float saa = 0.f, sxx = 0.f, sxag = 0.f, sgg = 0.f;
; #pragma unroll
;                 for (int bj = 0; bj < 2; ++bj) { const u32x4 w4 = XL[((ai * 4 + m) * 2 + bj) * 512];
; #pragma unroll
;                     for (int n = 0; n < 2; ++n) { const f32x4 a = acc[ai][bj][m][n]; const f32x4 ag = a * gv[bj][n]; const unsigned wx = n == 0 ? w4.x : w4.z, wy = n == 0 ? w4.y : w4.w;
;                         const f32x4 x = (f32x4){bflo(wx), bfhi(wx), bflo(wy), bfhi(wy)};
;                         saa += (a[0] * a[0] + a[1] * a[1]) + (a[2] * a[2] + a[3] * a[3]); sxx += (x[0] * x[0] + x[1] * x[1]) + (x[2] * x[2] + x[3] * x[3]);
;                         sxag += (x[0] * ag[0] + x[1] * ag[1]) + (x[2] * ag[2] + x[3] * ag[3]); sgg += (ag[0] * ag[0] + ag[1] * ag[1]) + (ag[2] * ag[2] + ag[3] * ag[3]); } }
;                 asm volatile("" : "+v"(saa), "+v"(sxx), "+v"(sxag), "+v"(sgg));
;                 saa += __shfl_xor(saa, 16); sxx += __shfl_xor(sxx, 16); sxag += __shfl_xor(sxag, 16); sgg += __shfl_xor(sgg, 16);
;                 saa += __shfl_xor(saa, 32); sxx += __shfl_xor(sxx, 32); sxag += __shfl_xor(sxag, 32); sgg += __shfl_xor(sgg, 32);
;                 if (fq == 0) P[(ai * HALF + wr * 64 + m * 16 + fr) * 4 + wc] = (f32x4){saa, sxx, sxag, sgg};
.LBB0_839:
	s_or_b64 exec, exec, s[0:1]
	s_waitcnt lgkmcnt(0)
	ds_read_b128 v[146:149], v206
	v_pk_mul_f32 v[150:151], v[64:65], v[64:65]
	s_waitcnt lgkmcnt(0)
	v_pk_mul_f32 v[152:153], v[62:63], v[62:63]
	v_pk_mul_f32 v[158:159], v[64:65], v[144:145]
	v_pk_mov_b32 v[164:165], v[152:153], v[150:151] op_sel:[1,0]
	v_mov_b32_e32 v153, v151
	v_pk_add_f32 v[150:151], v[164:165], v[152:153]
	v_pk_mul_f32 v[160:161], v[62:63], v[142:143]
	v_pk_add_f32 v[164:165], v[150:151], v[150:151] op_sel_hi:[0,1]
	ds_read_b128 v[150:153], v205
	s_waitcnt lgkmcnt(0)
	v_lshlrev_b32_e32 v166, 16, v146
	v_and_b32_e32 v173, 0xffff0000, v146
	v_and_b32_e32 v172, 16, v146
	v_mov_b32_e32 v167, v173
	v_mul_f32_e32 v146, v166, v166
	v_pk_fma_f32 v[174:175], v[166:167], v[166:167], v[146:147] op_sel_hi:[1,1,0]
	v_lshlrev_b32_e32 v146, 16, v147
	v_and_b32_e32 v147, 0xffff0000, v147
	v_mul_f32_e32 v162, v146, v146
	v_mov_b32_e32 v184, v160
	v_mov_b32_e32 v185, v159
	v_mov_b32_e32 v167, v147
	v_pk_fma_f32 v[180:181], v[146:147], v[146:147], v[162:163] op_sel_hi:[1,1,0]
	v_pk_mov_b32 v[182:183], v[160:161], v[158:159] op_sel:[1,0]
	v_pk_mov_b32 v[172:173], v[172:173], v[146:147] op_sel:[1,0]
	v_pk_mul_f32 v[146:147], v[184:185], v[166:167]
	v_pk_mul_f32 v[158:159], v[158:159], v[158:159]
	v_pk_mul_f32 v[160:161], v[160:161], v[160:161]
	v_pk_fma_f32 v[146:147], v[182:183], v[172:173], v[146:147]
	v_pk_mov_b32 v[166:167], v[160:161], v[158:159] op_sel:[1,0]
	v_mov_b32_e32 v161, v159
	v_pk_mul_f32 v[172:173], v[60:61], v[60:61]
	v_pk_mul_f32 v[182:183], v[58:59], v[58:59]
	v_pk_add_f32 v[158:159], v[166:167], v[160:161]
	v_pk_mul_f32 v[160:161], v[60:61], v[140:141]
	v_pk_mul_f32 v[166:167], v[58:59], v[138:139]
	v_pk_mov_b32 v[184:185], v[182:183], v[172:173] op_sel:[1,0]
	v_mov_b32_e32 v183, v173
	v_add_f32_e32 v146, v146, v147
	v_pk_add_f32 v[172:173], v[184:185], v[182:183]
	v_lshlrev_b32_e32 v183, 16, v149
	v_lshlrev_b32_e32 v182, 16, v148
	v_and_b32_e32 v149, 0xffff0000, v149
	v_and_b32_e32 v148, 0xffff0000, v148
	v_mov_b32_e32 v210, v167
	v_mov_b32_e32 v211, v161
	v_add_f32_e32 v147, 0, v146
	v_pk_mul_f32 v[184:185], v[148:149], v[148:149]
	v_mov_b32_e32 v208, v166
	v_mov_b32_e32 v209, v160
	v_pk_mul_f32 v[148:149], v[210:211], v[148:149]
	v_mul_f32_e32 v146, v54, v54
	v_pk_fma_f32 v[148:149], v[208:209], v[182:183], v[148:149]
	v_pk_mul_f32 v[160:161], v[160:161], v[160:161]
	v_pk_mul_f32 v[166:167], v[166:167], v[166:167]
	v_pk_fma_f32 v[208:209], v[54:55], v[54:55], v[146:147] op_sel_hi:[1,1,0]
	v_mul_f32_e32 v146, v56, v56
	s_waitcnt lgkmcnt(0)
	v_lshlrev_b32_e32 v212, 16, v150
	v_pk_fma_f32 v[184:185], v[182:183], v[182:183], v[184:185]
	v_pk_mov_b32 v[182:183], v[166:167], v[160:161] op_sel:[1,0]
	v_mov_b32_e32 v167, v161
	v_pk_fma_f32 v[210:211], v[56:57], v[56:57], v[146:147] op_sel_hi:[1,1,0]
	v_and_b32_e32 v213, 0xffff0000, v150
	v_mul_f32_e32 v146, v212, v212
	v_lshlrev_b32_e32 v150, 16, v151
	v_pk_add_f32 v[160:161], v[182:183], v[166:167]
	v_pk_mul_f32 v[182:183], v[54:55], v[134:135]
	v_pk_fma_f32 v[214:215], v[212:213], v[212:213], v[146:147] op_sel_hi:[1,1,0]
	v_and_b32_e32 v151, 0xffff0000, v151
	v_mul_f32_e32 v146, v150, v150
	v_pk_mul_f32 v[166:167], v[56:57], v[136:137]
	v_pk_fma_f32 v[216:217], v[150:151], v[150:151], v[146:147] op_sel_hi:[1,1,0]
	v_mul_f32_e32 v146, v182, v212
	v_pk_add_f32 v[172:173], v[172:173], v[172:173] op_sel_hi:[0,1]
	v_pk_add_f32 v[148:149], v[148:149], v[148:149] op_sel_hi:[0,1]
	v_pk_fma_f32 v[212:213], v[182:183], v[212:213], v[146:147] op_sel_hi:[1,1,0]
	v_mul_f32_e32 v146, v166, v150
	v_pk_add_f32 v[184:185], v[184:185], v[184:185] op_sel_hi:[0,1]
	v_pk_fma_f32 v[150:151], v[166:167], v[150:151], v[146:147] op_sel_hi:[1,1,0]
	v_pk_mul_f32 v[218:219], v[52:53], v[132:133]
	v_pk_mul_f32 v[220:221], v[50:51], v[130:131]
	v_lshlrev_b32_e32 v222, 16, v152
	v_and_b32_e32 v146, 0xffff0000, v152
	v_lshlrev_b32_e32 v148, 16, v153
	v_and_b32_e32 v157, 0xffff0000, v153
	v_mul_f32_e32 v208, v50, v50
	v_mul_f32_e32 v210, v51, v51
	v_mul_f32_e32 v172, v52, v52
	v_mul_f32_e32 v164, v53, v53
	v_pk_add_f32 v[152:153], v[208:209], v[210:211]
	v_pk_add_f32 v[164:165], v[172:173], v[164:165]
	v_mul_f32_e32 v184, v146, v146
	v_mul_f32_e32 v214, v148, v148
	v_mul_f32_e32 v212, v220, v222
	v_mul_f32_e32 v150, v221, v146
	v_mul_f32_e32 v148, v218, v148
	v_mul_f32_e32 v146, v219, v157
	v_pk_add_f32 v[152:153], v[152:153], v[164:165]
	v_mov_b32_e32 v223, v175
	v_mov_b32_e32 v164, v222
	v_mov_b32_e32 v165, v181
	v_pk_add_f32 v[150:151], v[212:213], v[150:151]
	v_pk_add_f32 v[146:147], v[148:149], v[146:147]
	v_pk_mul_f32 v[164:165], v[222:223], v[164:165]
	v_pk_add_f32 v[172:173], v[174:175], v[180:181]
	v_pk_add_f32 v[146:147], v[150:151], v[146:147]
	v_mul_f32_e32 v216, v157, v157
	v_mov_b32_e32 v165, v173
	v_add_f32_e32 v148, v146, v147
	v_mul_f32_e32 v149, v220, v220
	v_mul_f32_e32 v157, v221, v221
	v_pk_add_f32 v[146:147], v[158:159], v[158:159] op_sel:[0,1] op_sel_hi:[1,0]
	v_pk_add_f32 v[150:151], v[160:161], v[160:161] op_sel:[0,1] op_sel_hi:[1,0]
	v_pk_add_f32 v[164:165], v[164:165], v[184:185]
	v_pk_add_f32 v[172:173], v[214:215], v[216:217]
	v_mov_b32_e32 v147, v149
	v_mov_b32_e32 v151, v157
	v_pk_add_f32 v[164:165], v[164:165], v[172:173]
	v_pk_add_f32 v[146:147], v[146:147], v[150:151]
	v_mul_f32_e32 v150, v183, v183
	v_mul_f32_e32 v158, v167, v167
	v_add_f32_e32 v152, v152, v153
	v_add_f32_e32 v153, v164, v165
	v_mul_f32_e32 v162, v218, v218
	v_mul_f32_e32 v164, v219, v219
	v_pk_fma_f32 v[150:151], v[182:183], v[182:183], v[150:151] op_sel_hi:[1,1,0]
	v_pk_fma_f32 v[158:159], v[166:167], v[166:167], v[158:159] op_sel_hi:[1,1,0]
	v_mov_b32_e32 v151, v162
	v_mov_b32_e32 v159, v164
	v_pk_add_f32 v[150:151], v[150:151], v[158:159]
	s_nop 0
	v_pk_add_f32 v[146:147], v[146:147], v[150:151]
	s_nop 0
	v_add_f32_e32 v149, v146, v147
	v_mov_b32_e32 v146, v152
	s_nop 1
	v_permlane16_swap_b32_e32 v152, v146
	v_mov_b32_e32 v147, v153
	s_nop 1
	v_permlane16_swap_b32_e32 v153, v147
	v_mov_b32_e32 v150, v148
	s_nop 1
	v_permlane16_swap_b32_e32 v148, v150
	v_mov_b32_e32 v151, v149
	s_nop 1
	v_permlane16_swap_b32_e32 v149, v151
	s_waitcnt lgkmcnt(0)
	v_pk_add_f32 v[146:147], v[152:153], v[146:147]
	s_waitcnt lgkmcnt(0)
	v_pk_add_f32 v[150:151], v[148:149], v[150:151]
	v_mov_b32_e32 v148, v146
	s_nop 1
	v_permlane32_swap_b32_e32 v146, v148
	v_mov_b32_e32 v149, v147
	s_nop 1
	v_permlane32_swap_b32_e32 v147, v149
	v_mov_b32_e32 v152, v150
	s_nop 1
	v_permlane32_swap_b32_e32 v150, v152
	v_mov_b32_e32 v153, v151
	s_nop 1
	v_permlane32_swap_b32_e32 v151, v153
	s_and_saveexec_b64 s[0:1], vcc
	s_cbranch_execz .LBB0_841
	s_lshl_b32 s5, s23, 12
	s_add_i32 s5, s4, s5
	s_waitcnt lgkmcnt(0)
	v_pk_add_f32 v[150:151], v[150:151], v[152:153]
	v_pk_add_f32 v[148:149], v[146:147], v[148:149]
	v_add_u32_e32 v146, s5, v155
	ds_write_b128 v146, v[148:151] offset:8192
;     __device__ __forceinline__ void fused(f32x4 (&acc)[2][2][4][2], const Unit& u, int wr, int wc, int fr, int fq, PG8_LAS unsigned char* lds, int wid, int lane) const {
;     ...
;         for (int ai = 0; ai < 2; ++ai)
; #pragma unroll
;             for (int m = 0; m < 4; ++m) {
;                 float saa = 0.f, sxx = 0.f, sxag = 0.f, sgg = 0.f;
; #pragma unroll
;                 for (int bj = 0; bj < 2; ++bj) { const u32x4 w4 = XL[((ai * 4 + m) * 2 + bj) * 512];
; #pragma unroll
;                     for (int n = 0; n < 2; ++n) { const f32x4 a = acc[ai][bj][m][n]; const f32x4 ag = a * gv[bj][n]; const unsigned wx = n == 0 ? w4.x : w4.z, wy = n == 0 ? w4.y : w4.w;
;                         const f32x4 x = (f32x4){bflo(wx), bfhi(wx), bflo(wy), bfhi(wy)};
;                         saa += (a[0] * a[0] + a[1] * a[1]) + (a[2] * a[2] + a[3] * a[3]); sxx += (x[0] * x[0] + x[1] * x[1]) + (x[2] * x[2] + x[3] * x[3]);
;                         sxag += (x[0] * ag[0] + x[1] * ag[1]) + (x[2] * ag[2] + x[3] * ag[3]); sgg += (ag[0] * ag[0] + ag[1] * ag[1]) + (ag[2] * ag[2] + ag[3] * ag[3]); } }
;                 asm volatile("" : "+v"(saa), "+v"(sxx), "+v"(sxag), "+v"(sgg));
;                 saa += __shfl_xor(saa, 16); sxx += __shfl_xor(sxx, 16); sxag += __shfl_xor(sxag, 16); sgg += __shfl_xor(sgg, 16);
;                 saa += __shfl_xor(saa, 32); sxx += __shfl_xor(sxx, 32); sxag += __shfl_xor(sxag, 32); sgg += __shfl_xor(sgg, 32);
;                 if (fq == 0) P[(ai * HALF + wr * 64 + m * 16 + fr) * 4 + wc] = (f32x4){saa, sxx, sxag, sgg};
.LBB0_841:
	s_or_b64 exec, exec, s[0:1]
	s_waitcnt lgkmcnt(0)
	ds_read_b128 v[146:149], v204
	v_pk_mul_f32 v[150:151], v[48:49], v[48:49]
	s_waitcnt lgkmcnt(0)
	v_pk_mul_f32 v[152:153], v[46:47], v[46:47]
	v_pk_mul_f32 v[158:159], v[48:49], v[144:145]
	v_pk_mov_b32 v[164:165], v[152:153], v[150:151] op_sel:[1,0]
	v_mov_b32_e32 v153, v151
	v_pk_add_f32 v[150:151], v[164:165], v[152:153]
	v_pk_mul_f32 v[160:161], v[46:47], v[142:143]
	v_pk_add_f32 v[164:165], v[150:151], v[150:151] op_sel_hi:[0,1]
	ds_read_b128 v[150:153], v203
	s_waitcnt lgkmcnt(0)
	v_lshlrev_b32_e32 v166, 16, v146
	v_and_b32_e32 v173, 0xffff0000, v146
	v_and_b32_e32 v172, 16, v146
	v_mov_b32_e32 v167, v173
	v_mul_f32_e32 v146, v166, v166
	v_pk_fma_f32 v[174:175], v[166:167], v[166:167], v[146:147] op_sel_hi:[1,1,0]
	v_lshlrev_b32_e32 v146, 16, v147
	v_and_b32_e32 v147, 0xffff0000, v147
	v_mul_f32_e32 v162, v146, v146
	v_mov_b32_e32 v184, v160
	v_mov_b32_e32 v185, v159
	v_mov_b32_e32 v167, v147
	v_pk_fma_f32 v[180:181], v[146:147], v[146:147], v[162:163] op_sel_hi:[1,1,0]
	v_pk_mov_b32 v[182:183], v[160:161], v[158:159] op_sel:[1,0]
	v_pk_mov_b32 v[172:173], v[172:173], v[146:147] op_sel:[1,0]
	v_pk_mul_f32 v[146:147], v[184:185], v[166:167]
	v_pk_mul_f32 v[158:159], v[158:159], v[158:159]
	v_pk_mul_f32 v[160:161], v[160:161], v[160:161]
	v_pk_fma_f32 v[146:147], v[182:183], v[172:173], v[146:147]
	v_pk_mov_b32 v[166:167], v[160:161], v[158:159] op_sel:[1,0]
	v_mov_b32_e32 v161, v159
	v_pk_mul_f32 v[172:173], v[44:45], v[44:45]
	v_pk_mul_f32 v[182:183], v[42:43], v[42:43]
	v_pk_add_f32 v[158:159], v[166:167], v[160:161]
	v_pk_mul_f32 v[160:161], v[44:45], v[140:141]
	v_pk_mul_f32 v[166:167], v[42:43], v[138:139]
	v_pk_mov_b32 v[184:185], v[182:183], v[172:173] op_sel:[1,0]
	v_mov_b32_e32 v183, v173
	v_add_f32_e32 v146, v146, v147
	v_pk_add_f32 v[172:173], v[184:185], v[182:183]
	v_lshlrev_b32_e32 v183, 16, v149
	v_lshlrev_b32_e32 v182, 16, v148
	v_and_b32_e32 v149, 0xffff0000, v149
	v_and_b32_e32 v148, 0xffff0000, v148
	v_mov_b32_e32 v210, v167
	v_mov_b32_e32 v211, v161
	v_add_f32_e32 v147, 0, v146
	v_pk_mul_f32 v[184:185], v[148:149], v[148:149]
	v_mov_b32_e32 v208, v166
	v_mov_b32_e32 v209, v160
	v_pk_mul_f32 v[148:149], v[210:211], v[148:149]
	v_mul_f32_e32 v146, v38, v38
	v_pk_fma_f32 v[148:149], v[208:209], v[182:183], v[148:149]
	v_pk_mul_f32 v[160:161], v[160:161], v[160:161]
	v_pk_mul_f32 v[166:167], v[166:167], v[166:167]
	v_pk_fma_f32 v[208:209], v[38:39], v[38:39], v[146:147] op_sel_hi:[1,1,0]
	v_mul_f32_e32 v146, v40, v40
	s_waitcnt lgkmcnt(0)
	v_lshlrev_b32_e32 v212, 16, v150
	v_pk_fma_f32 v[184:185], v[182:183], v[182:183], v[184:185]
	v_pk_mov_b32 v[182:183], v[166:167], v[160:161] op_sel:[1,0]
	v_mov_b32_e32 v167, v161
	v_pk_fma_f32 v[210:211], v[40:41], v[40:41], v[146:147] op_sel_hi:[1,1,0]
	v_and_b32_e32 v213, 0xffff0000, v150
	v_mul_f32_e32 v146, v212, v212
	v_lshlrev_b32_e32 v150, 16, v151
	v_pk_add_f32 v[160:161], v[182:183], v[166:167]
	v_pk_mul_f32 v[182:183], v[38:39], v[134:135]
	v_pk_fma_f32 v[214:215], v[212:213], v[212:213], v[146:147] op_sel_hi:[1,1,0]
	v_and_b32_e32 v151, 0xffff0000, v151
	v_mul_f32_e32 v146, v150, v150
	v_pk_mul_f32 v[166:167], v[40:41], v[136:137]
	v_pk_fma_f32 v[216:217], v[150:151], v[150:151], v[146:147] op_sel_hi:[1,1,0]
	v_mul_f32_e32 v146, v182, v212
	v_pk_add_f32 v[172:173], v[172:173], v[172:173] op_sel_hi:[0,1]
	v_pk_add_f32 v[148:149], v[148:149], v[148:149] op_sel_hi:[0,1]
	v_pk_fma_f32 v[212:213], v[182:183], v[212:213], v[146:147] op_sel_hi:[1,1,0]
	v_mul_f32_e32 v146, v166, v150
	v_pk_add_f32 v[184:185], v[184:185], v[184:185] op_sel_hi:[0,1]
	v_pk_fma_f32 v[150:151], v[166:167], v[150:151], v[146:147] op_sel_hi:[1,1,0]
	v_pk_mul_f32 v[218:219], v[36:37], v[132:133]
	v_pk_mul_f32 v[220:221], v[34:35], v[130:131]
	v_lshlrev_b32_e32 v222, 16, v152
	v_and_b32_e32 v146, 0xffff0000, v152
	v_lshlrev_b32_e32 v148, 16, v153
	v_and_b32_e32 v157, 0xffff0000, v153
	v_mul_f32_e32 v208, v34, v34
	v_mul_f32_e32 v210, v35, v35
	v_mul_f32_e32 v172, v36, v36
	v_mul_f32_e32 v164, v37, v37
	v_pk_add_f32 v[152:153], v[208:209], v[210:211]
	v_pk_add_f32 v[164:165], v[172:173], v[164:165]
	v_mul_f32_e32 v184, v146, v146
	v_mul_f32_e32 v214, v148, v148
	v_mul_f32_e32 v212, v220, v222
	v_mul_f32_e32 v150, v221, v146
	v_mul_f32_e32 v148, v218, v148
	v_mul_f32_e32 v146, v219, v157
	v_pk_add_f32 v[152:153], v[152:153], v[164:165]
	v_mov_b32_e32 v223, v175
	v_mov_b32_e32 v164, v222
	v_mov_b32_e32 v165, v181
	v_pk_add_f32 v[150:151], v[212:213], v[150:151]
	v_pk_add_f32 v[146:147], v[148:149], v[146:147]
	v_pk_mul_f32 v[164:165], v[222:223], v[164:165]
	v_pk_add_f32 v[172:173], v[174:175], v[180:181]
	v_pk_add_f32 v[146:147], v[150:151], v[146:147]
	v_mul_f32_e32 v216, v157, v157
	v_mov_b32_e32 v165, v173
	v_add_f32_e32 v148, v146, v147
	v_mul_f32_e32 v149, v220, v220
	v_mul_f32_e32 v157, v221, v221
	v_pk_add_f32 v[146:147], v[158:159], v[158:159] op_sel:[0,1] op_sel_hi:[1,0]
	v_pk_add_f32 v[150:151], v[160:161], v[160:161] op_sel:[0,1] op_sel_hi:[1,0]
	v_pk_add_f32 v[164:165], v[164:165], v[184:185]
	v_pk_add_f32 v[172:173], v[214:215], v[216:217]
	v_mov_b32_e32 v147, v149
	v_mov_b32_e32 v151, v157
	v_pk_add_f32 v[164:165], v[164:165], v[172:173]
	v_pk_add_f32 v[146:147], v[146:147], v[150:151]
	v_mul_f32_e32 v150, v183, v183
	v_mul_f32_e32 v158, v167, v167
	v_add_f32_e32 v152, v152, v153
	v_add_f32_e32 v153, v164, v165
	v_mul_f32_e32 v162, v218, v218
	v_mul_f32_e32 v164, v219, v219
	v_pk_fma_f32 v[150:151], v[182:183], v[182:183], v[150:151] op_sel_hi:[1,1,0]
	v_pk_fma_f32 v[158:159], v[166:167], v[166:167], v[158:159] op_sel_hi:[1,1,0]
	v_mov_b32_e32 v151, v162
	v_mov_b32_e32 v159, v164
	v_pk_add_f32 v[150:151], v[150:151], v[158:159]
	s_nop 0
	v_pk_add_f32 v[146:147], v[146:147], v[150:151]
	s_nop 0
	v_add_f32_e32 v149, v146, v147
	v_mov_b32_e32 v146, v152
	s_nop 1
	v_permlane16_swap_b32_e32 v152, v146
	v_mov_b32_e32 v147, v153
	s_nop 1
	v_permlane16_swap_b32_e32 v153, v147
	v_mov_b32_e32 v150, v148
	s_nop 1
	v_permlane16_swap_b32_e32 v148, v150
	v_mov_b32_e32 v151, v149
	s_nop 1
	v_permlane16_swap_b32_e32 v149, v151
	s_waitcnt lgkmcnt(0)
	v_pk_add_f32 v[146:147], v[152:153], v[146:147]
	s_waitcnt lgkmcnt(0)
	v_pk_add_f32 v[150:151], v[148:149], v[150:151]
	v_mov_b32_e32 v148, v146
	s_nop 1
	v_permlane32_swap_b32_e32 v146, v148
	v_mov_b32_e32 v149, v147
	s_nop 1
	v_permlane32_swap_b32_e32 v147, v149
	v_mov_b32_e32 v152, v150
	s_nop 1
	v_permlane32_swap_b32_e32 v150, v152
	v_mov_b32_e32 v153, v151
	s_nop 1
	v_permlane32_swap_b32_e32 v151, v153
	s_and_saveexec_b64 s[0:1], vcc
	s_cbranch_execz .LBB0_843
	s_lshl_b32 s5, s23, 12
	s_add_i32 s5, s4, s5
	s_waitcnt lgkmcnt(0)
	v_pk_add_f32 v[150:151], v[150:151], v[152:153]
	v_pk_add_f32 v[148:149], v[146:147], v[148:149]
	v_add_u32_e32 v146, s5, v155
	ds_write_b128 v146, v[148:151] offset:9216
;     __device__ __forceinline__ void fused(f32x4 (&acc)[2][2][4][2], const Unit& u, int wr, int wc, int fr, int fq, PG8_LAS unsigned char* lds, int wid, int lane) const {
;     ...
;         for (int ai = 0; ai < 2; ++ai)
; #pragma unroll
;             for (int m = 0; m < 4; ++m) {
;                 float saa = 0.f, sxx = 0.f, sxag = 0.f, sgg = 0.f;
; #pragma unroll
;                 for (int bj = 0; bj < 2; ++bj) { const u32x4 w4 = XL[((ai * 4 + m) * 2 + bj) * 512];
; #pragma unroll
;                     for (int n = 0; n < 2; ++n) { const f32x4 a = acc[ai][bj][m][n]; const f32x4 ag = a * gv[bj][n]; const unsigned wx = n == 0 ? w4.x : w4.z, wy = n == 0 ? w4.y : w4.w;
;                         const f32x4 x = (f32x4){bflo(wx), bfhi(wx), bflo(wy), bfhi(wy)};
;                         saa += (a[0] * a[0] + a[1] * a[1]) + (a[2] * a[2] + a[3] * a[3]); sxx += (x[0] * x[0] + x[1] * x[1]) + (x[2] * x[2] + x[3] * x[3]);
;                         sxag += (x[0] * ag[0] + x[1] * ag[1]) + (x[2] * ag[2] + x[3] * ag[3]); sgg += (ag[0] * ag[0] + ag[1] * ag[1]) + (ag[2] * ag[2] + ag[3] * ag[3]); } }
;                 asm volatile("" : "+v"(saa), "+v"(sxx), "+v"(sxag), "+v"(sgg));
;                 saa += __shfl_xor(saa, 16); sxx += __shfl_xor(sxx, 16); sxag += __shfl_xor(sxag, 16); sgg += __shfl_xor(sgg, 16);
;                 saa += __shfl_xor(saa, 32); sxx += __shfl_xor(sxx, 32); sxag += __shfl_xor(sxag, 32); sgg += __shfl_xor(sgg, 32);
;                 if (fq == 0) P[(ai * HALF + wr * 64 + m * 16 + fr) * 4 + wc] = (f32x4){saa, sxx, sxag, sgg};
.LBB0_843:
	s_or_b64 exec, exec, s[0:1]
	s_waitcnt lgkmcnt(0)
	ds_read_b128 v[146:149], v202
	v_pk_mul_f32 v[150:151], v[32:33], v[32:33]
	s_waitcnt lgkmcnt(0)
	v_pk_mul_f32 v[152:153], v[30:31], v[30:31]
	v_pk_mul_f32 v[158:159], v[32:33], v[144:145]
	v_pk_mov_b32 v[164:165], v[152:153], v[150:151] op_sel:[1,0]
	v_mov_b32_e32 v153, v151
	v_pk_add_f32 v[150:151], v[164:165], v[152:153]
	v_pk_mul_f32 v[160:161], v[30:31], v[142:143]
	v_pk_add_f32 v[164:165], v[150:151], v[150:151] op_sel_hi:[0,1]
	ds_read_b128 v[150:153], v201
	s_waitcnt lgkmcnt(0)
	v_lshlrev_b32_e32 v166, 16, v146
	v_and_b32_e32 v173, 0xffff0000, v146
	v_and_b32_e32 v172, 16, v146
	v_mov_b32_e32 v167, v173
	v_mul_f32_e32 v146, v166, v166
	v_pk_fma_f32 v[174:175], v[166:167], v[166:167], v[146:147] op_sel_hi:[1,1,0]
	v_lshlrev_b32_e32 v146, 16, v147
	v_and_b32_e32 v147, 0xffff0000, v147
	v_mul_f32_e32 v162, v146, v146
	v_mov_b32_e32 v184, v160
	v_mov_b32_e32 v185, v159
	v_mov_b32_e32 v167, v147
	v_pk_fma_f32 v[180:181], v[146:147], v[146:147], v[162:163] op_sel_hi:[1,1,0]
	v_pk_mov_b32 v[182:183], v[160:161], v[158:159] op_sel:[1,0]
	v_pk_mov_b32 v[172:173], v[172:173], v[146:147] op_sel:[1,0]
	v_pk_mul_f32 v[146:147], v[184:185], v[166:167]
	v_pk_mul_f32 v[158:159], v[158:159], v[158:159]
	v_pk_mul_f32 v[160:161], v[160:161], v[160:161]
	v_pk_fma_f32 v[146:147], v[182:183], v[172:173], v[146:147]
	v_pk_mov_b32 v[166:167], v[160:161], v[158:159] op_sel:[1,0]
	v_mov_b32_e32 v161, v159
	v_pk_mul_f32 v[172:173], v[28:29], v[28:29]
	v_pk_mul_f32 v[182:183], v[26:27], v[26:27]
	v_pk_add_f32 v[158:159], v[166:167], v[160:161]
	v_pk_mul_f32 v[160:161], v[28:29], v[140:141]
	v_pk_mul_f32 v[166:167], v[26:27], v[138:139]
	v_pk_mov_b32 v[184:185], v[182:183], v[172:173] op_sel:[1,0]
	v_mov_b32_e32 v183, v173
	v_add_f32_e32 v146, v146, v147
	v_pk_add_f32 v[172:173], v[184:185], v[182:183]
	v_lshlrev_b32_e32 v183, 16, v149
	v_lshlrev_b32_e32 v182, 16, v148
	v_and_b32_e32 v149, 0xffff0000, v149
	v_and_b32_e32 v148, 0xffff0000, v148
	v_mov_b32_e32 v210, v167
	v_mov_b32_e32 v211, v161
	v_add_f32_e32 v147, 0, v146
	v_pk_mul_f32 v[184:185], v[148:149], v[148:149]
	v_mov_b32_e32 v208, v166
	v_mov_b32_e32 v209, v160
	v_pk_mul_f32 v[148:149], v[210:211], v[148:149]
	v_mul_f32_e32 v146, v22, v22
	v_pk_fma_f32 v[148:149], v[208:209], v[182:183], v[148:149]
	v_pk_mul_f32 v[160:161], v[160:161], v[160:161]
	v_pk_mul_f32 v[166:167], v[166:167], v[166:167]
	v_pk_fma_f32 v[208:209], v[22:23], v[22:23], v[146:147] op_sel_hi:[1,1,0]
	v_mul_f32_e32 v146, v24, v24
	s_waitcnt lgkmcnt(0)
	v_lshlrev_b32_e32 v212, 16, v150
	v_pk_fma_f32 v[184:185], v[182:183], v[182:183], v[184:185]
	v_pk_mov_b32 v[182:183], v[166:167], v[160:161] op_sel:[1,0]
	v_mov_b32_e32 v167, v161
	v_pk_fma_f32 v[210:211], v[24:25], v[24:25], v[146:147] op_sel_hi:[1,1,0]
	v_and_b32_e32 v213, 0xffff0000, v150
	v_mul_f32_e32 v146, v212, v212
	v_lshlrev_b32_e32 v150, 16, v151
	v_pk_add_f32 v[160:161], v[182:183], v[166:167]
	v_pk_mul_f32 v[182:183], v[22:23], v[134:135]
	v_pk_fma_f32 v[214:215], v[212:213], v[212:213], v[146:147] op_sel_hi:[1,1,0]
	v_and_b32_e32 v151, 0xffff0000, v151
	v_mul_f32_e32 v146, v150, v150
	v_pk_mul_f32 v[166:167], v[24:25], v[136:137]
	v_pk_fma_f32 v[216:217], v[150:151], v[150:151], v[146:147] op_sel_hi:[1,1,0]
	v_mul_f32_e32 v146, v182, v212
	v_pk_add_f32 v[172:173], v[172:173], v[172:173] op_sel_hi:[0,1]
	v_pk_add_f32 v[148:149], v[148:149], v[148:149] op_sel_hi:[0,1]
	v_pk_fma_f32 v[212:213], v[182:183], v[212:213], v[146:147] op_sel_hi:[1,1,0]
	v_mul_f32_e32 v146, v166, v150
	v_pk_add_f32 v[184:185], v[184:185], v[184:185] op_sel_hi:[0,1]
	v_pk_fma_f32 v[150:151], v[166:167], v[150:151], v[146:147] op_sel_hi:[1,1,0]
	v_pk_mul_f32 v[218:219], v[20:21], v[132:133]
	v_pk_mul_f32 v[220:221], v[18:19], v[130:131]
	v_lshlrev_b32_e32 v222, 16, v152
	v_and_b32_e32 v146, 0xffff0000, v152
	v_lshlrev_b32_e32 v148, 16, v153
	v_and_b32_e32 v157, 0xffff0000, v153
	v_mul_f32_e32 v208, v18, v18
	v_mul_f32_e32 v210, v19, v19
	v_mul_f32_e32 v172, v20, v20
	v_mul_f32_e32 v164, v21, v21
	v_pk_add_f32 v[152:153], v[208:209], v[210:211]
	v_pk_add_f32 v[164:165], v[172:173], v[164:165]
	v_mul_f32_e32 v184, v146, v146
	v_mul_f32_e32 v214, v148, v148
	v_mul_f32_e32 v212, v220, v222
	v_mul_f32_e32 v150, v221, v146
	v_mul_f32_e32 v148, v218, v148
	v_mul_f32_e32 v146, v219, v157
	v_pk_add_f32 v[152:153], v[152:153], v[164:165]
	v_mov_b32_e32 v223, v175
	v_mov_b32_e32 v164, v222
	v_mov_b32_e32 v165, v181
	v_pk_add_f32 v[150:151], v[212:213], v[150:151]
	v_pk_add_f32 v[146:147], v[148:149], v[146:147]
	v_pk_mul_f32 v[164:165], v[222:223], v[164:165]
	v_pk_add_f32 v[172:173], v[174:175], v[180:181]
	v_pk_add_f32 v[146:147], v[150:151], v[146:147]
	v_mul_f32_e32 v216, v157, v157
	v_mov_b32_e32 v165, v173
	v_add_f32_e32 v148, v146, v147
	v_mul_f32_e32 v149, v220, v220
	v_mul_f32_e32 v157, v221, v221
	v_pk_add_f32 v[146:147], v[158:159], v[158:159] op_sel:[0,1] op_sel_hi:[1,0]
	v_pk_add_f32 v[150:151], v[160:161], v[160:161] op_sel:[0,1] op_sel_hi:[1,0]
	v_pk_add_f32 v[164:165], v[164:165], v[184:185]
	v_pk_add_f32 v[172:173], v[214:215], v[216:217]
	v_mov_b32_e32 v147, v149
	v_mov_b32_e32 v151, v157
	v_pk_add_f32 v[164:165], v[164:165], v[172:173]
	v_pk_add_f32 v[146:147], v[146:147], v[150:151]
	v_mul_f32_e32 v150, v183, v183
	v_mul_f32_e32 v158, v167, v167
	v_add_f32_e32 v152, v152, v153
	v_add_f32_e32 v153, v164, v165
	v_mul_f32_e32 v162, v218, v218
	v_mul_f32_e32 v164, v219, v219
	v_pk_fma_f32 v[150:151], v[182:183], v[182:183], v[150:151] op_sel_hi:[1,1,0]
	v_pk_fma_f32 v[158:159], v[166:167], v[166:167], v[158:159] op_sel_hi:[1,1,0]
	v_mov_b32_e32 v151, v162
	v_mov_b32_e32 v159, v164
	v_pk_add_f32 v[150:151], v[150:151], v[158:159]
	s_nop 0
	v_pk_add_f32 v[146:147], v[146:147], v[150:151]
	s_nop 0
	v_add_f32_e32 v149, v146, v147
	v_mov_b32_e32 v146, v152
	s_nop 1
	v_permlane16_swap_b32_e32 v152, v146
	v_mov_b32_e32 v147, v153
	s_nop 1
	v_permlane16_swap_b32_e32 v153, v147
	v_mov_b32_e32 v150, v148
	s_nop 1
	v_permlane16_swap_b32_e32 v148, v150
	v_mov_b32_e32 v151, v149
	s_nop 1
	v_permlane16_swap_b32_e32 v149, v151
	s_waitcnt lgkmcnt(0)
	v_pk_add_f32 v[146:147], v[152:153], v[146:147]
	s_waitcnt lgkmcnt(0)
	v_pk_add_f32 v[150:151], v[148:149], v[150:151]
	v_mov_b32_e32 v148, v146
	s_nop 1
	v_permlane32_swap_b32_e32 v146, v148
	v_mov_b32_e32 v149, v147
	s_nop 1
	v_permlane32_swap_b32_e32 v147, v149
	v_mov_b32_e32 v152, v150
	s_nop 1
	v_permlane32_swap_b32_e32 v150, v152
	v_mov_b32_e32 v153, v151
	s_nop 1
	v_permlane32_swap_b32_e32 v151, v153
	s_and_saveexec_b64 s[0:1], vcc
	s_cbranch_execz .LBB0_845
	s_lshl_b32 s5, s23, 12
	s_add_i32 s5, s4, s5
	s_waitcnt lgkmcnt(0)
	v_pk_add_f32 v[150:151], v[150:151], v[152:153]
	v_pk_add_f32 v[148:149], v[146:147], v[148:149]
	v_add_u32_e32 v146, s5, v155
	ds_write_b128 v146, v[148:151] offset:10240
;     __device__ __forceinline__ void fused(f32x4 (&acc)[2][2][4][2], const Unit& u, int wr, int wc, int fr, int fq, PG8_LAS unsigned char* lds, int wid, int lane) const {
;     ...
;         for (int ai = 0; ai < 2; ++ai)
; #pragma unroll
;             for (int m = 0; m < 4; ++m) {
;                 float saa = 0.f, sxx = 0.f, sxag = 0.f, sgg = 0.f;
; #pragma unroll
;                 for (int bj = 0; bj < 2; ++bj) { const u32x4 w4 = XL[((ai * 4 + m) * 2 + bj) * 512];
; #pragma unroll
;                     for (int n = 0; n < 2; ++n) { const f32x4 a = acc[ai][bj][m][n]; const f32x4 ag = a * gv[bj][n]; const unsigned wx = n == 0 ? w4.x : w4.z, wy = n == 0 ? w4.y : w4.w;
;                         const f32x4 x = (f32x4){bflo(wx), bfhi(wx), bflo(wy), bfhi(wy)};
;                         saa += (a[0] * a[0] + a[1] * a[1]) + (a[2] * a[2] + a[3] * a[3]); sxx += (x[0] * x[0] + x[1] * x[1]) + (x[2] * x[2] + x[3] * x[3]);
;                         sxag += (x[0] * ag[0] + x[1] * ag[1]) + (x[2] * ag[2] + x[3] * ag[3]); sgg += (ag[0] * ag[0] + ag[1] * ag[1]) + (ag[2] * ag[2] + ag[3] * ag[3]); } }
;                 asm volatile("" : "+v"(saa), "+v"(sxx), "+v"(sxag), "+v"(sgg));
;                 saa += __shfl_xor(saa, 16); sxx += __shfl_xor(sxx, 16); sxag += __shfl_xor(sxag, 16); sgg += __shfl_xor(sgg, 16);
;                 saa += __shfl_xor(saa, 32); sxx += __shfl_xor(sxx, 32); sxag += __shfl_xor(sxag, 32); sgg += __shfl_xor(sgg, 32);
;                 if (fq == 0) P[(ai * HALF + wr * 64 + m * 16 + fr) * 4 + wc] = (f32x4){saa, sxx, sxag, sgg};
;                 __builtin_amdgcn_sched_barrier(0);
.LBB0_845:
	s_or_b64 exec, exec, s[0:1]
	s_waitcnt lgkmcnt(0)
	ds_read_b128 v[146:149], v0
	v_pk_mul_f32 v[150:151], v[16:17], v[144:145]
	s_waitcnt lgkmcnt(0)
	v_pk_mul_f32 v[152:153], v[14:15], v[142:143]
	v_pk_mul_f32 v[142:143], v[16:17], v[16:17]
	v_pk_mul_f32 v[144:145], v[14:15], v[14:15]
	v_pk_mov_b32 v[174:175], v[152:153], v[150:151] op_sel:[1,0]
	v_pk_mov_b32 v[158:159], v[144:145], v[142:143] op_sel:[1,0]
	v_mov_b32_e32 v145, v143
	v_pk_add_f32 v[142:143], v[158:159], v[144:145]
	v_mov_b32_e32 v180, v152
	v_pk_add_f32 v[158:159], v[142:143], v[142:143] op_sel_hi:[0,1]
	ds_read_b128 v[142:145], v200
	s_waitcnt lgkmcnt(0)
	v_lshlrev_b32_e32 v160, 16, v146
	v_and_b32_e32 v165, 0xffff0000, v146
	v_and_b32_e32 v164, 16, v146
	v_mov_b32_e32 v161, v165
	v_mul_f32_e32 v146, v160, v160
	v_pk_fma_f32 v[166:167], v[160:161], v[160:161], v[146:147] op_sel_hi:[1,1,0]
	v_lshlrev_b32_e32 v146, 16, v147
	v_and_b32_e32 v147, 0xffff0000, v147
	v_mul_f32_e32 v158, v146, v146
	v_mov_b32_e32 v181, v151
	v_mov_b32_e32 v161, v147
	v_pk_mul_f32 v[150:151], v[150:151], v[150:151]
	v_pk_mul_f32 v[152:153], v[152:153], v[152:153]
	v_pk_fma_f32 v[172:173], v[146:147], v[146:147], v[158:159] op_sel_hi:[1,1,0]
	v_pk_mov_b32 v[164:165], v[164:165], v[146:147] op_sel:[1,0]
	v_pk_mul_f32 v[146:147], v[180:181], v[160:161]
	v_pk_mov_b32 v[160:161], v[152:153], v[150:151] op_sel:[1,0]
	v_mov_b32_e32 v153, v151
	v_pk_add_f32 v[150:151], v[160:161], v[152:153]
	v_pk_mul_f32 v[152:153], v[12:13], v[12:13]
	v_pk_mul_f32 v[160:161], v[10:11], v[10:11]
	v_pk_fma_f32 v[146:147], v[174:175], v[164:165], v[146:147]
	v_pk_mul_f32 v[140:141], v[12:13], v[140:141]
	v_pk_mul_f32 v[138:139], v[10:11], v[138:139]
	v_pk_mov_b32 v[164:165], v[160:161], v[152:153] op_sel:[1,0]
	v_mov_b32_e32 v161, v153
	v_pk_add_f32 v[152:153], v[164:165], v[160:161]
	v_lshlrev_b32_e32 v161, 16, v149
	v_lshlrev_b32_e32 v160, 16, v148
	v_and_b32_e32 v149, 0xffff0000, v149
	v_and_b32_e32 v148, 0xffff0000, v148
	v_mov_b32_e32 v180, v139
	v_mov_b32_e32 v181, v141
	v_pk_mul_f32 v[164:165], v[148:149], v[148:149]
	v_mov_b32_e32 v174, v138
	v_mov_b32_e32 v175, v140
	v_pk_mul_f32 v[148:149], v[180:181], v[148:149]
	v_pk_mul_f32 v[140:141], v[140:141], v[140:141]
	v_pk_mul_f32 v[138:139], v[138:139], v[138:139]
	v_pk_fma_f32 v[164:165], v[160:161], v[160:161], v[164:165]
	v_pk_fma_f32 v[148:149], v[174:175], v[160:161], v[148:149]
	v_pk_mov_b32 v[160:161], v[138:139], v[140:141] op_sel:[1,0]
	v_mul_f32_e32 v140, v6, v6
	v_mov_b32_e32 v139, v141
	v_pk_fma_f32 v[140:141], v[6:7], v[6:7], v[140:141] op_sel_hi:[1,1,0]
	s_waitcnt lgkmcnt(0)
	v_lshlrev_b32_e32 v174, 16, v142
	v_mul_f32_e32 v140, v8, v8
	v_pk_add_f32 v[138:139], v[160:161], v[138:139]
	v_pk_fma_f32 v[160:161], v[8:9], v[8:9], v[140:141] op_sel_hi:[1,1,0]
	v_and_b32_e32 v175, 0xffff0000, v142
	v_mul_f32_e32 v140, v174, v174
	v_lshlrev_b32_e32 v142, 16, v143
	v_pk_mul_f32 v[134:135], v[6:7], v[134:135]
	v_pk_fma_f32 v[180:181], v[174:175], v[174:175], v[140:141] op_sel_hi:[1,1,0]
	v_and_b32_e32 v143, 0xffff0000, v143
	v_mul_f32_e32 v140, v142, v142
	v_pk_mul_f32 v[136:137], v[8:9], v[136:137]
	v_pk_fma_f32 v[182:183], v[142:143], v[142:143], v[140:141] op_sel_hi:[1,1,0]
	v_mul_f32_e32 v140, v134, v174
	v_pk_add_f32 v[152:153], v[152:153], v[152:153] op_sel_hi:[0,1]
	v_pk_fma_f32 v[174:175], v[134:135], v[174:175], v[140:141] op_sel_hi:[1,1,0]
	v_mul_f32_e32 v140, v136, v142
	v_add_f32_e32 v146, v146, v147
	v_pk_fma_f32 v[142:143], v[136:137], v[142:143], v[140:141] op_sel_hi:[1,1,0]
	v_mul_f32_e32 v140, v2, v2
	v_mul_f32_e32 v160, v3, v3
	v_mul_f32_e32 v152, v4, v4
	v_mul_f32_e32 v158, v5, v5
	v_add_f32_e32 v147, 0, v146
	v_lshlrev_b32_e32 v184, 16, v144
	v_and_b32_e32 v142, 0xffff0000, v144
	v_lshlrev_b32_e32 v146, 16, v145
	v_and_b32_e32 v157, 0xffff0000, v145
	v_pk_add_f32 v[140:141], v[140:141], v[160:161]
	v_pk_add_f32 v[144:145], v[152:153], v[158:159]
	v_mov_b32_e32 v185, v167
	v_pk_add_f32 v[140:141], v[140:141], v[144:145]
	v_mov_b32_e32 v144, v184
	v_mov_b32_e32 v145, v173
	v_pk_add_f32 v[164:165], v[164:165], v[164:165] op_sel_hi:[0,1]
	v_pk_mul_f32 v[144:145], v[184:185], v[144:145]
	v_pk_add_f32 v[152:153], v[166:167], v[172:173]
	v_mul_f32_e32 v164, v142, v142
	v_mul_f32_e32 v180, v146, v146
	v_mul_f32_e32 v182, v157, v157
	v_mov_b32_e32 v145, v153
	v_pk_add_f32 v[148:149], v[148:149], v[148:149] op_sel_hi:[0,1]
	v_pk_mul_f32 v[132:133], v[4:5], v[132:133]
	v_pk_mul_f32 v[130:131], v[2:3], v[130:131]
	v_pk_add_f32 v[144:145], v[144:145], v[164:165]
	v_pk_add_f32 v[152:153], v[180:181], v[182:183]
	v_mul_f32_e32 v174, v130, v184
	v_pk_add_f32 v[144:145], v[144:145], v[152:153]
	v_mul_f32_e32 v142, v131, v142
	v_mul_f32_e32 v148, v132, v146
	v_mul_f32_e32 v146, v133, v157
	v_add_f32_e32 v140, v140, v141
	v_add_f32_e32 v141, v144, v145
	v_pk_add_f32 v[142:143], v[174:175], v[142:143]
	v_pk_add_f32 v[144:145], v[148:149], v[146:147]
	v_mul_f32_e32 v146, v133, v133
	v_pk_add_f32 v[142:143], v[142:143], v[144:145]
	v_mul_f32_e32 v144, v131, v131
	v_add_f32_e32 v142, v142, v143
	v_mul_f32_e32 v143, v130, v130
	v_mul_f32_e32 v145, v132, v132
	v_pk_add_f32 v[130:131], v[150:151], v[150:151] op_sel:[0,1] op_sel_hi:[1,0]
	v_pk_add_f32 v[132:133], v[138:139], v[138:139] op_sel:[0,1] op_sel_hi:[1,0]
	v_mov_b32_e32 v131, v143
	v_mov_b32_e32 v133, v144
	v_pk_add_f32 v[130:131], v[130:131], v[132:133]
	v_mul_f32_e32 v132, v135, v135
	v_pk_fma_f32 v[132:133], v[134:135], v[134:135], v[132:133] op_sel_hi:[1,1,0]
	v_mul_f32_e32 v134, v137, v137
	v_pk_fma_f32 v[134:135], v[136:137], v[136:137], v[134:135] op_sel_hi:[1,1,0]
	v_mov_b32_e32 v133, v145
	v_mov_b32_e32 v135, v146
	v_pk_add_f32 v[132:133], v[132:133], v[134:135]
	s_nop 0
	v_pk_add_f32 v[130:131], v[130:131], v[132:133]
	s_nop 0
	v_add_f32_e32 v143, v130, v131
	v_mov_b32_e32 v130, v140
	s_nop 1
	v_permlane16_swap_b32_e32 v140, v130
	v_mov_b32_e32 v131, v141
	s_nop 1
	v_permlane16_swap_b32_e32 v141, v131
	v_mov_b32_e32 v132, v142
	s_nop 1
	v_permlane16_swap_b32_e32 v142, v132
	v_mov_b32_e32 v133, v143
	s_nop 1
	v_permlane16_swap_b32_e32 v143, v133
	s_waitcnt lgkmcnt(0)
	v_pk_add_f32 v[130:131], v[140:141], v[130:131]
	s_waitcnt lgkmcnt(0)
	v_pk_add_f32 v[134:135], v[142:143], v[132:133]
	v_mov_b32_e32 v132, v130
	s_nop 1
	v_permlane32_swap_b32_e32 v130, v132
	v_mov_b32_e32 v133, v131
	s_nop 1
	v_permlane32_swap_b32_e32 v131, v133
	v_mov_b32_e32 v136, v134
	s_nop 1
	v_permlane32_swap_b32_e32 v134, v136
	v_mov_b32_e32 v137, v135
	s_nop 1
	v_permlane32_swap_b32_e32 v135, v137
	s_and_saveexec_b64 s[0:1], vcc
	s_cbranch_execz .LBB0_847
	s_lshl_b32 s5, s23, 12
	s_add_i32 s4, s4, s5
	s_waitcnt lgkmcnt(0)
	v_pk_add_f32 v[134:135], v[134:135], v[136:137]
	v_pk_add_f32 v[132:133], v[130:131], v[132:133]
	v_add_u32_e32 v130, s4, v155
	ds_write_b128 v130, v[132:135] offset:11264
;     __device__ __forceinline__ void fused(f32x4 (&acc)[2][2][4][2], const Unit& u, int wr, int wc, int fr, int fq, PG8_LAS unsigned char* lds, int wid, int lane) const {
;     ...
;         asm volatile("s_waitcnt lgkmcnt(0)" ::: "memory"); __builtin_amdgcn_s_barrier(); asm volatile("" ::: "memory");
;         const int row = wid * 32 + (lane & 31);
;         unsigned long long* slot = xbuf + ((size_t)(u.pm * BM + row) * 8) * 2;
;         if (lane < 32) { const f32x4 q = (P[row * 4 + 0] + P[row * 4 + 1]) + (P[row * 4 + 2] + P[row * 4 + 3]);
;             __hip_atomic_store(slot + u.pn * 2, ((unsigned long long)__float_as_uint(q[1]) << 32) | __float_as_uint(q[0]), __ATOMIC_RELAXED, __HIP_MEMORY_SCOPE_AGENT);
;             __hip_atomic_store(slot + u.pn * 2 + 1, ((unsigned long long)__float_as_uint(q[3]) << 32) | __float_as_uint(q[2]), __ATOMIC_RELAXED, __HIP_MEMORY_SCOPE_AGENT); }
.LBB0_847:
	s_or_b64 exec, exec, s[0:1]
	v_readlane_b32 s48, v254, 62
	v_readlane_b32 s49, v254, 63
	s_lshl_b64 s[0:1], s[48:49], 3
	v_readlane_b32 s4, v251, 61
	s_add_u32 s0, s4, s0
	v_readlane_b32 s4, v251, 62
	s_addc_u32 s1, s4, s1
	v_readlane_b32 s50, v255, 0
	v_readlane_b32 s51, v255, 1
	v_readlane_b32 s52, v255, 2
	v_readlane_b32 s53, v255, 3
	v_readlane_b32 s54, v255, 4
	v_readlane_b32 s55, v255, 5
	v_readlane_b32 s56, v255, 6
	v_readlane_b32 s57, v255, 7
	v_readlane_b32 s58, v255, 8
	v_readlane_b32 s59, v255, 9
	v_readlane_b32 s60, v255, 10
	v_readlane_b32 s61, v255, 11
	v_readlane_b32 s62, v255, 12
	v_readlane_b32 s63, v255, 13
	v_and_b32_e32 v130, 31, v154
	v_lshl_or_b32 v138, s22, 5, v130
	v_add_u32_e32 v130, s10, v138
	s_waitcnt lgkmcnt(0)
	s_barrier
	v_ashrrev_i32_e32 v131, 31, v130
	v_lshlrev_b64 v[130:131], 7, v[130:131]
	v_lshl_add_u64 v[130:131], s[0:1], 0, v[130:131]
	v_cmp_gt_u32_e64 s[0:1], 32, v156
	s_and_saveexec_b64 s[4:5], s[0:1]
	s_cbranch_execz .LBB0_849
	s_waitcnt lgkmcnt(0)
	v_lshl_add_u32 v132, v138, 6, 0
	s_waitcnt lgkmcnt(0)
	v_add_u32_e32 v136, 0x20000, v132
	ds_read_b128 v[132:135], v136
	ds_read_b128 v[140:143], v136 offset:16
	ds_read_b128 v[144:147], v136 offset:32
	ds_read_b128 v[148:151], v136 offset:48
	s_lshl_b32 s6, s25, 1
	s_ashr_i32 s7, s6, 31
	s_waitcnt lgkmcnt(0)
	v_pk_add_f32 v[134:135], v[134:135], v[142:143]
	v_pk_add_f32 v[132:133], v[132:133], v[140:141]
	s_waitcnt lgkmcnt(0)
	v_pk_add_f32 v[136:137], v[146:147], v[150:151]
	v_pk_add_f32 v[140:141], v[144:145], v[148:149]
	v_pk_add_f32 v[134:135], v[134:135], v[136:137]
	v_pk_add_f32 v[132:133], v[132:133], v[140:141]
	v_lshl_add_u64 v[136:137], s[6:7], 3, v[130:131]
	global_store_dwordx2 v[136:137], v[132:133], off sc1
	global_store_dwordx2 v[136:137], v[134:135], off offset:8 sc1

; #define PG8_LAS __attribute__((address_space(3)))
;     __device__ __forceinline__ void fused(f32x4 (&acc)[2][2][4][2], const Unit& u, int wr, int wc, int fr, int fq, PG8_LAS unsigned char* lds, int wid, int lane) const {
;     ...
;         const int col0 = u.pn * BM + wc * 32 + 8 * fq;
;         f32x4 gv[2][2];
; #pragma unroll
;         for (int bj = 0; bj < 2; ++bj)
; #pragma unroll
;             for (int n = 0; n < 2; ++n) gv[bj][n] = *(const f32x4*)(g1 + col0 + bj * HALF + n * 4);
;         PG8_LAS u32x4* XL = (PG8_LAS u32x4*)lds + (wid * 64 + lane);
; #pragma unroll
;         for (int ai = 0; ai < 2; ++ai)
; #pragma unroll
;             for (int m = 0; m < 4; ++m) { const size_t off = (size_t)(u.pm * BM + ai * HALF + wr * 64 + m * 16 + fr) * ldc + col0;
; #pragma unroll
;                 for (int bj = 0; bj < 2; ++bj) XL[((ai * 4 + m) * 2 + bj) * 512] = *(const u32x4*)(base_b + off + bj * HALF); }
.LBB0_1071:
	v_readlane_b32 s0, v251, 17
	v_readlane_b32 s1, v251, 18
	v_readlane_b32 s2, v251, 19
	v_readlane_b32 s8, v251, 25
	v_readlane_b32 s0, v255, 21
	v_readlane_b32 s3, v251, 20
	v_readlane_b32 s9, v251, 26
	v_readlane_b32 s1, v255, 22
	s_add_u32 s2, s8, s0
	v_readlane_b32 s10, v251, 27
	s_addc_u32 s3, s9, s1
	s_lshl_b32 s0, s22, 5
	s_lshl_b32 s1, s21, 8
	v_lshrrev_b32_e32 v0, 1, v154
	s_or_b32 s0, s1, s0
	s_lshl_b32 s10, s20, 8
	v_and_or_b32 v176, v0, 24, s0
	s_add_i32 s0, s10, s16
	v_or_b32_e32 v164, s0, v178
	v_or_b32_e32 v158, 16, v164
	v_readlane_b32 s0, v251, 63
	v_ashrrev_i32_e32 v159, 31, v158
	v_ashrrev_i32_e32 v177, 31, v176
	v_readlane_b32 s1, v252, 0
	v_lshlrev_b64 v[158:159], 12, v[158:159]
	v_lshlrev_b64 v[166:167], 1, v[176:177]
	v_lshl_add_u64 v[158:159], s[0:1], 0, v[158:159]
	v_lshl_add_u64 v[134:135], v[176:177], 2, s[2:3]
	v_lshl_add_u64 v[172:173], v[158:159], 0, v[166:167]
	s_barrier
	global_load_dwordx4 v[138:141], v[134:135], off offset:16
	global_load_dwordx4 v[142:145], v[134:135], off
	global_load_dwordx4 v[130:133], v[134:135], off offset:528
	s_nop 0
	global_load_dwordx4 v[134:137], v[134:135], off offset:512
	v_and_b32_e32 v156, 63, v154
	global_load_dwordx4 v[158:161], v[172:173], off
	v_lshl_add_u32 v207, v156, 4, s26
	v_add_u32_e32 v206, 0x10000, v207
	v_add_u32_e32 v205, 0x12000, v207
	v_add_u32_e32 v204, 0x14000, v207
	v_add_u32_e32 v203, 0x16000, v207
	v_add_u32_e32 v202, 0x18000, v207
	v_add_u32_e32 v201, 0x1a000, v207
	v_ashrrev_i32_e32 v165, 31, v164
	v_lshlrev_b64 v[146:147], 12, v[164:165]
	v_lshl_add_u64 v[146:147], s[0:1], 0, v[146:147]
	v_lshl_add_u64 v[146:147], v[146:147], 0, v[166:167]
	global_load_dwordx4 v[150:153], v[146:147], off
	v_add_u32_e32 v200, 0x1c000, v207
	v_add_u32_e32 v0, 0x1e000, v207
	v_readlane_b32 s4, v251, 21
	v_cmp_gt_u32_e32 vcc, 16, v156
	v_readlane_b32 s5, v251, 22
	v_readlane_b32 s6, v251, 23
	v_readlane_b32 s7, v251, 24
	v_readlane_b32 s11, v251, 28
	v_readlane_b32 s12, v251, 29
	v_readlane_b32 s13, v251, 30
	v_readlane_b32 s14, v251, 31
	v_readlane_b32 s15, v251, 32
	s_waitcnt vmcnt(0)
	v_pk_mul_f32 v[218:219], v[116:117], v[132:133]
	v_pk_mul_f32 v[220:221], v[114:115], v[130:131]
	ds_write_b128 v207, v[158:161] offset:16384
	global_load_dwordx4 v[224:227], v[172:173], off offset:256
	v_or_b32_e32 v158, 32, v164
	v_ashrrev_i32_e32 v159, 31, v158
	v_lshlrev_b64 v[158:159], 12, v[158:159]
	v_lshl_add_u64 v[158:159], s[0:1], 0, v[158:159]
	v_lshl_add_u64 v[172:173], v[158:159], 0, v[166:167]
	global_load_dwordx4 v[228:231], v[172:173], off
	global_load_dwordx4 v[232:235], v[172:173], off offset:256
	v_or_b32_e32 v158, 48, v164
	v_ashrrev_i32_e32 v159, 31, v158
	v_lshlrev_b64 v[158:159], 12, v[158:159]
	v_lshl_add_u64 v[158:159], s[0:1], 0, v[158:159]
	v_lshl_add_u64 v[172:173], v[158:159], 0, v[166:167]
	global_load_dwordx4 v[236:239], v[172:173], off
	global_load_dwordx4 v[240:243], v[172:173], off offset:256
	v_add_u32_e32 v158, 0x80, v164
	v_ashrrev_i32_e32 v159, 31, v158
	v_lshlrev_b64 v[158:159], 12, v[158:159]
	v_lshl_add_u64 v[158:159], s[0:1], 0, v[158:159]
	v_lshl_add_u64 v[172:173], v[158:159], 0, v[166:167]
	global_load_dwordx4 v[244:247], v[172:173], off
	global_load_dwordx4 v[158:161], v[172:173], off offset:256
	s_waitcnt vmcnt(6)
	ds_write_b128 v207, v[224:227] offset:24576
	s_waitcnt vmcnt(5)
	ds_write_b128 v207, v[228:231] offset:32768
	s_waitcnt vmcnt(4)
	ds_write_b128 v207, v[232:235] offset:40960
	s_waitcnt vmcnt(3)
	ds_write_b128 v207, v[236:239] offset:49152
	s_waitcnt vmcnt(2)
	ds_write_b128 v207, v[240:243] offset:57344
	s_waitcnt vmcnt(1)
	ds_write_b128 v206, v[244:247]
	s_waitcnt vmcnt(0)
	ds_write_b128 v205, v[158:161]
	v_add_u32_e32 v158, 0x90, v164
	v_ashrrev_i32_e32 v159, 31, v158
	v_lshlrev_b64 v[158:159], 12, v[158:159]
	v_lshl_add_u64 v[158:159], s[0:1], 0, v[158:159]
	v_lshl_add_u64 v[172:173], v[158:159], 0, v[166:167]
	global_load_dwordx4 v[224:227], v[172:173], off
	global_load_dwordx4 v[228:231], v[172:173], off offset:256
	v_add_u32_e32 v158, 0xa0, v164
	v_ashrrev_i32_e32 v159, 31, v158
	v_lshlrev_b64 v[158:159], 12, v[158:159]
	v_lshl_add_u64 v[158:159], s[0:1], 0, v[158:159]
	v_lshl_add_u64 v[172:173], v[158:159], 0, v[166:167]
	global_load_dwordx4 v[232:235], v[172:173], off
	global_load_dwordx4 v[236:239], v[172:173], off offset:256
	v_add_u32_e32 v158, 0xb0, v164
	v_ashrrev_i32_e32 v159, 31, v158
	v_lshlrev_b64 v[158:159], 12, v[158:159]
	v_lshl_add_u64 v[158:159], s[0:1], 0, v[158:159]
	v_lshl_add_u64 v[164:165], v[158:159], 0, v[166:167]
	global_load_dwordx4 v[158:161], v[164:165], off
	v_pk_mul_f32 v[166:167], v[126:127], v[126:127]
	global_load_dwordx4 v[146:149], v[146:147], off offset:256
	ds_write_b128 v207, v[150:153]
	s_lshl_b32 s0, s22, 4
	s_add_i32 s4, s0, 0
	s_add_i32 s4, s4, 0x20000
	s_waitcnt vmcnt(1)
	ds_write_b128 v204, v[224:227]
	ds_write_b128 v203, v[228:231]
	ds_write_b128 v202, v[232:235]
	ds_write_b128 v201, v[236:239]
	ds_write_b128 v200, v[158:161]
	global_load_dwordx4 v[158:161], v[164:165], off offset:256
	v_pk_mul_f32 v[164:165], v[128:129], v[128:129]
	s_waitcnt vmcnt(1)
;     __device__ __forceinline__ void fused(f32x4 (&acc)[2][2][4][2], const Unit& u, int wr, int wc, int fr, int fq, PG8_LAS unsigned char* lds, int wid, int lane) const {
;     ...
;         for (int ai = 0; ai < 2; ++ai)
; #pragma unroll
;             for (int m = 0; m < 4; ++m) {
;                 float saa = 0.f, sxx = 0.f, sxag = 0.f, sgg = 0.f;
; #pragma unroll
;                 for (int bj = 0; bj < 2; ++bj) { const u32x4 w4 = XL[((ai * 4 + m) * 2 + bj) * 512];
; #pragma unroll
;                     for (int n = 0; n < 2; ++n) { const f32x4 a = acc[ai][bj][m][n]; const f32x4 ag = a * gv[bj][n]; const unsigned wx = n == 0 ? w4.x : w4.z, wy = n == 0 ? w4.y : w4.w;
;                         const f32x4 x = (f32x4){bflo(wx), bfhi(wx), bflo(wy), bfhi(wy)};
;                         saa += (a[0] * a[0] + a[1] * a[1]) + (a[2] * a[2] + a[3] * a[3]); sxx += (x[0] * x[0] + x[1] * x[1]) + (x[2] * x[2] + x[3] * x[3]);
;                         sxag += (x[0] * ag[0] + x[1] * ag[1]) + (x[2] * ag[2] + x[3] * ag[3]); sgg += (ag[0] * ag[0] + ag[1] * ag[1]) + (ag[2] * ag[2] + ag[3] * ag[3]); } }
;                 asm volatile("" : "+v"(saa), "+v"(sxx), "+v"(sxag), "+v"(sgg));
;                 saa += __shfl_xor(saa, 16); sxx += __shfl_xor(sxx, 16); sxag += __shfl_xor(sxag, 16); sgg += __shfl_xor(sgg, 16);
;                 saa += __shfl_xor(saa, 32); sxx += __shfl_xor(sxx, 32); sxag += __shfl_xor(sxag, 32); sgg += __shfl_xor(sgg, 32);
;                 if (fq == 0) P[(ai * HALF + wr * 64 + m * 16 + fr) * 4 + wc] = (f32x4){saa, sxx, sxag, sgg};
;                 __builtin_amdgcn_sched_barrier(0);
	v_lshlrev_b32_e32 v212, 16, v146
	v_pk_mov_b32 v[172:173], v[166:167], v[164:165] op_sel:[1,0]
	v_mov_b32_e32 v167, v165
	v_pk_add_f32 v[164:165], v[172:173], v[166:167]
	v_lshlrev_b32_e32 v166, 16, v150
	v_and_b32_e32 v173, 0xffff0000, v150
	v_and_b32_e32 v172, 16, v150
	v_mov_b32_e32 v167, v173
	v_mul_f32_e32 v150, v166, v166
	v_pk_fma_f32 v[174:175], v[166:167], v[166:167], v[150:151] op_sel_hi:[1,1,0]
	v_lshlrev_b32_e32 v150, 16, v151
	v_and_b32_e32 v151, 0xffff0000, v151
	v_mul_f32_e32 v162, v150, v150
	v_mov_b32_e32 v167, v151
	v_pk_fma_f32 v[180:181], v[150:151], v[150:151], v[162:163] op_sel_hi:[1,1,0]
	v_pk_mov_b32 v[172:173], v[172:173], v[150:151] op_sel:[1,0]
	ds_write_b128 v207, v[146:149] offset:8192
	v_and_b32_e32 v213, 0xffff0000, v146
	v_mul_f32_e32 v146, v212, v212
	v_pk_fma_f32 v[214:215], v[212:213], v[212:213], v[146:147] op_sel_hi:[1,1,0]
	v_lshlrev_b32_e32 v146, 16, v147
	v_and_b32_e32 v147, 0xffff0000, v147
	v_pk_add_f32 v[164:165], v[164:165], v[164:165] op_sel_hi:[0,1]
	v_lshlrev_b32_e32 v222, 16, v148
	v_lshlrev_b32_e32 v157, 16, v149
	v_and_b32_e32 v162, 0xffff0000, v149
	v_mul_f32_e32 v164, v117, v117
	v_mov_b32_e32 v223, v175
	v_mul_f32_e32 v214, v157, v157
	s_waitcnt vmcnt(0)
	ds_write_b128 v0, v[158:161]
	v_pk_mul_f32 v[158:159], v[128:129], v[144:145]
	v_pk_mul_f32 v[160:161], v[126:127], v[142:143]
	v_mov_b32_e32 v185, v159
	v_mov_b32_e32 v184, v160
	v_pk_mov_b32 v[182:183], v[160:161], v[158:159] op_sel:[1,0]
	v_pk_mul_f32 v[150:151], v[184:185], v[166:167]
	v_pk_mul_f32 v[158:159], v[158:159], v[158:159]
	v_pk_mul_f32 v[160:161], v[160:161], v[160:161]
	v_pk_fma_f32 v[150:151], v[182:183], v[172:173], v[150:151]
	v_pk_mov_b32 v[166:167], v[160:161], v[158:159] op_sel:[1,0]
	v_mov_b32_e32 v161, v159
	v_pk_mul_f32 v[172:173], v[124:125], v[124:125]
	v_pk_mul_f32 v[182:183], v[122:123], v[122:123]
	v_pk_add_f32 v[158:159], v[166:167], v[160:161]
	v_pk_mul_f32 v[160:161], v[124:125], v[140:141]
	v_pk_mul_f32 v[166:167], v[122:123], v[138:139]
	v_pk_mov_b32 v[184:185], v[182:183], v[172:173] op_sel:[1,0]
	v_mov_b32_e32 v183, v173
	v_add_f32_e32 v150, v150, v151
	v_pk_add_f32 v[172:173], v[184:185], v[182:183]
	v_lshlrev_b32_e32 v183, 16, v153
	v_lshlrev_b32_e32 v182, 16, v152
	v_and_b32_e32 v153, 0xffff0000, v153
	v_and_b32_e32 v152, 0xffff0000, v152
	v_mov_b32_e32 v210, v167
	v_mov_b32_e32 v211, v161
	v_add_f32_e32 v151, 0, v150
	v_pk_mul_f32 v[184:185], v[152:153], v[152:153]
	v_mov_b32_e32 v208, v166
	v_mov_b32_e32 v209, v160
	v_pk_mul_f32 v[152:153], v[210:211], v[152:153]
	v_pk_mul_f32 v[160:161], v[160:161], v[160:161]
	v_pk_mul_f32 v[166:167], v[166:167], v[166:167]
	v_mul_f32_e32 v150, v118, v118
	v_pk_fma_f32 v[184:185], v[182:183], v[182:183], v[184:185]
	v_pk_fma_f32 v[152:153], v[208:209], v[182:183], v[152:153]
	v_pk_mov_b32 v[182:183], v[166:167], v[160:161] op_sel:[1,0]
	v_mov_b32_e32 v167, v161
	v_pk_fma_f32 v[208:209], v[118:119], v[118:119], v[150:151] op_sel_hi:[1,1,0]
	v_mul_f32_e32 v150, v120, v120
	v_pk_add_f32 v[160:161], v[182:183], v[166:167]
	v_pk_mul_f32 v[182:183], v[118:119], v[134:135]
	v_pk_fma_f32 v[210:211], v[120:121], v[120:121], v[150:151] op_sel_hi:[1,1,0]
	v_mul_f32_e32 v150, v146, v146
	v_pk_mul_f32 v[166:167], v[120:121], v[136:137]
	v_pk_fma_f32 v[216:217], v[146:147], v[146:147], v[150:151] op_sel_hi:[1,1,0]
	v_mul_f32_e32 v150, v182, v212
	v_pk_fma_f32 v[212:213], v[182:183], v[212:213], v[150:151] op_sel_hi:[1,1,0]
	v_mul_f32_e32 v150, v166, v146
	v_pk_add_f32 v[172:173], v[172:173], v[172:173] op_sel_hi:[0,1]
	v_pk_fma_f32 v[146:147], v[166:167], v[146:147], v[150:151] op_sel_hi:[1,1,0]
	v_pk_add_f32 v[184:185], v[184:185], v[184:185] op_sel_hi:[0,1]
	v_pk_add_f32 v[152:153], v[152:153], v[152:153] op_sel_hi:[0,1]
	v_and_b32_e32 v146, 0xffff0000, v148
	v_mul_f32_e32 v208, v114, v114
	v_mul_f32_e32 v210, v115, v115
	v_mul_f32_e32 v172, v116, v116
	v_pk_add_f32 v[148:149], v[208:209], v[210:211]
	v_pk_add_f32 v[164:165], v[172:173], v[164:165]
	v_mul_f32_e32 v184, v146, v146
	v_mul_f32_e32 v152, v220, v222
	v_mul_f32_e32 v150, v221, v146
	v_mul_f32_e32 v212, v218, v157
	v_mul_f32_e32 v146, v219, v162
	v_pk_add_f32 v[148:149], v[148:149], v[164:165]
	v_mov_b32_e32 v164, v222
	v_mov_b32_e32 v165, v181
	v_pk_add_f32 v[150:151], v[152:153], v[150:151]
	v_pk_add_f32 v[146:147], v[212:213], v[146:147]
	v_pk_mul_f32 v[164:165], v[222:223], v[164:165]
	v_pk_add_f32 v[172:173], v[174:175], v[180:181]
	v_pk_add_f32 v[146:147], v[150:151], v[146:147]
	v_mul_f32_e32 v216, v162, v162
	v_mov_b32_e32 v165, v173
	v_add_f32_e32 v150, v146, v147
	v_mul_f32_e32 v151, v220, v220
	v_mul_f32_e32 v157, v221, v221
	v_pk_add_f32 v[146:147], v[158:159], v[158:159] op_sel:[0,1] op_sel_hi:[1,0]
	v_pk_add_f32 v[152:153], v[160:161], v[160:161] op_sel:[0,1] op_sel_hi:[1,0]
	v_pk_add_f32 v[164:165], v[164:165], v[184:185]
	v_pk_add_f32 v[172:173], v[214:215], v[216:217]
	v_mov_b32_e32 v147, v151
	v_mov_b32_e32 v153, v157
	v_pk_add_f32 v[164:165], v[164:165], v[172:173]
	v_pk_add_f32 v[146:147], v[146:147], v[152:153]
	v_mul_f32_e32 v152, v183, v183
	v_mul_f32_e32 v158, v167, v167
	v_add_f32_e32 v148, v148, v149
	v_add_f32_e32 v149, v164, v165
	v_mul_f32_e32 v162, v218, v218
	v_mul_f32_e32 v164, v219, v219
	v_pk_fma_f32 v[152:153], v[182:183], v[182:183], v[152:153] op_sel_hi:[1,1,0]
	v_pk_fma_f32 v[158:159], v[166:167], v[166:167], v[158:159] op_sel_hi:[1,1,0]
	v_mov_b32_e32 v153, v162
	v_mov_b32_e32 v159, v164
	v_pk_add_f32 v[152:153], v[152:153], v[158:159]
	s_nop 0
	v_pk_add_f32 v[146:147], v[146:147], v[152:153]
	s_nop 0
	v_add_f32_e32 v151, v146, v147
	v_mov_b32_e32 v146, v148
	s_nop 1
	v_permlane16_swap_b32_e32 v148, v146
	v_mov_b32_e32 v147, v149
	s_nop 1
	v_permlane16_swap_b32_e32 v149, v147
	s_waitcnt lgkmcnt(0)
	v_pk_add_f32 v[146:147], v[148:149], v[146:147]
	v_mov_b32_e32 v148, v150
	s_nop 1
	v_permlane16_swap_b32_e32 v150, v148
	v_mov_b32_e32 v149, v151
	s_nop 1
	v_permlane16_swap_b32_e32 v151, v149
	s_waitcnt lgkmcnt(0)
	v_pk_add_f32 v[150:151], v[150:151], v[148:149]
	v_mov_b32_e32 v148, v146
	s_nop 1
	v_permlane32_swap_b32_e32 v146, v148
	v_mov_b32_e32 v149, v147
	s_nop 1
	v_permlane32_swap_b32_e32 v147, v149
	v_mov_b32_e32 v152, v150
	s_nop 1
	v_permlane32_swap_b32_e32 v150, v152
	v_mov_b32_e32 v153, v151
	s_nop 1
	v_permlane32_swap_b32_e32 v151, v153
	s_and_saveexec_b64 s[0:1], vcc
	s_cbranch_execz .LBB0_1073
	s_lshl_b32 s5, s19, 12
	s_add_i32 s5, s4, s5
	s_waitcnt lgkmcnt(0)
	v_pk_add_f32 v[150:151], v[150:151], v[152:153]
	v_pk_add_f32 v[148:149], v[146:147], v[148:149]
	v_add_u32_e32 v146, s5, v155
	ds_write_b128 v146, v[148:151]
;     __device__ __forceinline__ void fused(f32x4 (&acc)[2][2][4][2], const Unit& u, int wr, int wc, int fr, int fq, PG8_LAS unsigned char* lds, int wid, int lane) const {
;     ...
;         for (int ai = 0; ai < 2; ++ai)
; #pragma unroll
;             for (int m = 0; m < 4; ++m) {
;                 float saa = 0.f, sxx = 0.f, sxag = 0.f, sgg = 0.f;
; #pragma unroll
;                 for (int bj = 0; bj < 2; ++bj) { const u32x4 w4 = XL[((ai * 4 + m) * 2 + bj) * 512];
; #pragma unroll
;                     for (int n = 0; n < 2; ++n) { const f32x4 a = acc[ai][bj][m][n]; const f32x4 ag = a * gv[bj][n]; const unsigned wx = n == 0 ? w4.x : w4.z, wy = n == 0 ? w4.y : w4.w;
;                         const f32x4 x = (f32x4){bflo(wx), bfhi(wx), bflo(wy), bfhi(wy)};
;                         saa += (a[0] * a[0] + a[1] * a[1]) + (a[2] * a[2] + a[3] * a[3]); sxx += (x[0] * x[0] + x[1] * x[1]) + (x[2] * x[2] + x[3] * x[3]);
;                         sxag += (x[0] * ag[0] + x[1] * ag[1]) + (x[2] * ag[2] + x[3] * ag[3]); sgg += (ag[0] * ag[0] + ag[1] * ag[1]) + (ag[2] * ag[2] + ag[3] * ag[3]); } }
;                 asm volatile("" : "+v"(saa), "+v"(sxx), "+v"(sxag), "+v"(sgg));
;                 saa += __shfl_xor(saa, 16); sxx += __shfl_xor(sxx, 16); sxag += __shfl_xor(sxag, 16); sgg += __shfl_xor(sgg, 16);
;                 saa += __shfl_xor(saa, 32); sxx += __shfl_xor(sxx, 32); sxag += __shfl_xor(sxag, 32); sgg += __shfl_xor(sgg, 32);
;                 if (fq == 0) P[(ai * HALF + wr * 64 + m * 16 + fr) * 4 + wc] = (f32x4){saa, sxx, sxag, sgg};
;                 __builtin_amdgcn_sched_barrier(0);
.LBB0_1073:
	s_or_b64 exec, exec, s[0:1]
	s_waitcnt lgkmcnt(0)
	ds_read_b128 v[146:149], v207 offset:16384
	v_pk_mul_f32 v[150:151], v[112:113], v[112:113]
	s_waitcnt lgkmcnt(0)
	v_pk_mul_f32 v[152:153], v[110:111], v[110:111]
	v_pk_mul_f32 v[158:159], v[112:113], v[144:145]
	v_pk_mov_b32 v[164:165], v[152:153], v[150:151] op_sel:[1,0]
	v_mov_b32_e32 v153, v151
	v_pk_add_f32 v[150:151], v[164:165], v[152:153]
	v_pk_mul_f32 v[160:161], v[110:111], v[142:143]
	v_pk_add_f32 v[164:165], v[150:151], v[150:151] op_sel_hi:[0,1]
	ds_read_b128 v[150:153], v207 offset:24576
	s_waitcnt lgkmcnt(0)
	v_lshlrev_b32_e32 v166, 16, v146
	v_and_b32_e32 v173, 0xffff0000, v146
	v_and_b32_e32 v172, 16, v146
	v_mov_b32_e32 v167, v173
	v_mul_f32_e32 v146, v166, v166
	v_pk_fma_f32 v[174:175], v[166:167], v[166:167], v[146:147] op_sel_hi:[1,1,0]
	v_lshlrev_b32_e32 v146, 16, v147
	v_and_b32_e32 v147, 0xffff0000, v147
	v_mul_f32_e32 v162, v146, v146
	v_mov_b32_e32 v184, v160
	v_mov_b32_e32 v185, v159
	v_mov_b32_e32 v167, v147
	v_pk_fma_f32 v[180:181], v[146:147], v[146:147], v[162:163] op_sel_hi:[1,1,0]
	v_pk_mov_b32 v[182:183], v[160:161], v[158:159] op_sel:[1,0]
	v_pk_mov_b32 v[172:173], v[172:173], v[146:147] op_sel:[1,0]
	v_pk_mul_f32 v[146:147], v[184:185], v[166:167]
	v_pk_mul_f32 v[158:159], v[158:159], v[158:159]
	v_pk_mul_f32 v[160:161], v[160:161], v[160:161]
	v_pk_fma_f32 v[146:147], v[182:183], v[172:173], v[146:147]
	v_pk_mov_b32 v[166:167], v[160:161], v[158:159] op_sel:[1,0]
	v_mov_b32_e32 v161, v159
	v_pk_mul_f32 v[172:173], v[108:109], v[108:109]
	v_pk_mul_f32 v[182:183], v[106:107], v[106:107]
	v_pk_add_f32 v[158:159], v[166:167], v[160:161]
	v_pk_mul_f32 v[160:161], v[108:109], v[140:141]
	v_pk_mul_f32 v[166:167], v[106:107], v[138:139]
	v_pk_mov_b32 v[184:185], v[182:183], v[172:173] op_sel:[1,0]
	v_mov_b32_e32 v183, v173
	v_add_f32_e32 v146, v146, v147
	v_pk_add_f32 v[172:173], v[184:185], v[182:183]
	v_lshlrev_b32_e32 v183, 16, v149
	v_lshlrev_b32_e32 v182, 16, v148
	v_and_b32_e32 v149, 0xffff0000, v149
	v_and_b32_e32 v148, 0xffff0000, v148
	v_mov_b32_e32 v210, v167
	v_mov_b32_e32 v211, v161
	v_add_f32_e32 v147, 0, v146
	v_pk_mul_f32 v[184:185], v[148:149], v[148:149]
	v_mov_b32_e32 v208, v166
	v_mov_b32_e32 v209, v160
	v_pk_mul_f32 v[148:149], v[210:211], v[148:149]
	v_mul_f32_e32 v146, v102, v102
	v_pk_fma_f32 v[148:149], v[208:209], v[182:183], v[148:149]
	v_pk_mul_f32 v[160:161], v[160:161], v[160:161]
	v_pk_mul_f32 v[166:167], v[166:167], v[166:167]
	v_pk_fma_f32 v[208:209], v[102:103], v[102:103], v[146:147] op_sel_hi:[1,1,0]
	v_mul_f32_e32 v146, v104, v104
	s_waitcnt lgkmcnt(0)
	v_lshlrev_b32_e32 v212, 16, v150
	v_pk_fma_f32 v[184:185], v[182:183], v[182:183], v[184:185]
	v_pk_mov_b32 v[182:183], v[166:167], v[160:161] op_sel:[1,0]
	v_mov_b32_e32 v167, v161
	v_pk_fma_f32 v[210:211], v[104:105], v[104:105], v[146:147] op_sel_hi:[1,1,0]
	v_and_b32_e32 v213, 0xffff0000, v150
	v_mul_f32_e32 v146, v212, v212
	v_lshlrev_b32_e32 v150, 16, v151
	v_pk_add_f32 v[160:161], v[182:183], v[166:167]
	v_pk_mul_f32 v[182:183], v[102:103], v[134:135]
	v_pk_fma_f32 v[214:215], v[212:213], v[212:213], v[146:147] op_sel_hi:[1,1,0]
	v_and_b32_e32 v151, 0xffff0000, v151
	v_mul_f32_e32 v146, v150, v150
	v_pk_mul_f32 v[166:167], v[104:105], v[136:137]
	v_pk_fma_f32 v[216:217], v[150:151], v[150:151], v[146:147] op_sel_hi:[1,1,0]
	v_mul_f32_e32 v146, v182, v212
	v_pk_add_f32 v[172:173], v[172:173], v[172:173] op_sel_hi:[0,1]
	v_pk_add_f32 v[148:149], v[148:149], v[148:149] op_sel_hi:[0,1]
	v_pk_fma_f32 v[212:213], v[182:183], v[212:213], v[146:147] op_sel_hi:[1,1,0]
	v_mul_f32_e32 v146, v166, v150
	v_pk_add_f32 v[184:185], v[184:185], v[184:185] op_sel_hi:[0,1]
	v_pk_fma_f32 v[150:151], v[166:167], v[150:151], v[146:147] op_sel_hi:[1,1,0]
	v_pk_mul_f32 v[218:219], v[100:101], v[132:133]
	v_pk_mul_f32 v[220:221], v[98:99], v[130:131]
	v_lshlrev_b32_e32 v222, 16, v152
	v_and_b32_e32 v146, 0xffff0000, v152
	v_lshlrev_b32_e32 v148, 16, v153
	v_and_b32_e32 v157, 0xffff0000, v153
	v_mul_f32_e32 v208, v98, v98
	v_mul_f32_e32 v210, v99, v99
	v_mul_f32_e32 v172, v100, v100
	v_mul_f32_e32 v164, v101, v101
	v_pk_add_f32 v[152:153], v[208:209], v[210:211]
	v_pk_add_f32 v[164:165], v[172:173], v[164:165]
	v_mul_f32_e32 v184, v146, v146
	v_mul_f32_e32 v214, v148, v148
	v_mul_f32_e32 v212, v220, v222
	v_mul_f32_e32 v150, v221, v146
	v_mul_f32_e32 v148, v218, v148
	v_mul_f32_e32 v146, v219, v157
	v_pk_add_f32 v[152:153], v[152:153], v[164:165]
	v_mov_b32_e32 v223, v175
	v_mov_b32_e32 v164, v222
	v_mov_b32_e32 v165, v181
	v_pk_add_f32 v[150:151], v[212:213], v[150:151]
	v_pk_add_f32 v[146:147], v[148:149], v[146:147]
	v_pk_mul_f32 v[164:165], v[222:223], v[164:165]
	v_pk_add_f32 v[172:173], v[174:175], v[180:181]
	v_pk_add_f32 v[146:147], v[150:151], v[146:147]
	v_mul_f32_e32 v216, v157, v157
	v_mov_b32_e32 v165, v173
	v_add_f32_e32 v148, v146, v147
	v_mul_f32_e32 v149, v220, v220
	v_mul_f32_e32 v157, v221, v221
	v_pk_add_f32 v[146:147], v[158:159], v[158:159] op_sel:[0,1] op_sel_hi:[1,0]
	v_pk_add_f32 v[150:151], v[160:161], v[160:161] op_sel:[0,1] op_sel_hi:[1,0]
	v_pk_add_f32 v[164:165], v[164:165], v[184:185]
	v_pk_add_f32 v[172:173], v[214:215], v[216:217]
	v_mov_b32_e32 v147, v149
	v_mov_b32_e32 v151, v157
	v_pk_add_f32 v[164:165], v[164:165], v[172:173]
	v_pk_add_f32 v[146:147], v[146:147], v[150:151]
	v_mul_f32_e32 v150, v183, v183
	v_mul_f32_e32 v158, v167, v167
	v_add_f32_e32 v152, v152, v153
	v_add_f32_e32 v153, v164, v165
	v_mul_f32_e32 v162, v218, v218
	v_mul_f32_e32 v164, v219, v219
	v_pk_fma_f32 v[150:151], v[182:183], v[182:183], v[150:151] op_sel_hi:[1,1,0]
	v_pk_fma_f32 v[158:159], v[166:167], v[166:167], v[158:159] op_sel_hi:[1,1,0]
	v_mov_b32_e32 v151, v162
	v_mov_b32_e32 v159, v164
	v_pk_add_f32 v[150:151], v[150:151], v[158:159]
	s_nop 0
	v_pk_add_f32 v[146:147], v[146:147], v[150:151]
	s_nop 0
	v_add_f32_e32 v149, v146, v147
	v_mov_b32_e32 v146, v152
	s_nop 1
	v_permlane16_swap_b32_e32 v152, v146
	v_mov_b32_e32 v147, v153
	s_nop 1
	v_permlane16_swap_b32_e32 v153, v147
	v_mov_b32_e32 v150, v148
	s_nop 1
	v_permlane16_swap_b32_e32 v148, v150
	v_mov_b32_e32 v151, v149
	s_nop 1
	v_permlane16_swap_b32_e32 v149, v151
	s_waitcnt lgkmcnt(0)
	v_pk_add_f32 v[146:147], v[152:153], v[146:147]
	s_waitcnt lgkmcnt(0)
	v_pk_add_f32 v[150:151], v[148:149], v[150:151]
	v_mov_b32_e32 v148, v146
	s_nop 1
	v_permlane32_swap_b32_e32 v146, v148
	v_mov_b32_e32 v149, v147
	s_nop 1
	v_permlane32_swap_b32_e32 v147, v149
	v_mov_b32_e32 v152, v150
	s_nop 1
	v_permlane32_swap_b32_e32 v150, v152
	v_mov_b32_e32 v153, v151
	s_nop 1
	v_permlane32_swap_b32_e32 v151, v153
	s_and_saveexec_b64 s[0:1], vcc
	s_cbranch_execz .LBB0_1075
	s_lshl_b32 s5, s19, 12
	s_add_i32 s5, s4, s5
	s_waitcnt lgkmcnt(0)
	v_pk_add_f32 v[150:151], v[150:151], v[152:153]
	v_pk_add_f32 v[148:149], v[146:147], v[148:149]
	v_add_u32_e32 v146, s5, v155
	ds_write_b128 v146, v[148:151] offset:1024
;     __device__ __forceinline__ void fused(f32x4 (&acc)[2][2][4][2], const Unit& u, int wr, int wc, int fr, int fq, PG8_LAS unsigned char* lds, int wid, int lane) const {
;     ...
;         for (int ai = 0; ai < 2; ++ai)
; #pragma unroll
;             for (int m = 0; m < 4; ++m) {
;                 float saa = 0.f, sxx = 0.f, sxag = 0.f, sgg = 0.f;
; #pragma unroll
;                 for (int bj = 0; bj < 2; ++bj) { const u32x4 w4 = XL[((ai * 4 + m) * 2 + bj) * 512];
; #pragma unroll
;                     for (int n = 0; n < 2; ++n) { const f32x4 a = acc[ai][bj][m][n]; const f32x4 ag = a * gv[bj][n]; const unsigned wx = n == 0 ? w4.x : w4.z, wy = n == 0 ? w4.y : w4.w;
;                         const f32x4 x = (f32x4){bflo(wx), bfhi(wx), bflo(wy), bfhi(wy)};
;                         saa += (a[0] * a[0] + a[1] * a[1]) + (a[2] * a[2] + a[3] * a[3]); sxx += (x[0] * x[0] + x[1] * x[1]) + (x[2] * x[2] + x[3] * x[3]);
;                         sxag += (x[0] * ag[0] + x[1] * ag[1]) + (x[2] * ag[2] + x[3] * ag[3]); sgg += (ag[0] * ag[0] + ag[1] * ag[1]) + (ag[2] * ag[2] + ag[3] * ag[3]); } }
;                 asm volatile("" : "+v"(saa), "+v"(sxx), "+v"(sxag), "+v"(sgg));
;                 saa += __shfl_xor(saa, 16); sxx += __shfl_xor(sxx, 16); sxag += __shfl_xor(sxag, 16); sgg += __shfl_xor(sgg, 16);
;                 saa += __shfl_xor(saa, 32); sxx += __shfl_xor(sxx, 32); sxag += __shfl_xor(sxag, 32); sgg += __shfl_xor(sgg, 32);
;                 if (fq == 0) P[(ai * HALF + wr * 64 + m * 16 + fr) * 4 + wc] = (f32x4){saa, sxx, sxag, sgg};
;                 __builtin_amdgcn_sched_barrier(0);
.LBB0_1075:
	s_or_b64 exec, exec, s[0:1]
	s_waitcnt lgkmcnt(0)
	ds_read_b128 v[146:149], v207 offset:32768
	v_pk_mul_f32 v[150:151], v[96:97], v[96:97]
	s_waitcnt lgkmcnt(0)
	v_pk_mul_f32 v[152:153], v[94:95], v[94:95]
	v_pk_mul_f32 v[158:159], v[96:97], v[144:145]
	v_pk_mov_b32 v[164:165], v[152:153], v[150:151] op_sel:[1,0]
	v_mov_b32_e32 v153, v151
	v_pk_add_f32 v[150:151], v[164:165], v[152:153]
	v_pk_mul_f32 v[160:161], v[94:95], v[142:143]
	v_pk_add_f32 v[164:165], v[150:151], v[150:151] op_sel_hi:[0,1]
	ds_read_b128 v[150:153], v207 offset:40960
	s_waitcnt lgkmcnt(0)
	v_lshlrev_b32_e32 v166, 16, v146
	v_and_b32_e32 v173, 0xffff0000, v146
	v_and_b32_e32 v172, 16, v146
	v_mov_b32_e32 v167, v173
	v_mul_f32_e32 v146, v166, v166
	v_pk_fma_f32 v[174:175], v[166:167], v[166:167], v[146:147] op_sel_hi:[1,1,0]
	v_lshlrev_b32_e32 v146, 16, v147
	v_and_b32_e32 v147, 0xffff0000, v147
	v_mul_f32_e32 v162, v146, v146
	v_mov_b32_e32 v184, v160
	v_mov_b32_e32 v185, v159
	v_mov_b32_e32 v167, v147
	v_pk_fma_f32 v[180:181], v[146:147], v[146:147], v[162:163] op_sel_hi:[1,1,0]
	v_pk_mov_b32 v[182:183], v[160:161], v[158:159] op_sel:[1,0]
	v_pk_mov_b32 v[172:173], v[172:173], v[146:147] op_sel:[1,0]
	v_pk_mul_f32 v[146:147], v[184:185], v[166:167]
	v_pk_mul_f32 v[158:159], v[158:159], v[158:159]
	v_pk_mul_f32 v[160:161], v[160:161], v[160:161]
	v_pk_fma_f32 v[146:147], v[182:183], v[172:173], v[146:147]
	v_pk_mov_b32 v[166:167], v[160:161], v[158:159] op_sel:[1,0]
	v_mov_b32_e32 v161, v159
	v_pk_mul_f32 v[172:173], v[92:93], v[92:93]
	v_pk_mul_f32 v[182:183], v[90:91], v[90:91]
	v_pk_add_f32 v[158:159], v[166:167], v[160:161]
	v_pk_mul_f32 v[160:161], v[92:93], v[140:141]
	v_pk_mul_f32 v[166:167], v[90:91], v[138:139]
	v_pk_mov_b32 v[184:185], v[182:183], v[172:173] op_sel:[1,0]
	v_mov_b32_e32 v183, v173
	v_add_f32_e32 v146, v146, v147
	v_pk_add_f32 v[172:173], v[184:185], v[182:183]
	v_lshlrev_b32_e32 v183, 16, v149
	v_lshlrev_b32_e32 v182, 16, v148
	v_and_b32_e32 v149, 0xffff0000, v149
	v_and_b32_e32 v148, 0xffff0000, v148
	v_mov_b32_e32 v210, v167
	v_mov_b32_e32 v211, v161
	v_add_f32_e32 v147, 0, v146
	v_pk_mul_f32 v[184:185], v[148:149], v[148:149]
	v_mov_b32_e32 v208, v166
	v_mov_b32_e32 v209, v160
	v_pk_mul_f32 v[148:149], v[210:211], v[148:149]
	v_mul_f32_e32 v146, v86, v86
	v_pk_fma_f32 v[148:149], v[208:209], v[182:183], v[148:149]
	v_pk_mul_f32 v[160:161], v[160:161], v[160:161]
	v_pk_mul_f32 v[166:167], v[166:167], v[166:167]
	v_pk_fma_f32 v[208:209], v[86:87], v[86:87], v[146:147] op_sel_hi:[1,1,0]
	v_mul_f32_e32 v146, v88, v88
	s_waitcnt lgkmcnt(0)
	v_lshlrev_b32_e32 v212, 16, v150
	v_pk_fma_f32 v[184:185], v[182:183], v[182:183], v[184:185]
	v_pk_mov_b32 v[182:183], v[166:167], v[160:161] op_sel:[1,0]
	v_mov_b32_e32 v167, v161
	v_pk_fma_f32 v[210:211], v[88:89], v[88:89], v[146:147] op_sel_hi:[1,1,0]
	v_and_b32_e32 v213, 0xffff0000, v150
	v_mul_f32_e32 v146, v212, v212
	v_lshlrev_b32_e32 v150, 16, v151
	v_pk_add_f32 v[160:161], v[182:183], v[166:167]
	v_pk_mul_f32 v[182:183], v[86:87], v[134:135]
	v_pk_fma_f32 v[214:215], v[212:213], v[212:213], v[146:147] op_sel_hi:[1,1,0]
	v_and_b32_e32 v151, 0xffff0000, v151
	v_mul_f32_e32 v146, v150, v150
	v_pk_mul_f32 v[166:167], v[88:89], v[136:137]
	v_pk_fma_f32 v[216:217], v[150:151], v[150:151], v[146:147] op_sel_hi:[1,1,0]
	v_mul_f32_e32 v146, v182, v212
	v_pk_add_f32 v[172:173], v[172:173], v[172:173] op_sel_hi:[0,1]
	v_pk_add_f32 v[148:149], v[148:149], v[148:149] op_sel_hi:[0,1]
	v_pk_fma_f32 v[212:213], v[182:183], v[212:213], v[146:147] op_sel_hi:[1,1,0]
	v_mul_f32_e32 v146, v166, v150
	v_pk_add_f32 v[184:185], v[184:185], v[184:185] op_sel_hi:[0,1]
	v_pk_fma_f32 v[150:151], v[166:167], v[150:151], v[146:147] op_sel_hi:[1,1,0]
	v_pk_mul_f32 v[218:219], v[84:85], v[132:133]
	v_pk_mul_f32 v[220:221], v[82:83], v[130:131]
	v_lshlrev_b32_e32 v222, 16, v152
	v_and_b32_e32 v146, 0xffff0000, v152
	v_lshlrev_b32_e32 v148, 16, v153
	v_and_b32_e32 v157, 0xffff0000, v153
	v_mul_f32_e32 v208, v82, v82
	v_mul_f32_e32 v210, v83, v83
	v_mul_f32_e32 v172, v84, v84
	v_mul_f32_e32 v164, v85, v85
	v_pk_add_f32 v[152:153], v[208:209], v[210:211]
	v_pk_add_f32 v[164:165], v[172:173], v[164:165]
	v_mul_f32_e32 v184, v146, v146
	v_mul_f32_e32 v214, v148, v148
	v_mul_f32_e32 v212, v220, v222
	v_mul_f32_e32 v150, v221, v146
	v_mul_f32_e32 v148, v218, v148
	v_mul_f32_e32 v146, v219, v157
	v_pk_add_f32 v[152:153], v[152:153], v[164:165]
	v_mov_b32_e32 v223, v175
	v_mov_b32_e32 v164, v222
	v_mov_b32_e32 v165, v181
	v_pk_add_f32 v[150:151], v[212:213], v[150:151]
	v_pk_add_f32 v[146:147], v[148:149], v[146:147]
	v_pk_mul_f32 v[164:165], v[222:223], v[164:165]
	v_pk_add_f32 v[172:173], v[174:175], v[180:181]
	v_pk_add_f32 v[146:147], v[150:151], v[146:147]
	v_mul_f32_e32 v216, v157, v157
	v_mov_b32_e32 v165, v173
	v_add_f32_e32 v148, v146, v147
	v_mul_f32_e32 v149, v220, v220
	v_mul_f32_e32 v157, v221, v221
	v_pk_add_f32 v[146:147], v[158:159], v[158:159] op_sel:[0,1] op_sel_hi:[1,0]
	v_pk_add_f32 v[150:151], v[160:161], v[160:161] op_sel:[0,1] op_sel_hi:[1,0]
	v_pk_add_f32 v[164:165], v[164:165], v[184:185]
	v_pk_add_f32 v[172:173], v[214:215], v[216:217]
	v_mov_b32_e32 v147, v149
	v_mov_b32_e32 v151, v157
	v_pk_add_f32 v[164:165], v[164:165], v[172:173]
	v_pk_add_f32 v[146:147], v[146:147], v[150:151]
	v_mul_f32_e32 v150, v183, v183
	v_mul_f32_e32 v158, v167, v167
	v_add_f32_e32 v152, v152, v153
	v_add_f32_e32 v153, v164, v165
	v_mul_f32_e32 v162, v218, v218
	v_mul_f32_e32 v164, v219, v219
	v_pk_fma_f32 v[150:151], v[182:183], v[182:183], v[150:151] op_sel_hi:[1,1,0]
	v_pk_fma_f32 v[158:159], v[166:167], v[166:167], v[158:159] op_sel_hi:[1,1,0]
	v_mov_b32_e32 v151, v162
	v_mov_b32_e32 v159, v164
	v_pk_add_f32 v[150:151], v[150:151], v[158:159]
	s_nop 0
	v_pk_add_f32 v[146:147], v[146:147], v[150:151]
	s_nop 0
	v_add_f32_e32 v149, v146, v147
	v_mov_b32_e32 v146, v152
	s_nop 1
	v_permlane16_swap_b32_e32 v152, v146
	v_mov_b32_e32 v147, v153
	s_nop 1
	v_permlane16_swap_b32_e32 v153, v147
	v_mov_b32_e32 v150, v148
	s_nop 1
	v_permlane16_swap_b32_e32 v148, v150
	v_mov_b32_e32 v151, v149
	s_nop 1
	v_permlane16_swap_b32_e32 v149, v151
	s_waitcnt lgkmcnt(0)
	v_pk_add_f32 v[146:147], v[152:153], v[146:147]
	s_waitcnt lgkmcnt(0)
	v_pk_add_f32 v[150:151], v[148:149], v[150:151]
	v_mov_b32_e32 v148, v146
	s_nop 1
	v_permlane32_swap_b32_e32 v146, v148
	v_mov_b32_e32 v149, v147
	s_nop 1
	v_permlane32_swap_b32_e32 v147, v149
	v_mov_b32_e32 v152, v150
	s_nop 1
	v_permlane32_swap_b32_e32 v150, v152
	v_mov_b32_e32 v153, v151
	s_nop 1
	v_permlane32_swap_b32_e32 v151, v153
	s_and_saveexec_b64 s[0:1], vcc
	s_cbranch_execz .LBB0_1077
	s_lshl_b32 s5, s19, 12
	s_add_i32 s5, s4, s5
	s_waitcnt lgkmcnt(0)
	v_pk_add_f32 v[150:151], v[150:151], v[152:153]
	v_pk_add_f32 v[148:149], v[146:147], v[148:149]
	v_add_u32_e32 v146, s5, v155
	ds_write_b128 v146, v[148:151] offset:2048
;     __device__ __forceinline__ void fused(f32x4 (&acc)[2][2][4][2], const Unit& u, int wr, int wc, int fr, int fq, PG8_LAS unsigned char* lds, int wid, int lane) const {
;     ...
;         for (int ai = 0; ai < 2; ++ai)
; #pragma unroll
;             for (int m = 0; m < 4; ++m) {
;                 float saa = 0.f, sxx = 0.f, sxag = 0.f, sgg = 0.f;
; #pragma unroll
;                 for (int bj = 0; bj < 2; ++bj) { const u32x4 w4 = XL[((ai * 4 + m) * 2 + bj) * 512];
; #pragma unroll
;                     for (int n = 0; n < 2; ++n) { const f32x4 a = acc[ai][bj][m][n]; const f32x4 ag = a * gv[bj][n]; const unsigned wx = n == 0 ? w4.x : w4.z, wy = n == 0 ? w4.y : w4.w;
;                         const f32x4 x = (f32x4){bflo(wx), bfhi(wx), bflo(wy), bfhi(wy)};
;                         saa += (a[0] * a[0] + a[1] * a[1]) + (a[2] * a[2] + a[3] * a[3]); sxx += (x[0] * x[0] + x[1] * x[1]) + (x[2] * x[2] + x[3] * x[3]);
;                         sxag += (x[0] * ag[0] + x[1] * ag[1]) + (x[2] * ag[2] + x[3] * ag[3]); sgg += (ag[0] * ag[0] + ag[1] * ag[1]) + (ag[2] * ag[2] + ag[3] * ag[3]); } }
;                 asm volatile("" : "+v"(saa), "+v"(sxx), "+v"(sxag), "+v"(sgg));
;                 saa += __shfl_xor(saa, 16); sxx += __shfl_xor(sxx, 16); sxag += __shfl_xor(sxag, 16); sgg += __shfl_xor(sgg, 16);
;                 saa += __shfl_xor(saa, 32); sxx += __shfl_xor(sxx, 32); sxag += __shfl_xor(sxag, 32); sgg += __shfl_xor(sgg, 32);
;                 if (fq == 0) P[(ai * HALF + wr * 64 + m * 16 + fr) * 4 + wc] = (f32x4){saa, sxx, sxag, sgg};
;                 __builtin_amdgcn_sched_barrier(0);
.LBB0_1077:
	s_or_b64 exec, exec, s[0:1]
	s_waitcnt lgkmcnt(0)
	ds_read_b128 v[146:149], v207 offset:49152
	v_pk_mul_f32 v[150:151], v[80:81], v[80:81]
	s_waitcnt lgkmcnt(0)
	v_pk_mul_f32 v[152:153], v[78:79], v[78:79]
	v_pk_mul_f32 v[158:159], v[80:81], v[144:145]
	v_pk_mov_b32 v[164:165], v[152:153], v[150:151] op_sel:[1,0]
	v_mov_b32_e32 v153, v151
	v_pk_add_f32 v[150:151], v[164:165], v[152:153]
	v_pk_mul_f32 v[160:161], v[78:79], v[142:143]
	v_pk_add_f32 v[164:165], v[150:151], v[150:151] op_sel_hi:[0,1]
	ds_read_b128 v[150:153], v207 offset:57344
	s_waitcnt lgkmcnt(0)
	v_lshlrev_b32_e32 v166, 16, v146
	v_and_b32_e32 v173, 0xffff0000, v146
	v_and_b32_e32 v172, 16, v146
	v_mov_b32_e32 v167, v173
	v_mul_f32_e32 v146, v166, v166
	v_pk_fma_f32 v[174:175], v[166:167], v[166:167], v[146:147] op_sel_hi:[1,1,0]
	v_lshlrev_b32_e32 v146, 16, v147
	v_and_b32_e32 v147, 0xffff0000, v147
	v_mul_f32_e32 v162, v146, v146
	v_mov_b32_e32 v184, v160
	v_mov_b32_e32 v185, v159
	v_mov_b32_e32 v167, v147
	v_pk_fma_f32 v[180:181], v[146:147], v[146:147], v[162:163] op_sel_hi:[1,1,0]
	v_pk_mov_b32 v[182:183], v[160:161], v[158:159] op_sel:[1,0]
	v_pk_mov_b32 v[172:173], v[172:173], v[146:147] op_sel:[1,0]
	v_pk_mul_f32 v[146:147], v[184:185], v[166:167]
	v_pk_mul_f32 v[158:159], v[158:159], v[158:159]
	v_pk_mul_f32 v[160:161], v[160:161], v[160:161]
	v_pk_fma_f32 v[146:147], v[182:183], v[172:173], v[146:147]
	v_pk_mov_b32 v[166:167], v[160:161], v[158:159] op_sel:[1,0]
	v_mov_b32_e32 v161, v159
	v_pk_mul_f32 v[172:173], v[76:77], v[76:77]
	v_pk_mul_f32 v[182:183], v[74:75], v[74:75]
	v_pk_add_f32 v[158:159], v[166:167], v[160:161]
	v_pk_mul_f32 v[160:161], v[76:77], v[140:141]
	v_pk_mul_f32 v[166:167], v[74:75], v[138:139]
	v_pk_mov_b32 v[184:185], v[182:183], v[172:173] op_sel:[1,0]
	v_mov_b32_e32 v183, v173
	v_add_f32_e32 v146, v146, v147
	v_pk_add_f32 v[172:173], v[184:185], v[182:183]
	v_lshlrev_b32_e32 v183, 16, v149
	v_lshlrev_b32_e32 v182, 16, v148
	v_and_b32_e32 v149, 0xffff0000, v149
	v_and_b32_e32 v148, 0xffff0000, v148
	v_mov_b32_e32 v210, v167
	v_mov_b32_e32 v211, v161
	v_add_f32_e32 v147, 0, v146
	v_pk_mul_f32 v[184:185], v[148:149], v[148:149]
	v_mov_b32_e32 v208, v166
	v_mov_b32_e32 v209, v160
	v_pk_mul_f32 v[148:149], v[210:211], v[148:149]
	v_mul_f32_e32 v146, v70, v70
	v_pk_fma_f32 v[148:149], v[208:209], v[182:183], v[148:149]
	v_pk_mul_f32 v[160:161], v[160:161], v[160:161]
	v_pk_mul_f32 v[166:167], v[166:167], v[166:167]
	v_pk_fma_f32 v[208:209], v[70:71], v[70:71], v[146:147] op_sel_hi:[1,1,0]
	v_mul_f32_e32 v146, v72, v72
	s_waitcnt lgkmcnt(0)
	v_lshlrev_b32_e32 v212, 16, v150
	v_pk_fma_f32 v[184:185], v[182:183], v[182:183], v[184:185]
	v_pk_mov_b32 v[182:183], v[166:167], v[160:161] op_sel:[1,0]
	v_mov_b32_e32 v167, v161
	v_pk_fma_f32 v[210:211], v[72:73], v[72:73], v[146:147] op_sel_hi:[1,1,0]
	v_and_b32_e32 v213, 0xffff0000, v150
	v_mul_f32_e32 v146, v212, v212
	v_lshlrev_b32_e32 v150, 16, v151
	v_pk_add_f32 v[160:161], v[182:183], v[166:167]
	v_pk_mul_f32 v[182:183], v[70:71], v[134:135]
	v_pk_fma_f32 v[214:215], v[212:213], v[212:213], v[146:147] op_sel_hi:[1,1,0]
	v_and_b32_e32 v151, 0xffff0000, v151
	v_mul_f32_e32 v146, v150, v150
	v_pk_mul_f32 v[166:167], v[72:73], v[136:137]
	v_pk_fma_f32 v[216:217], v[150:151], v[150:151], v[146:147] op_sel_hi:[1,1,0]
	v_mul_f32_e32 v146, v182, v212
	v_pk_add_f32 v[172:173], v[172:173], v[172:173] op_sel_hi:[0,1]
	v_pk_add_f32 v[148:149], v[148:149], v[148:149] op_sel_hi:[0,1]
	v_pk_fma_f32 v[212:213], v[182:183], v[212:213], v[146:147] op_sel_hi:[1,1,0]
	v_mul_f32_e32 v146, v166, v150
	v_pk_add_f32 v[184:185], v[184:185], v[184:185] op_sel_hi:[0,1]
	v_pk_fma_f32 v[150:151], v[166:167], v[150:151], v[146:147] op_sel_hi:[1,1,0]
	v_pk_mul_f32 v[218:219], v[68:69], v[132:133]
	v_pk_mul_f32 v[220:221], v[66:67], v[130:131]
	v_lshlrev_b32_e32 v222, 16, v152
	v_and_b32_e32 v146, 0xffff0000, v152
	v_lshlrev_b32_e32 v148, 16, v153
	v_and_b32_e32 v157, 0xffff0000, v153
	v_mul_f32_e32 v208, v66, v66
	v_mul_f32_e32 v210, v67, v67
	v_mul_f32_e32 v172, v68, v68
	v_mul_f32_e32 v164, v69, v69
	v_pk_add_f32 v[152:153], v[208:209], v[210:211]
	v_pk_add_f32 v[164:165], v[172:173], v[164:165]
	v_mul_f32_e32 v184, v146, v146
	v_mul_f32_e32 v214, v148, v148
	v_mul_f32_e32 v212, v220, v222
	v_mul_f32_e32 v150, v221, v146
	v_mul_f32_e32 v148, v218, v148
	v_mul_f32_e32 v146, v219, v157
	v_pk_add_f32 v[152:153], v[152:153], v[164:165]
	v_mov_b32_e32 v223, v175
	v_mov_b32_e32 v164, v222
	v_mov_b32_e32 v165, v181
	v_pk_add_f32 v[150:151], v[212:213], v[150:151]
	v_pk_add_f32 v[146:147], v[148:149], v[146:147]
	v_pk_mul_f32 v[164:165], v[222:223], v[164:165]
	v_pk_add_f32 v[172:173], v[174:175], v[180:181]
	v_pk_add_f32 v[146:147], v[150:151], v[146:147]
	v_mul_f32_e32 v216, v157, v157
	v_mov_b32_e32 v165, v173
	v_add_f32_e32 v148, v146, v147
	v_mul_f32_e32 v149, v220, v220
	v_mul_f32_e32 v157, v221, v221
	v_pk_add_f32 v[146:147], v[158:159], v[158:159] op_sel:[0,1] op_sel_hi:[1,0]
	v_pk_add_f32 v[150:151], v[160:161], v[160:161] op_sel:[0,1] op_sel_hi:[1,0]
	v_pk_add_f32 v[164:165], v[164:165], v[184:185]
	v_pk_add_f32 v[172:173], v[214:215], v[216:217]
	v_mov_b32_e32 v147, v149
	v_mov_b32_e32 v151, v157
	v_pk_add_f32 v[164:165], v[164:165], v[172:173]
	v_pk_add_f32 v[146:147], v[146:147], v[150:151]
	v_mul_f32_e32 v150, v183, v183
	v_mul_f32_e32 v158, v167, v167
	v_add_f32_e32 v152, v152, v153
	v_add_f32_e32 v153, v164, v165
	v_mul_f32_e32 v162, v218, v218
	v_mul_f32_e32 v164, v219, v219
	v_pk_fma_f32 v[150:151], v[182:183], v[182:183], v[150:151] op_sel_hi:[1,1,0]
	v_pk_fma_f32 v[158:159], v[166:167], v[166:167], v[158:159] op_sel_hi:[1,1,0]
	v_mov_b32_e32 v151, v162
	v_mov_b32_e32 v159, v164
	v_pk_add_f32 v[150:151], v[150:151], v[158:159]
	s_nop 0
	v_pk_add_f32 v[146:147], v[146:147], v[150:151]
	s_nop 0
	v_add_f32_e32 v149, v146, v147
	v_mov_b32_e32 v146, v152
	s_nop 1
	v_permlane16_swap_b32_e32 v152, v146
	v_mov_b32_e32 v147, v153
	s_nop 1
	v_permlane16_swap_b32_e32 v153, v147
	v_mov_b32_e32 v150, v148
	s_nop 1
	v_permlane16_swap_b32_e32 v148, v150
	v_mov_b32_e32 v151, v149
	s_nop 1
	v_permlane16_swap_b32_e32 v149, v151
	s_waitcnt lgkmcnt(0)
	v_pk_add_f32 v[146:147], v[152:153], v[146:147]
	s_waitcnt lgkmcnt(0)
	v_pk_add_f32 v[150:151], v[148:149], v[150:151]
	v_mov_b32_e32 v148, v146
	s_nop 1
	v_permlane32_swap_b32_e32 v146, v148
	v_mov_b32_e32 v149, v147
	s_nop 1
	v_permlane32_swap_b32_e32 v147, v149
	v_mov_b32_e32 v152, v150
	s_nop 1
	v_permlane32_swap_b32_e32 v150, v152
	v_mov_b32_e32 v153, v151
	s_nop 1
	v_permlane32_swap_b32_e32 v151, v153
	s_and_saveexec_b64 s[0:1], vcc
	s_cbranch_execz .LBB0_1079
	s_lshl_b32 s5, s19, 12
	s_add_i32 s5, s4, s5
	s_waitcnt lgkmcnt(0)
	v_pk_add_f32 v[150:151], v[150:151], v[152:153]
	v_pk_add_f32 v[148:149], v[146:147], v[148:149]
	v_add_u32_e32 v146, s5, v155
	ds_write_b128 v146, v[148:151] offset:3072
;     __device__ __forceinline__ void fused(f32x4 (&acc)[2][2][4][2], const Unit& u, int wr, int wc, int fr, int fq, PG8_LAS unsigned char* lds, int wid, int lane) const {
;     ...
;         for (int ai = 0; ai < 2; ++ai)
; #pragma unroll
;             for (int m = 0; m < 4; ++m) {
;                 float saa = 0.f, sxx = 0.f, sxag = 0.f, sgg = 0.f;
; #pragma unroll
;                 for (int bj = 0; bj < 2; ++bj) { const u32x4 w4 = XL[((ai * 4 + m) * 2 + bj) * 512];
; #pragma unroll
;                     for (int n = 0; n < 2; ++n) { const f32x4 a = acc[ai][bj][m][n]; const f32x4 ag = a * gv[bj][n]; const unsigned wx = n == 0 ? w4.x : w4.z, wy = n == 0 ? w4.y : w4.w;
;                         const f32x4 x = (f32x4){bflo(wx), bfhi(wx), bflo(wy), bfhi(wy)};
;                         saa += (a[0] * a[0] + a[1] * a[1]) + (a[2] * a[2] + a[3] * a[3]); sxx += (x[0] * x[0] + x[1] * x[1]) + (x[2] * x[2] + x[3] * x[3]);
;                         sxag += (x[0] * ag[0] + x[1] * ag[1]) + (x[2] * ag[2] + x[3] * ag[3]); sgg += (ag[0] * ag[0] + ag[1] * ag[1]) + (ag[2] * ag[2] + ag[3] * ag[3]); } }
;                 asm volatile("" : "+v"(saa), "+v"(sxx), "+v"(sxag), "+v"(sgg));
;                 saa += __shfl_xor(saa, 16); sxx += __shfl_xor(sxx, 16); sxag += __shfl_xor(sxag, 16); sgg += __shfl_xor(sgg, 16);
;                 saa += __shfl_xor(saa, 32); sxx += __shfl_xor(sxx, 32); sxag += __shfl_xor(sxag, 32); sgg += __shfl_xor(sgg, 32);
;                 if (fq == 0) P[(ai * HALF + wr * 64 + m * 16 + fr) * 4 + wc] = (f32x4){saa, sxx, sxag, sgg};
;                 __builtin_amdgcn_sched_barrier(0);
.LBB0_1079:
	s_or_b64 exec, exec, s[0:1]
	s_waitcnt lgkmcnt(0)
	ds_read_b128 v[146:149], v206
	v_pk_mul_f32 v[150:151], v[64:65], v[64:65]
	s_waitcnt lgkmcnt(0)
	v_pk_mul_f32 v[152:153], v[62:63], v[62:63]
	v_pk_mul_f32 v[158:159], v[64:65], v[144:145]
	v_pk_mov_b32 v[164:165], v[152:153], v[150:151] op_sel:[1,0]
	v_mov_b32_e32 v153, v151
	v_pk_add_f32 v[150:151], v[164:165], v[152:153]
	v_pk_mul_f32 v[160:161], v[62:63], v[142:143]
	v_pk_add_f32 v[164:165], v[150:151], v[150:151] op_sel_hi:[0,1]
	ds_read_b128 v[150:153], v205
	s_waitcnt lgkmcnt(0)
	v_lshlrev_b32_e32 v166, 16, v146
	v_and_b32_e32 v173, 0xffff0000, v146
	v_and_b32_e32 v172, 16, v146
	v_mov_b32_e32 v167, v173
	v_mul_f32_e32 v146, v166, v166
	v_pk_fma_f32 v[174:175], v[166:167], v[166:167], v[146:147] op_sel_hi:[1,1,0]
	v_lshlrev_b32_e32 v146, 16, v147
	v_and_b32_e32 v147, 0xffff0000, v147
	v_mul_f32_e32 v162, v146, v146
	v_mov_b32_e32 v184, v160
	v_mov_b32_e32 v185, v159
	v_mov_b32_e32 v167, v147
	v_pk_fma_f32 v[180:181], v[146:147], v[146:147], v[162:163] op_sel_hi:[1,1,0]
	v_pk_mov_b32 v[182:183], v[160:161], v[158:159] op_sel:[1,0]
	v_pk_mov_b32 v[172:173], v[172:173], v[146:147] op_sel:[1,0]
	v_pk_mul_f32 v[146:147], v[184:185], v[166:167]
	v_pk_mul_f32 v[158:159], v[158:159], v[158:159]
	v_pk_mul_f32 v[160:161], v[160:161], v[160:161]
	v_pk_fma_f32 v[146:147], v[182:183], v[172:173], v[146:147]
	v_pk_mov_b32 v[166:167], v[160:161], v[158:159] op_sel:[1,0]
	v_mov_b32_e32 v161, v159
	v_pk_mul_f32 v[172:173], v[60:61], v[60:61]
	v_pk_mul_f32 v[182:183], v[58:59], v[58:59]
	v_pk_add_f32 v[158:159], v[166:167], v[160:161]
	v_pk_mul_f32 v[160:161], v[60:61], v[140:141]
	v_pk_mul_f32 v[166:167], v[58:59], v[138:139]
	v_pk_mov_b32 v[184:185], v[182:183], v[172:173] op_sel:[1,0]
	v_mov_b32_e32 v183, v173
	v_add_f32_e32 v146, v146, v147
	v_pk_add_f32 v[172:173], v[184:185], v[182:183]
	v_lshlrev_b32_e32 v183, 16, v149
	v_lshlrev_b32_e32 v182, 16, v148
	v_and_b32_e32 v149, 0xffff0000, v149
	v_and_b32_e32 v148, 0xffff0000, v148
	v_mov_b32_e32 v210, v167
	v_mov_b32_e32 v211, v161
	v_add_f32_e32 v147, 0, v146
	v_pk_mul_f32 v[184:185], v[148:149], v[148:149]
	v_mov_b32_e32 v208, v166
	v_mov_b32_e32 v209, v160
	v_pk_mul_f32 v[148:149], v[210:211], v[148:149]
	v_mul_f32_e32 v146, v54, v54
	v_pk_fma_f32 v[148:149], v[208:209], v[182:183], v[148:149]
	v_pk_mul_f32 v[160:161], v[160:161], v[160:161]
	v_pk_mul_f32 v[166:167], v[166:167], v[166:167]
	v_pk_fma_f32 v[208:209], v[54:55], v[54:55], v[146:147] op_sel_hi:[1,1,0]
	v_mul_f32_e32 v146, v56, v56
	s_waitcnt lgkmcnt(0)
	v_lshlrev_b32_e32 v212, 16, v150
	v_pk_fma_f32 v[184:185], v[182:183], v[182:183], v[184:185]
	v_pk_mov_b32 v[182:183], v[166:167], v[160:161] op_sel:[1,0]
	v_mov_b32_e32 v167, v161
	v_pk_fma_f32 v[210:211], v[56:57], v[56:57], v[146:147] op_sel_hi:[1,1,0]
	v_and_b32_e32 v213, 0xffff0000, v150
	v_mul_f32_e32 v146, v212, v212
	v_lshlrev_b32_e32 v150, 16, v151
	v_pk_add_f32 v[160:161], v[182:183], v[166:167]
	v_pk_mul_f32 v[182:183], v[54:55], v[134:135]
	v_pk_fma_f32 v[214:215], v[212:213], v[212:213], v[146:147] op_sel_hi:[1,1,0]
	v_and_b32_e32 v151, 0xffff0000, v151
	v_mul_f32_e32 v146, v150, v150
	v_pk_mul_f32 v[166:167], v[56:57], v[136:137]
	v_pk_fma_f32 v[216:217], v[150:151], v[150:151], v[146:147] op_sel_hi:[1,1,0]
	v_mul_f32_e32 v146, v182, v212
	v_pk_add_f32 v[172:173], v[172:173], v[172:173] op_sel_hi:[0,1]
	v_pk_add_f32 v[148:149], v[148:149], v[148:149] op_sel_hi:[0,1]
	v_pk_fma_f32 v[212:213], v[182:183], v[212:213], v[146:147] op_sel_hi:[1,1,0]
	v_mul_f32_e32 v146, v166, v150
	v_pk_add_f32 v[184:185], v[184:185], v[184:185] op_sel_hi:[0,1]
	v_pk_fma_f32 v[150:151], v[166:167], v[150:151], v[146:147] op_sel_hi:[1,1,0]
	v_pk_mul_f32 v[218:219], v[52:53], v[132:133]
	v_pk_mul_f32 v[220:221], v[50:51], v[130:131]
	v_lshlrev_b32_e32 v222, 16, v152
	v_and_b32_e32 v146, 0xffff0000, v152
	v_lshlrev_b32_e32 v148, 16, v153
	v_and_b32_e32 v157, 0xffff0000, v153
	v_mul_f32_e32 v208, v50, v50
	v_mul_f32_e32 v210, v51, v51
	v_mul_f32_e32 v172, v52, v52
	v_mul_f32_e32 v164, v53, v53
	v_pk_add_f32 v[152:153], v[208:209], v[210:211]
	v_pk_add_f32 v[164:165], v[172:173], v[164:165]
	v_mul_f32_e32 v184, v146, v146
	v_mul_f32_e32 v214, v148, v148
	v_mul_f32_e32 v212, v220, v222
	v_mul_f32_e32 v150, v221, v146
	v_mul_f32_e32 v148, v218, v148
	v_mul_f32_e32 v146, v219, v157
	v_pk_add_f32 v[152:153], v[152:153], v[164:165]
	v_mov_b32_e32 v223, v175
	v_mov_b32_e32 v164, v222
	v_mov_b32_e32 v165, v181
	v_pk_add_f32 v[150:151], v[212:213], v[150:151]
	v_pk_add_f32 v[146:147], v[148:149], v[146:147]
	v_pk_mul_f32 v[164:165], v[222:223], v[164:165]
	v_pk_add_f32 v[172:173], v[174:175], v[180:181]
	v_pk_add_f32 v[146:147], v[150:151], v[146:147]
	v_mul_f32_e32 v216, v157, v157
	v_mov_b32_e32 v165, v173
	v_add_f32_e32 v148, v146, v147
	v_mul_f32_e32 v149, v220, v220
	v_mul_f32_e32 v157, v221, v221
	v_pk_add_f32 v[146:147], v[158:159], v[158:159] op_sel:[0,1] op_sel_hi:[1,0]
	v_pk_add_f32 v[150:151], v[160:161], v[160:161] op_sel:[0,1] op_sel_hi:[1,0]
	v_pk_add_f32 v[164:165], v[164:165], v[184:185]
	v_pk_add_f32 v[172:173], v[214:215], v[216:217]
	v_mov_b32_e32 v147, v149
	v_mov_b32_e32 v151, v157
	v_pk_add_f32 v[164:165], v[164:165], v[172:173]
	v_pk_add_f32 v[146:147], v[146:147], v[150:151]
	v_mul_f32_e32 v150, v183, v183
	v_mul_f32_e32 v158, v167, v167
	v_add_f32_e32 v152, v152, v153
	v_add_f32_e32 v153, v164, v165
	v_mul_f32_e32 v162, v218, v218
	v_mul_f32_e32 v164, v219, v219
	v_pk_fma_f32 v[150:151], v[182:183], v[182:183], v[150:151] op_sel_hi:[1,1,0]
	v_pk_fma_f32 v[158:159], v[166:167], v[166:167], v[158:159] op_sel_hi:[1,1,0]
	v_mov_b32_e32 v151, v162
	v_mov_b32_e32 v159, v164
	v_pk_add_f32 v[150:151], v[150:151], v[158:159]
	s_nop 0
	v_pk_add_f32 v[146:147], v[146:147], v[150:151]
	s_nop 0
	v_add_f32_e32 v149, v146, v147
	v_mov_b32_e32 v146, v152
	s_nop 1
	v_permlane16_swap_b32_e32 v152, v146
	v_mov_b32_e32 v147, v153
	s_nop 1
	v_permlane16_swap_b32_e32 v153, v147
	v_mov_b32_e32 v150, v148
	s_nop 1
	v_permlane16_swap_b32_e32 v148, v150
	v_mov_b32_e32 v151, v149
	s_nop 1
	v_permlane16_swap_b32_e32 v149, v151
	s_waitcnt lgkmcnt(0)
	v_pk_add_f32 v[146:147], v[152:153], v[146:147]
	s_waitcnt lgkmcnt(0)
	v_pk_add_f32 v[150:151], v[148:149], v[150:151]
	v_mov_b32_e32 v148, v146
	s_nop 1
	v_permlane32_swap_b32_e32 v146, v148
	v_mov_b32_e32 v149, v147
	s_nop 1
	v_permlane32_swap_b32_e32 v147, v149
	v_mov_b32_e32 v152, v150
	s_nop 1
	v_permlane32_swap_b32_e32 v150, v152
	v_mov_b32_e32 v153, v151
	s_nop 1
	v_permlane32_swap_b32_e32 v151, v153
	s_and_saveexec_b64 s[0:1], vcc
	s_cbranch_execz .LBB0_1081
	s_lshl_b32 s5, s19, 12
	s_add_i32 s5, s4, s5
	s_waitcnt lgkmcnt(0)
	v_pk_add_f32 v[150:151], v[150:151], v[152:153]
	v_pk_add_f32 v[148:149], v[146:147], v[148:149]
	v_add_u32_e32 v146, s5, v155
	ds_write_b128 v146, v[148:151] offset:8192
;     __device__ __forceinline__ void fused(f32x4 (&acc)[2][2][4][2], const Unit& u, int wr, int wc, int fr, int fq, PG8_LAS unsigned char* lds, int wid, int lane) const {
;     ...
;         for (int ai = 0; ai < 2; ++ai)
; #pragma unroll
;             for (int m = 0; m < 4; ++m) {
;                 float saa = 0.f, sxx = 0.f, sxag = 0.f, sgg = 0.f;
; #pragma unroll
;                 for (int bj = 0; bj < 2; ++bj) { const u32x4 w4 = XL[((ai * 4 + m) * 2 + bj) * 512];
; #pragma unroll
;                     for (int n = 0; n < 2; ++n) { const f32x4 a = acc[ai][bj][m][n]; const f32x4 ag = a * gv[bj][n]; const unsigned wx = n == 0 ? w4.x : w4.z, wy = n == 0 ? w4.y : w4.w;
;                         const f32x4 x = (f32x4){bflo(wx), bfhi(wx), bflo(wy), bfhi(wy)};
;                         saa += (a[0] * a[0] + a[1] * a[1]) + (a[2] * a[2] + a[3] * a[3]); sxx += (x[0] * x[0] + x[1] * x[1]) + (x[2] * x[2] + x[3] * x[3]);
;                         sxag += (x[0] * ag[0] + x[1] * ag[1]) + (x[2] * ag[2] + x[3] * ag[3]); sgg += (ag[0] * ag[0] + ag[1] * ag[1]) + (ag[2] * ag[2] + ag[3] * ag[3]); } }
;                 asm volatile("" : "+v"(saa), "+v"(sxx), "+v"(sxag), "+v"(sgg));
;                 saa += __shfl_xor(saa, 16); sxx += __shfl_xor(sxx, 16); sxag += __shfl_xor(sxag, 16); sgg += __shfl_xor(sgg, 16);
;                 saa += __shfl_xor(saa, 32); sxx += __shfl_xor(sxx, 32); sxag += __shfl_xor(sxag, 32); sgg += __shfl_xor(sgg, 32);
;                 if (fq == 0) P[(ai * HALF + wr * 64 + m * 16 + fr) * 4 + wc] = (f32x4){saa, sxx, sxag, sgg};
;                 __builtin_amdgcn_sched_barrier(0);
.LBB0_1081:
	s_or_b64 exec, exec, s[0:1]
	s_waitcnt lgkmcnt(0)
	ds_read_b128 v[146:149], v204
	v_pk_mul_f32 v[150:151], v[48:49], v[48:49]
	s_waitcnt lgkmcnt(0)
	v_pk_mul_f32 v[152:153], v[46:47], v[46:47]
	v_pk_mul_f32 v[158:159], v[48:49], v[144:145]
	v_pk_mov_b32 v[164:165], v[152:153], v[150:151] op_sel:[1,0]
	v_mov_b32_e32 v153, v151
	v_pk_add_f32 v[150:151], v[164:165], v[152:153]
	v_pk_mul_f32 v[160:161], v[46:47], v[142:143]
	v_pk_add_f32 v[164:165], v[150:151], v[150:151] op_sel_hi:[0,1]
	ds_read_b128 v[150:153], v203
	s_waitcnt lgkmcnt(0)
	v_lshlrev_b32_e32 v166, 16, v146
	v_and_b32_e32 v173, 0xffff0000, v146
	v_and_b32_e32 v172, 16, v146
	v_mov_b32_e32 v167, v173
	v_mul_f32_e32 v146, v166, v166
	v_pk_fma_f32 v[174:175], v[166:167], v[166:167], v[146:147] op_sel_hi:[1,1,0]
	v_lshlrev_b32_e32 v146, 16, v147
	v_and_b32_e32 v147, 0xffff0000, v147
	v_mul_f32_e32 v162, v146, v146
	v_mov_b32_e32 v184, v160
	v_mov_b32_e32 v185, v159
	v_mov_b32_e32 v167, v147
	v_pk_fma_f32 v[180:181], v[146:147], v[146:147], v[162:163] op_sel_hi:[1,1,0]
	v_pk_mov_b32 v[182:183], v[160:161], v[158:159] op_sel:[1,0]
	v_pk_mov_b32 v[172:173], v[172:173], v[146:147] op_sel:[1,0]
	v_pk_mul_f32 v[146:147], v[184:185], v[166:167]
	v_pk_mul_f32 v[158:159], v[158:159], v[158:159]
	v_pk_mul_f32 v[160:161], v[160:161], v[160:161]
	v_pk_fma_f32 v[146:147], v[182:183], v[172:173], v[146:147]
	v_pk_mov_b32 v[166:167], v[160:161], v[158:159] op_sel:[1,0]
	v_mov_b32_e32 v161, v159
	v_pk_mul_f32 v[172:173], v[44:45], v[44:45]
	v_pk_mul_f32 v[182:183], v[42:43], v[42:43]
	v_pk_add_f32 v[158:159], v[166:167], v[160:161]
	v_pk_mul_f32 v[160:161], v[44:45], v[140:141]
	v_pk_mul_f32 v[166:167], v[42:43], v[138:139]
	v_pk_mov_b32 v[184:185], v[182:183], v[172:173] op_sel:[1,0]
	v_mov_b32_e32 v183, v173
	v_add_f32_e32 v146, v146, v147
	v_pk_add_f32 v[172:173], v[184:185], v[182:183]
	v_lshlrev_b32_e32 v183, 16, v149
	v_lshlrev_b32_e32 v182, 16, v148
	v_and_b32_e32 v149, 0xffff0000, v149
	v_and_b32_e32 v148, 0xffff0000, v148
	v_mov_b32_e32 v210, v167
	v_mov_b32_e32 v211, v161
	v_add_f32_e32 v147, 0, v146
	v_pk_mul_f32 v[184:185], v[148:149], v[148:149]
	v_mov_b32_e32 v208, v166
	v_mov_b32_e32 v209, v160
	v_pk_mul_f32 v[148:149], v[210:211], v[148:149]
	v_mul_f32_e32 v146, v38, v38
	v_pk_fma_f32 v[148:149], v[208:209], v[182:183], v[148:149]
	v_pk_mul_f32 v[160:161], v[160:161], v[160:161]
	v_pk_mul_f32 v[166:167], v[166:167], v[166:167]
	v_pk_fma_f32 v[208:209], v[38:39], v[38:39], v[146:147] op_sel_hi:[1,1,0]
	v_mul_f32_e32 v146, v40, v40
	s_waitcnt lgkmcnt(0)
	v_lshlrev_b32_e32 v212, 16, v150
	v_pk_fma_f32 v[184:185], v[182:183], v[182:183], v[184:185]
	v_pk_mov_b32 v[182:183], v[166:167], v[160:161] op_sel:[1,0]
	v_mov_b32_e32 v167, v161
	v_pk_fma_f32 v[210:211], v[40:41], v[40:41], v[146:147] op_sel_hi:[1,1,0]
	v_and_b32_e32 v213, 0xffff0000, v150
	v_mul_f32_e32 v146, v212, v212
	v_lshlrev_b32_e32 v150, 16, v151
	v_pk_add_f32 v[160:161], v[182:183], v[166:167]
	v_pk_mul_f32 v[182:183], v[38:39], v[134:135]
	v_pk_fma_f32 v[214:215], v[212:213], v[212:213], v[146:147] op_sel_hi:[1,1,0]
	v_and_b32_e32 v151, 0xffff0000, v151
	v_mul_f32_e32 v146, v150, v150
	v_pk_mul_f32 v[166:167], v[40:41], v[136:137]
	v_pk_fma_f32 v[216:217], v[150:151], v[150:151], v[146:147] op_sel_hi:[1,1,0]
	v_mul_f32_e32 v146, v182, v212
	v_pk_add_f32 v[172:173], v[172:173], v[172:173] op_sel_hi:[0,1]
	v_pk_add_f32 v[148:149], v[148:149], v[148:149] op_sel_hi:[0,1]
	v_pk_fma_f32 v[212:213], v[182:183], v[212:213], v[146:147] op_sel_hi:[1,1,0]
	v_mul_f32_e32 v146, v166, v150
	v_pk_add_f32 v[184:185], v[184:185], v[184:185] op_sel_hi:[0,1]
	v_pk_fma_f32 v[150:151], v[166:167], v[150:151], v[146:147] op_sel_hi:[1,1,0]
	v_pk_mul_f32 v[218:219], v[36:37], v[132:133]
	v_pk_mul_f32 v[220:221], v[34:35], v[130:131]
	v_lshlrev_b32_e32 v222, 16, v152
	v_and_b32_e32 v146, 0xffff0000, v152
	v_lshlrev_b32_e32 v148, 16, v153
	v_and_b32_e32 v157, 0xffff0000, v153
	v_mul_f32_e32 v208, v34, v34
	v_mul_f32_e32 v210, v35, v35
	v_mul_f32_e32 v172, v36, v36
	v_mul_f32_e32 v164, v37, v37
	v_pk_add_f32 v[152:153], v[208:209], v[210:211]
	v_pk_add_f32 v[164:165], v[172:173], v[164:165]
	v_mul_f32_e32 v184, v146, v146
	v_mul_f32_e32 v214, v148, v148
	v_mul_f32_e32 v212, v220, v222
	v_mul_f32_e32 v150, v221, v146
	v_mul_f32_e32 v148, v218, v148
	v_mul_f32_e32 v146, v219, v157
	v_pk_add_f32 v[152:153], v[152:153], v[164:165]
	v_mov_b32_e32 v223, v175
	v_mov_b32_e32 v164, v222
	v_mov_b32_e32 v165, v181
	v_pk_add_f32 v[150:151], v[212:213], v[150:151]
	v_pk_add_f32 v[146:147], v[148:149], v[146:147]
	v_pk_mul_f32 v[164:165], v[222:223], v[164:165]
	v_pk_add_f32 v[172:173], v[174:175], v[180:181]
	v_pk_add_f32 v[146:147], v[150:151], v[146:147]
	v_mul_f32_e32 v216, v157, v157
	v_mov_b32_e32 v165, v173
	v_add_f32_e32 v148, v146, v147
	v_mul_f32_e32 v149, v220, v220
	v_mul_f32_e32 v157, v221, v221
	v_pk_add_f32 v[146:147], v[158:159], v[158:159] op_sel:[0,1] op_sel_hi:[1,0]
	v_pk_add_f32 v[150:151], v[160:161], v[160:161] op_sel:[0,1] op_sel_hi:[1,0]
	v_pk_add_f32 v[164:165], v[164:165], v[184:185]
	v_pk_add_f32 v[172:173], v[214:215], v[216:217]
	v_mov_b32_e32 v147, v149
	v_mov_b32_e32 v151, v157
	v_pk_add_f32 v[164:165], v[164:165], v[172:173]
	v_pk_add_f32 v[146:147], v[146:147], v[150:151]
	v_mul_f32_e32 v150, v183, v183
	v_mul_f32_e32 v158, v167, v167
	v_add_f32_e32 v152, v152, v153
	v_add_f32_e32 v153, v164, v165
	v_mul_f32_e32 v162, v218, v218
	v_mul_f32_e32 v164, v219, v219
	v_pk_fma_f32 v[150:151], v[182:183], v[182:183], v[150:151] op_sel_hi:[1,1,0]
	v_pk_fma_f32 v[158:159], v[166:167], v[166:167], v[158:159] op_sel_hi:[1,1,0]
	v_mov_b32_e32 v151, v162
	v_mov_b32_e32 v159, v164
	v_pk_add_f32 v[150:151], v[150:151], v[158:159]
	s_nop 0
	v_pk_add_f32 v[146:147], v[146:147], v[150:151]
	s_nop 0
	v_add_f32_e32 v149, v146, v147
	v_mov_b32_e32 v146, v152
	s_nop 1
	v_permlane16_swap_b32_e32 v152, v146
	v_mov_b32_e32 v147, v153
	s_nop 1
	v_permlane16_swap_b32_e32 v153, v147
	v_mov_b32_e32 v150, v148
	s_nop 1
	v_permlane16_swap_b32_e32 v148, v150
	v_mov_b32_e32 v151, v149
	s_nop 1
	v_permlane16_swap_b32_e32 v149, v151
	s_waitcnt lgkmcnt(0)
	v_pk_add_f32 v[146:147], v[152:153], v[146:147]
	s_waitcnt lgkmcnt(0)
	v_pk_add_f32 v[150:151], v[148:149], v[150:151]
	v_mov_b32_e32 v148, v146
	s_nop 1
	v_permlane32_swap_b32_e32 v146, v148
	v_mov_b32_e32 v149, v147
	s_nop 1
	v_permlane32_swap_b32_e32 v147, v149
	v_mov_b32_e32 v152, v150
	s_nop 1
	v_permlane32_swap_b32_e32 v150, v152
	v_mov_b32_e32 v153, v151
	s_nop 1
	v_permlane32_swap_b32_e32 v151, v153
	s_and_saveexec_b64 s[0:1], vcc
	s_cbranch_execz .LBB0_1083
	s_lshl_b32 s5, s19, 12
	s_add_i32 s5, s4, s5
	s_waitcnt lgkmcnt(0)
	v_pk_add_f32 v[150:151], v[150:151], v[152:153]
	v_pk_add_f32 v[148:149], v[146:147], v[148:149]
	v_add_u32_e32 v146, s5, v155
	ds_write_b128 v146, v[148:151] offset:9216
;     __device__ __forceinline__ void fused(f32x4 (&acc)[2][2][4][2], const Unit& u, int wr, int wc, int fr, int fq, PG8_LAS unsigned char* lds, int wid, int lane) const {
;     ...
;         for (int ai = 0; ai < 2; ++ai)
; #pragma unroll
;             for (int m = 0; m < 4; ++m) {
;                 float saa = 0.f, sxx = 0.f, sxag = 0.f, sgg = 0.f;
; #pragma unroll
;                 for (int bj = 0; bj < 2; ++bj) { const u32x4 w4 = XL[((ai * 4 + m) * 2 + bj) * 512];
; #pragma unroll
;                     for (int n = 0; n < 2; ++n) { const f32x4 a = acc[ai][bj][m][n]; const f32x4 ag = a * gv[bj][n]; const unsigned wx = n == 0 ? w4.x : w4.z, wy = n == 0 ? w4.y : w4.w;
;                         const f32x4 x = (f32x4){bflo(wx), bfhi(wx), bflo(wy), bfhi(wy)};
;                         saa += (a[0] * a[0] + a[1] * a[1]) + (a[2] * a[2] + a[3] * a[3]); sxx += (x[0] * x[0] + x[1] * x[1]) + (x[2] * x[2] + x[3] * x[3]);
;                         sxag += (x[0] * ag[0] + x[1] * ag[1]) + (x[2] * ag[2] + x[3] * ag[3]); sgg += (ag[0] * ag[0] + ag[1] * ag[1]) + (ag[2] * ag[2] + ag[3] * ag[3]); } }
;                 asm volatile("" : "+v"(saa), "+v"(sxx), "+v"(sxag), "+v"(sgg));
;                 saa += __shfl_xor(saa, 16); sxx += __shfl_xor(sxx, 16); sxag += __shfl_xor(sxag, 16); sgg += __shfl_xor(sgg, 16);
;                 saa += __shfl_xor(saa, 32); sxx += __shfl_xor(sxx, 32); sxag += __shfl_xor(sxag, 32); sgg += __shfl_xor(sgg, 32);
;                 if (fq == 0) P[(ai * HALF + wr * 64 + m * 16 + fr) * 4 + wc] = (f32x4){saa, sxx, sxag, sgg};
;                 __builtin_amdgcn_sched_barrier(0);
.LBB0_1083:
	s_or_b64 exec, exec, s[0:1]
	s_waitcnt lgkmcnt(0)
	ds_read_b128 v[146:149], v202
	v_pk_mul_f32 v[150:151], v[32:33], v[32:33]
	s_waitcnt lgkmcnt(0)
	v_pk_mul_f32 v[152:153], v[30:31], v[30:31]
	v_pk_mul_f32 v[158:159], v[32:33], v[144:145]
	v_pk_mov_b32 v[164:165], v[152:153], v[150:151] op_sel:[1,0]
	v_mov_b32_e32 v153, v151
	v_pk_add_f32 v[150:151], v[164:165], v[152:153]
	v_pk_mul_f32 v[160:161], v[30:31], v[142:143]
	v_pk_add_f32 v[164:165], v[150:151], v[150:151] op_sel_hi:[0,1]
	ds_read_b128 v[150:153], v201
	s_waitcnt lgkmcnt(0)
	v_lshlrev_b32_e32 v166, 16, v146
	v_and_b32_e32 v173, 0xffff0000, v146
	v_and_b32_e32 v172, 16, v146
	v_mov_b32_e32 v167, v173
	v_mul_f32_e32 v146, v166, v166
	v_pk_fma_f32 v[174:175], v[166:167], v[166:167], v[146:147] op_sel_hi:[1,1,0]
	v_lshlrev_b32_e32 v146, 16, v147
	v_and_b32_e32 v147, 0xffff0000, v147
	v_mul_f32_e32 v162, v146, v146
	v_mov_b32_e32 v184, v160
	v_mov_b32_e32 v185, v159
	v_mov_b32_e32 v167, v147
	v_pk_fma_f32 v[180:181], v[146:147], v[146:147], v[162:163] op_sel_hi:[1,1,0]
	v_pk_mov_b32 v[182:183], v[160:161], v[158:159] op_sel:[1,0]
	v_pk_mov_b32 v[172:173], v[172:173], v[146:147] op_sel:[1,0]
	v_pk_mul_f32 v[146:147], v[184:185], v[166:167]
	v_pk_mul_f32 v[158:159], v[158:159], v[158:159]
	v_pk_mul_f32 v[160:161], v[160:161], v[160:161]
	v_pk_fma_f32 v[146:147], v[182:183], v[172:173], v[146:147]
	v_pk_mov_b32 v[166:167], v[160:161], v[158:159] op_sel:[1,0]
	v_mov_b32_e32 v161, v159
	v_pk_mul_f32 v[172:173], v[28:29], v[28:29]
	v_pk_mul_f32 v[182:183], v[26:27], v[26:27]
	v_pk_add_f32 v[158:159], v[166:167], v[160:161]
	v_pk_mul_f32 v[160:161], v[28:29], v[140:141]
	v_pk_mul_f32 v[166:167], v[26:27], v[138:139]
	v_pk_mov_b32 v[184:185], v[182:183], v[172:173] op_sel:[1,0]
	v_mov_b32_e32 v183, v173
	v_add_f32_e32 v146, v146, v147
	v_pk_add_f32 v[172:173], v[184:185], v[182:183]
	v_lshlrev_b32_e32 v183, 16, v149
	v_lshlrev_b32_e32 v182, 16, v148
	v_and_b32_e32 v149, 0xffff0000, v149
	v_and_b32_e32 v148, 0xffff0000, v148
	v_mov_b32_e32 v210, v167
	v_mov_b32_e32 v211, v161
	v_add_f32_e32 v147, 0, v146
	v_pk_mul_f32 v[184:185], v[148:149], v[148:149]
	v_mov_b32_e32 v208, v166
	v_mov_b32_e32 v209, v160
	v_pk_mul_f32 v[148:149], v[210:211], v[148:149]
	v_mul_f32_e32 v146, v22, v22
	v_pk_fma_f32 v[148:149], v[208:209], v[182:183], v[148:149]
	v_pk_mul_f32 v[160:161], v[160:161], v[160:161]
	v_pk_mul_f32 v[166:167], v[166:167], v[166:167]
	v_pk_fma_f32 v[208:209], v[22:23], v[22:23], v[146:147] op_sel_hi:[1,1,0]
	v_mul_f32_e32 v146, v24, v24
	s_waitcnt lgkmcnt(0)
	v_lshlrev_b32_e32 v212, 16, v150
	v_pk_fma_f32 v[184:185], v[182:183], v[182:183], v[184:185]
	v_pk_mov_b32 v[182:183], v[166:167], v[160:161] op_sel:[1,0]
	v_mov_b32_e32 v167, v161
	v_pk_fma_f32 v[210:211], v[24:25], v[24:25], v[146:147] op_sel_hi:[1,1,0]
	v_and_b32_e32 v213, 0xffff0000, v150
	v_mul_f32_e32 v146, v212, v212
	v_lshlrev_b32_e32 v150, 16, v151
	v_pk_add_f32 v[160:161], v[182:183], v[166:167]
	v_pk_mul_f32 v[182:183], v[22:23], v[134:135]
	v_pk_fma_f32 v[214:215], v[212:213], v[212:213], v[146:147] op_sel_hi:[1,1,0]
	v_and_b32_e32 v151, 0xffff0000, v151
	v_mul_f32_e32 v146, v150, v150
	v_pk_mul_f32 v[166:167], v[24:25], v[136:137]
	v_pk_fma_f32 v[216:217], v[150:151], v[150:151], v[146:147] op_sel_hi:[1,1,0]
	v_mul_f32_e32 v146, v182, v212
	v_pk_add_f32 v[172:173], v[172:173], v[172:173] op_sel_hi:[0,1]
	v_pk_add_f32 v[148:149], v[148:149], v[148:149] op_sel_hi:[0,1]
	v_pk_fma_f32 v[212:213], v[182:183], v[212:213], v[146:147] op_sel_hi:[1,1,0]
	v_mul_f32_e32 v146, v166, v150
	v_pk_add_f32 v[184:185], v[184:185], v[184:185] op_sel_hi:[0,1]
	v_pk_fma_f32 v[150:151], v[166:167], v[150:151], v[146:147] op_sel_hi:[1,1,0]
	v_pk_mul_f32 v[218:219], v[20:21], v[132:133]
	v_pk_mul_f32 v[220:221], v[18:19], v[130:131]
	v_lshlrev_b32_e32 v222, 16, v152
	v_and_b32_e32 v146, 0xffff0000, v152
	v_lshlrev_b32_e32 v148, 16, v153
	v_and_b32_e32 v157, 0xffff0000, v153
	v_mul_f32_e32 v208, v18, v18
	v_mul_f32_e32 v210, v19, v19
	v_mul_f32_e32 v172, v20, v20
	v_mul_f32_e32 v164, v21, v21
	v_pk_add_f32 v[152:153], v[208:209], v[210:211]
	v_pk_add_f32 v[164:165], v[172:173], v[164:165]
	v_mul_f32_e32 v184, v146, v146
	v_mul_f32_e32 v214, v148, v148
	v_mul_f32_e32 v212, v220, v222
	v_mul_f32_e32 v150, v221, v146
	v_mul_f32_e32 v148, v218, v148
	v_mul_f32_e32 v146, v219, v157
	v_pk_add_f32 v[152:153], v[152:153], v[164:165]
	v_mov_b32_e32 v223, v175
	v_mov_b32_e32 v164, v222
	v_mov_b32_e32 v165, v181
	v_pk_add_f32 v[150:151], v[212:213], v[150:151]
	v_pk_add_f32 v[146:147], v[148:149], v[146:147]
	v_pk_mul_f32 v[164:165], v[222:223], v[164:165]
	v_pk_add_f32 v[172:173], v[174:175], v[180:181]
	v_pk_add_f32 v[146:147], v[150:151], v[146:147]
	v_mul_f32_e32 v216, v157, v157
	v_mov_b32_e32 v165, v173
	v_add_f32_e32 v148, v146, v147
	v_mul_f32_e32 v149, v220, v220
	v_mul_f32_e32 v157, v221, v221
	v_pk_add_f32 v[146:147], v[158:159], v[158:159] op_sel:[0,1] op_sel_hi:[1,0]
	v_pk_add_f32 v[150:151], v[160:161], v[160:161] op_sel:[0,1] op_sel_hi:[1,0]
	v_pk_add_f32 v[164:165], v[164:165], v[184:185]
	v_pk_add_f32 v[172:173], v[214:215], v[216:217]
	v_mov_b32_e32 v147, v149
	v_mov_b32_e32 v151, v157
	v_pk_add_f32 v[164:165], v[164:165], v[172:173]
	v_pk_add_f32 v[146:147], v[146:147], v[150:151]
	v_mul_f32_e32 v150, v183, v183
	v_mul_f32_e32 v158, v167, v167
	v_add_f32_e32 v152, v152, v153
	v_add_f32_e32 v153, v164, v165
	v_mul_f32_e32 v162, v218, v218
	v_mul_f32_e32 v164, v219, v219
	v_pk_fma_f32 v[150:151], v[182:183], v[182:183], v[150:151] op_sel_hi:[1,1,0]
	v_pk_fma_f32 v[158:159], v[166:167], v[166:167], v[158:159] op_sel_hi:[1,1,0]
	v_mov_b32_e32 v151, v162
	v_mov_b32_e32 v159, v164
	v_pk_add_f32 v[150:151], v[150:151], v[158:159]
	s_nop 0
	v_pk_add_f32 v[146:147], v[146:147], v[150:151]
	s_nop 0
	v_add_f32_e32 v149, v146, v147
	v_mov_b32_e32 v146, v152
	s_nop 1
	v_permlane16_swap_b32_e32 v152, v146
	v_mov_b32_e32 v147, v153
	s_nop 1
	v_permlane16_swap_b32_e32 v153, v147
	v_mov_b32_e32 v150, v148
	s_nop 1
	v_permlane16_swap_b32_e32 v148, v150
	v_mov_b32_e32 v151, v149
	s_nop 1
	v_permlane16_swap_b32_e32 v149, v151
	s_waitcnt lgkmcnt(0)
	v_pk_add_f32 v[146:147], v[152:153], v[146:147]
	s_waitcnt lgkmcnt(0)
	v_pk_add_f32 v[150:151], v[148:149], v[150:151]
	v_mov_b32_e32 v148, v146
	s_nop 1
	v_permlane32_swap_b32_e32 v146, v148
	v_mov_b32_e32 v149, v147
	s_nop 1
	v_permlane32_swap_b32_e32 v147, v149
	v_mov_b32_e32 v152, v150
	s_nop 1
	v_permlane32_swap_b32_e32 v150, v152
	v_mov_b32_e32 v153, v151
	s_nop 1
	v_permlane32_swap_b32_e32 v151, v153
	s_and_saveexec_b64 s[0:1], vcc
	s_cbranch_execz .LBB0_1085
	s_lshl_b32 s5, s19, 12
	s_add_i32 s5, s4, s5
	s_waitcnt lgkmcnt(0)
	v_pk_add_f32 v[150:151], v[150:151], v[152:153]
	v_pk_add_f32 v[148:149], v[146:147], v[148:149]
	v_add_u32_e32 v146, s5, v155
	ds_write_b128 v146, v[148:151] offset:10240
;     __device__ __forceinline__ void fused(f32x4 (&acc)[2][2][4][2], const Unit& u, int wr, int wc, int fr, int fq, PG8_LAS unsigned char* lds, int wid, int lane) const {
;     ...
;         for (int ai = 0; ai < 2; ++ai)
; #pragma unroll
;             for (int m = 0; m < 4; ++m) {
;                 float saa = 0.f, sxx = 0.f, sxag = 0.f, sgg = 0.f;
; #pragma unroll
;                 for (int bj = 0; bj < 2; ++bj) { const u32x4 w4 = XL[((ai * 4 + m) * 2 + bj) * 512];
; #pragma unroll
;                     for (int n = 0; n < 2; ++n) { const f32x4 a = acc[ai][bj][m][n]; const f32x4 ag = a * gv[bj][n]; const unsigned wx = n == 0 ? w4.x : w4.z, wy = n == 0 ? w4.y : w4.w;
;                         const f32x4 x = (f32x4){bflo(wx), bfhi(wx), bflo(wy), bfhi(wy)};
;                         saa += (a[0] * a[0] + a[1] * a[1]) + (a[2] * a[2] + a[3] * a[3]); sxx += (x[0] * x[0] + x[1] * x[1]) + (x[2] * x[2] + x[3] * x[3]);
;                         sxag += (x[0] * ag[0] + x[1] * ag[1]) + (x[2] * ag[2] + x[3] * ag[3]); sgg += (ag[0] * ag[0] + ag[1] * ag[1]) + (ag[2] * ag[2] + ag[3] * ag[3]); } }
;                 asm volatile("" : "+v"(saa), "+v"(sxx), "+v"(sxag), "+v"(sgg));
;                 saa += __shfl_xor(saa, 16); sxx += __shfl_xor(sxx, 16); sxag += __shfl_xor(sxag, 16); sgg += __shfl_xor(sgg, 16);
;                 saa += __shfl_xor(saa, 32); sxx += __shfl_xor(sxx, 32); sxag += __shfl_xor(sxag, 32); sgg += __shfl_xor(sgg, 32);
;                 if (fq == 0) P[(ai * HALF + wr * 64 + m * 16 + fr) * 4 + wc] = (f32x4){saa, sxx, sxag, sgg};
;                 __builtin_amdgcn_sched_barrier(0);
.LBB0_1085:
	s_or_b64 exec, exec, s[0:1]
	s_waitcnt lgkmcnt(0)
	ds_read_b128 v[146:149], v200
	v_pk_mul_f32 v[150:151], v[16:17], v[144:145]
	s_waitcnt lgkmcnt(0)
	v_pk_mul_f32 v[152:153], v[14:15], v[142:143]
	v_pk_mul_f32 v[142:143], v[16:17], v[16:17]
	v_pk_mul_f32 v[144:145], v[14:15], v[14:15]
	v_pk_mov_b32 v[174:175], v[152:153], v[150:151] op_sel:[1,0]
	v_pk_mov_b32 v[158:159], v[144:145], v[142:143] op_sel:[1,0]
	v_mov_b32_e32 v145, v143
	v_pk_add_f32 v[142:143], v[158:159], v[144:145]
	v_mov_b32_e32 v180, v152
	v_pk_add_f32 v[158:159], v[142:143], v[142:143] op_sel_hi:[0,1]
	ds_read_b128 v[142:145], v0
	s_waitcnt lgkmcnt(0)
	v_lshlrev_b32_e32 v160, 16, v146
	v_and_b32_e32 v165, 0xffff0000, v146
	v_and_b32_e32 v164, 16, v146
	v_mov_b32_e32 v161, v165
	v_mul_f32_e32 v146, v160, v160
	v_pk_fma_f32 v[166:167], v[160:161], v[160:161], v[146:147] op_sel_hi:[1,1,0]
	v_lshlrev_b32_e32 v146, 16, v147
	v_and_b32_e32 v147, 0xffff0000, v147
	v_mul_f32_e32 v158, v146, v146
	v_mov_b32_e32 v181, v151
	v_mov_b32_e32 v161, v147
	v_pk_mul_f32 v[150:151], v[150:151], v[150:151]
	v_pk_mul_f32 v[152:153], v[152:153], v[152:153]
	v_pk_fma_f32 v[172:173], v[146:147], v[146:147], v[158:159] op_sel_hi:[1,1,0]
	v_pk_mov_b32 v[164:165], v[164:165], v[146:147] op_sel:[1,0]
	v_pk_mul_f32 v[146:147], v[180:181], v[160:161]
	v_pk_mov_b32 v[160:161], v[152:153], v[150:151] op_sel:[1,0]
	v_mov_b32_e32 v153, v151
	v_pk_add_f32 v[150:151], v[160:161], v[152:153]
	v_pk_mul_f32 v[152:153], v[12:13], v[12:13]
	v_pk_mul_f32 v[160:161], v[10:11], v[10:11]
	v_pk_fma_f32 v[146:147], v[174:175], v[164:165], v[146:147]
	v_pk_mul_f32 v[140:141], v[12:13], v[140:141]
	v_pk_mul_f32 v[138:139], v[10:11], v[138:139]
	v_pk_mov_b32 v[164:165], v[160:161], v[152:153] op_sel:[1,0]
	v_mov_b32_e32 v161, v153
	v_pk_add_f32 v[152:153], v[164:165], v[160:161]
	v_lshlrev_b32_e32 v161, 16, v149
	v_lshlrev_b32_e32 v160, 16, v148
	v_and_b32_e32 v149, 0xffff0000, v149
	v_and_b32_e32 v148, 0xffff0000, v148
	v_mov_b32_e32 v180, v139
	v_mov_b32_e32 v181, v141
	v_pk_mul_f32 v[164:165], v[148:149], v[148:149]
	v_mov_b32_e32 v174, v138
	v_mov_b32_e32 v175, v140
	v_pk_mul_f32 v[148:149], v[180:181], v[148:149]
	v_pk_mul_f32 v[140:141], v[140:141], v[140:141]
	v_pk_mul_f32 v[138:139], v[138:139], v[138:139]
	v_pk_fma_f32 v[164:165], v[160:161], v[160:161], v[164:165]
	v_pk_fma_f32 v[148:149], v[174:175], v[160:161], v[148:149]
	v_pk_mov_b32 v[160:161], v[138:139], v[140:141] op_sel:[1,0]
	v_mul_f32_e32 v140, v6, v6
	v_mov_b32_e32 v139, v141
	v_pk_fma_f32 v[140:141], v[6:7], v[6:7], v[140:141] op_sel_hi:[1,1,0]
	s_waitcnt lgkmcnt(0)
	v_lshlrev_b32_e32 v174, 16, v142
	v_mul_f32_e32 v140, v8, v8
	v_pk_add_f32 v[138:139], v[160:161], v[138:139]
	v_pk_fma_f32 v[160:161], v[8:9], v[8:9], v[140:141] op_sel_hi:[1,1,0]
	v_and_b32_e32 v175, 0xffff0000, v142
	v_mul_f32_e32 v140, v174, v174
	v_lshlrev_b32_e32 v142, 16, v143
	v_pk_mul_f32 v[134:135], v[6:7], v[134:135]
	v_pk_fma_f32 v[180:181], v[174:175], v[174:175], v[140:141] op_sel_hi:[1,1,0]
	v_and_b32_e32 v143, 0xffff0000, v143
	v_mul_f32_e32 v140, v142, v142
	v_pk_mul_f32 v[136:137], v[8:9], v[136:137]
	v_pk_fma_f32 v[182:183], v[142:143], v[142:143], v[140:141] op_sel_hi:[1,1,0]
	v_mul_f32_e32 v140, v134, v174
	v_pk_add_f32 v[152:153], v[152:153], v[152:153] op_sel_hi:[0,1]
	v_pk_fma_f32 v[174:175], v[134:135], v[174:175], v[140:141] op_sel_hi:[1,1,0]
	v_mul_f32_e32 v140, v136, v142
	v_add_f32_e32 v146, v146, v147
	v_pk_fma_f32 v[142:143], v[136:137], v[142:143], v[140:141] op_sel_hi:[1,1,0]
	v_mul_f32_e32 v140, v2, v2
	v_mul_f32_e32 v160, v3, v3
	v_mul_f32_e32 v152, v4, v4
	v_mul_f32_e32 v158, v5, v5
	v_add_f32_e32 v147, 0, v146
	v_lshlrev_b32_e32 v184, 16, v144
	v_and_b32_e32 v142, 0xffff0000, v144
	v_lshlrev_b32_e32 v146, 16, v145
	v_and_b32_e32 v157, 0xffff0000, v145
	v_pk_add_f32 v[140:141], v[140:141], v[160:161]
	v_pk_add_f32 v[144:145], v[152:153], v[158:159]
	v_mov_b32_e32 v185, v167
	v_pk_add_f32 v[140:141], v[140:141], v[144:145]
	v_mov_b32_e32 v144, v184
	v_mov_b32_e32 v145, v173
	v_pk_add_f32 v[164:165], v[164:165], v[164:165] op_sel_hi:[0,1]
	v_pk_mul_f32 v[144:145], v[184:185], v[144:145]
	v_pk_add_f32 v[152:153], v[166:167], v[172:173]
	v_mul_f32_e32 v164, v142, v142
	v_mul_f32_e32 v180, v146, v146
	v_mul_f32_e32 v182, v157, v157
	v_mov_b32_e32 v145, v153
	v_pk_add_f32 v[148:149], v[148:149], v[148:149] op_sel_hi:[0,1]
	v_pk_mul_f32 v[132:133], v[4:5], v[132:133]
	v_pk_mul_f32 v[130:131], v[2:3], v[130:131]
	v_pk_add_f32 v[144:145], v[144:145], v[164:165]
	v_pk_add_f32 v[152:153], v[180:181], v[182:183]
	v_mul_f32_e32 v174, v130, v184
	v_pk_add_f32 v[144:145], v[144:145], v[152:153]
	v_mul_f32_e32 v142, v131, v142
	v_mul_f32_e32 v148, v132, v146
	v_mul_f32_e32 v146, v133, v157
	v_add_f32_e32 v140, v140, v141
	v_add_f32_e32 v141, v144, v145
	v_pk_add_f32 v[142:143], v[174:175], v[142:143]
	v_pk_add_f32 v[144:145], v[148:149], v[146:147]
	v_mul_f32_e32 v146, v133, v133
	v_pk_add_f32 v[142:143], v[142:143], v[144:145]
	v_mul_f32_e32 v144, v131, v131
	v_add_f32_e32 v142, v142, v143
	v_mul_f32_e32 v143, v130, v130
	v_mul_f32_e32 v145, v132, v132
	v_pk_add_f32 v[130:131], v[150:151], v[150:151] op_sel:[0,1] op_sel_hi:[1,0]
	v_pk_add_f32 v[132:133], v[138:139], v[138:139] op_sel:[0,1] op_sel_hi:[1,0]
	v_mov_b32_e32 v131, v143
	v_mov_b32_e32 v133, v144
	v_pk_add_f32 v[130:131], v[130:131], v[132:133]
	v_mul_f32_e32 v132, v135, v135
	v_pk_fma_f32 v[132:133], v[134:135], v[134:135], v[132:133] op_sel_hi:[1,1,0]
	v_mul_f32_e32 v134, v137, v137
	v_pk_fma_f32 v[134:135], v[136:137], v[136:137], v[134:135] op_sel_hi:[1,1,0]
	v_mov_b32_e32 v133, v145
	v_mov_b32_e32 v135, v146
	v_pk_add_f32 v[132:133], v[132:133], v[134:135]
	s_nop 0
	v_pk_add_f32 v[130:131], v[130:131], v[132:133]
	s_nop 0
	v_add_f32_e32 v143, v130, v131
	v_mov_b32_e32 v130, v140
	s_nop 1
	v_permlane16_swap_b32_e32 v140, v130
	v_mov_b32_e32 v131, v141
	s_nop 1
	v_permlane16_swap_b32_e32 v141, v131
	v_mov_b32_e32 v132, v142
	s_nop 1
	v_permlane16_swap_b32_e32 v142, v132
	v_mov_b32_e32 v133, v143
	s_nop 1
	v_permlane16_swap_b32_e32 v143, v133
	s_waitcnt lgkmcnt(0)
	v_pk_add_f32 v[130:131], v[140:141], v[130:131]
	s_waitcnt lgkmcnt(0)
	v_pk_add_f32 v[134:135], v[142:143], v[132:133]
	v_mov_b32_e32 v132, v130
	s_nop 1
	v_permlane32_swap_b32_e32 v130, v132
	v_mov_b32_e32 v133, v131
	s_nop 1
	v_permlane32_swap_b32_e32 v131, v133
	v_mov_b32_e32 v136, v134
	s_nop 1
	v_permlane32_swap_b32_e32 v134, v136
	v_mov_b32_e32 v137, v135
	s_nop 1
	v_permlane32_swap_b32_e32 v135, v137
	s_and_saveexec_b64 s[0:1], vcc
	s_cbranch_execz .LBB0_1087
	s_lshl_b32 s5, s19, 12
	s_add_i32 s4, s4, s5
	s_waitcnt lgkmcnt(0)
	v_pk_add_f32 v[134:135], v[134:135], v[136:137]
	v_pk_add_f32 v[132:133], v[130:131], v[132:133]
	v_add_u32_e32 v130, s4, v155
	ds_write_b128 v130, v[132:135] offset:11264
;     __device__ __forceinline__ void fused(f32x4 (&acc)[2][2][4][2], const Unit& u, int wr, int wc, int fr, int fq, PG8_LAS unsigned char* lds, int wid, int lane) const {
;     ...
;         asm volatile("s_waitcnt lgkmcnt(0)" ::: "memory"); __builtin_amdgcn_s_barrier(); asm volatile("" ::: "memory");
;         const int row = wid * 32 + (lane & 31);
;         unsigned long long* slot = xbuf + ((size_t)(u.pm * BM + row) * 8) * 2;
;         if (lane < 32) { const f32x4 q = (P[row * 4 + 0] + P[row * 4 + 1]) + (P[row * 4 + 2] + P[row * 4 + 3]);
;             __hip_atomic_store(slot + u.pn * 2, ((unsigned long long)__float_as_uint(q[1]) << 32) | __float_as_uint(q[0]), __ATOMIC_RELAXED, __HIP_MEMORY_SCOPE_AGENT);
;             __hip_atomic_store(slot + u.pn * 2 + 1, ((unsigned long long)__float_as_uint(q[3]) << 32) | __float_as_uint(q[2]), __ATOMIC_RELAXED, __HIP_MEMORY_SCOPE_AGENT); }
.LBB0_1087:
	s_or_b64 exec, exec, s[0:1]
	v_readlane_b32 s0, v255, 14
	v_readlane_b32 s48, v254, 62
	s_lshl_b32 s0, s0, 1
	v_readlane_b32 s49, v254, 63
	s_or_b32 s6, s0, 1
	s_mov_b32 s5, s49
	v_readlane_b32 s1, v255, 15
	v_readlane_b32 s50, v255, 0
	v_readlane_b32 s51, v255, 1
	v_readlane_b32 s52, v255, 2
	v_readlane_b32 s53, v255, 3
	v_readlane_b32 s54, v255, 4
	v_readlane_b32 s55, v255, 5
	v_readlane_b32 s56, v255, 6
	v_readlane_b32 s57, v255, 7
	v_readlane_b32 s58, v255, 8
	v_readlane_b32 s59, v255, 9
	v_readlane_b32 s60, v255, 10
	v_readlane_b32 s61, v255, 11
	v_readlane_b32 s62, v255, 12
	v_readlane_b32 s63, v255, 13
	s_lshl_b32 s0, s6, 17
	v_writelane_b32 v254, s4, 62
	s_mov_b32 s1, s49
	s_lshl_b64 s[0:1], s[0:1], 3
	v_writelane_b32 v255, s6, 0
	v_writelane_b32 v255, s7, 1
	v_writelane_b32 v255, s8, 2
	v_writelane_b32 v255, s9, 3
	v_writelane_b32 v255, s10, 4
	v_writelane_b32 v255, s11, 5
	v_writelane_b32 v255, s12, 6
	v_writelane_b32 v255, s13, 7
	v_writelane_b32 v255, s14, 8
	v_writelane_b32 v255, s15, 9
	v_writelane_b32 v255, s16, 10
	v_writelane_b32 v255, s17, 11
	v_writelane_b32 v255, s18, 12
	v_writelane_b32 v255, s19, 13
	v_readlane_b32 s4, v251, 61
	s_add_u32 s0, s4, s0
	v_readlane_b32 s4, v251, 62
	v_writelane_b32 v254, s5, 63
	s_addc_u32 s1, s4, s1
	v_and_b32_e32 v130, 31, v154
	v_lshl_or_b32 v138, s18, 5, v130
	v_add_u32_e32 v130, s10, v138
	s_waitcnt lgkmcnt(0)
	s_barrier
	v_ashrrev_i32_e32 v131, 31, v130
	v_lshlrev_b64 v[130:131], 7, v[130:131]
	v_lshl_add_u64 v[130:131], s[0:1], 0, v[130:131]
	v_cmp_gt_u32_e64 s[0:1], 32, v156
	s_and_saveexec_b64 s[4:5], s[0:1]
	s_cbranch_execz .LBB0_1089
	s_waitcnt lgkmcnt(0)
	v_lshl_add_u32 v132, v138, 6, 0
	s_waitcnt lgkmcnt(0)
	v_add_u32_e32 v136, 0x20000, v132
	ds_read_b128 v[132:135], v136
	ds_read_b128 v[140:143], v136 offset:16
	ds_read_b128 v[144:147], v136 offset:32
	ds_read_b128 v[148:151], v136 offset:48
	s_lshl_b32 s8, s21, 1
	s_ashr_i32 s9, s8, 31
	s_waitcnt lgkmcnt(2)
	v_pk_add_f32 v[134:135], v[134:135], v[142:143]
	v_pk_add_f32 v[132:133], v[132:133], v[140:141]
	s_waitcnt lgkmcnt(0)
	v_pk_add_f32 v[136:137], v[146:147], v[150:151]
	v_pk_add_f32 v[140:141], v[144:145], v[148:149]
	v_pk_add_f32 v[134:135], v[134:135], v[136:137]
	v_pk_add_f32 v[132:133], v[132:133], v[140:141]
	v_lshl_add_u64 v[136:137], s[8:9], 3, v[130:131]
	global_store_dwordx2 v[136:137], v[132:133], off sc1
	global_store_dwordx2 v[136:137], v[134:135], off offset:8 sc1
